# first K-iteration of five GEMM main loops peeled: its first MFMA per accumulator takes C=0, the 128 accumulator-clearing v_mov per tile in the unit header removed
# speedup vs baseline: 1.0103x; 1.0103x over previous
.LBB0_402:
	s_add_u32 s7, s14, 0x100
	s_addc_u32 s36, s15, 0
	s_mov_b32 s37, -2
	s_add_u32 s14, s4, 0x100
	s_addc_u32 s15, s5, 0
	s_add_i32 s38, 0, 0x10000
	v_add_u32_e32 v12, s38, v193
	ds_read_b128 v[0:3], v12
	ds_read_b128 v[8:11], v12 offset:2048
	ds_read_b128 v[4:7], v12 offset:1024
	ds_read_b128 v[12:15], v12 offset:3072
	s_cmp_eq_u32 s37, 12
	s_cselect_b32 s19, s9, s15
	s_cselect_b32 s18, s8, s14
	s_cselect_b32 s17, s11, s36
	s_cselect_b32 s16, s10, s7
	v_lshl_add_u64 v[190:191], s[4:5], 0, v[186:187]
	s_add_i32 m0, s23, 0xc000
	ds_read_b128 v[16:19], v206
	ds_read_b128 v[24:27], v206 offset:2048
	ds_read_b128 v[162:165], v206 offset:4096
	ds_read_b128 v[170:173], v206 offset:6144
	ds_read_b128 v[20:23], v206 offset:1024
	ds_read_b128 v[28:31], v206 offset:3072
	ds_read_b128 v[166:169], v206 offset:5120
	ds_read_b128 v[174:177], v206 offset:7168
	global_load_lds_dwordx4 v[190:191], off
	v_lshl_add_u64 v[190:191], s[4:5], 0, v[188:189]
	s_add_i32 m0, s23, 0xe000
	s_nop 0
	global_load_lds_dwordx4 v[190:191], off
	s_waitcnt lgkmcnt(8)
	s_barrier
	s_waitcnt lgkmcnt(7)
	s_setprio 1
	v_mfma_f32_16x16x32_f16 v[158:161], v[0:3], v[16:19], 0
	v_mfma_f32_16x16x32_f16 v[142:145], v[8:11], v[16:19], 0
	s_waitcnt lgkmcnt(6)
	v_mfma_f32_16x16x32_f16 v[150:153], v[0:3], v[24:27], 0
	v_mfma_f32_16x16x32_f16 v[134:137], v[8:11], v[24:27], 0
	s_waitcnt lgkmcnt(5)
	v_mfma_f32_16x16x32_f16 v[154:157], v[0:3], v[162:165], 0
	v_mfma_f32_16x16x32_f16 v[138:141], v[8:11], v[162:165], 0
	s_waitcnt lgkmcnt(4)
	v_mfma_f32_16x16x32_f16 v[146:149], v[0:3], v[170:173], 0
	v_mfma_f32_16x16x32_f16 v[130:133], v[8:11], v[170:173], 0
	s_waitcnt lgkmcnt(3)
	v_mfma_f32_16x16x32_f16 v[158:161], v[4:7], v[20:23], v[158:161]
	v_mfma_f32_16x16x32_f16 v[142:145], v[12:15], v[20:23], v[142:145]
	s_waitcnt lgkmcnt(2)
	v_mfma_f32_16x16x32_f16 v[150:153], v[4:7], v[28:31], v[150:153]
	v_mfma_f32_16x16x32_f16 v[134:137], v[12:15], v[28:31], v[134:137]
	s_waitcnt lgkmcnt(1)
	v_mfma_f32_16x16x32_f16 v[154:157], v[4:7], v[166:169], v[154:157]
	v_mfma_f32_16x16x32_f16 v[138:141], v[12:15], v[166:169], v[138:141]
	s_waitcnt lgkmcnt(0)
	v_mfma_f32_16x16x32_f16 v[146:149], v[4:7], v[174:177], v[146:149]
	v_mfma_f32_16x16x32_f16 v[130:133], v[12:15], v[174:177], v[130:133]
	s_setprio 0
	s_barrier
	s_add_i32 s39, 0, 0x14000
	s_add_i32 s4, s38, s22
	v_add_u32_e32 v32, s39, v193
	v_lshl_add_u64 v[190:191], s[16:17], 0, v[178:179]
	s_mov_b32 m0, s4
	ds_read_b128 v[208:211], v32
	ds_read_b128 v[216:219], v32 offset:2048
	ds_read_b128 v[212:215], v32 offset:1024
	ds_read_b128 v[230:233], v32 offset:3072
	global_load_lds_dwordx4 v[190:191], off
	v_lshl_add_u64 v[238:239], s[16:17], 0, v[180:181]
	s_add_i32 m0, s4, 0x2000
	s_nop 0
	global_load_lds_dwordx4 v[238:239], off
	s_barrier
	s_waitcnt lgkmcnt(2)
	s_setprio 1
	v_mfma_f32_16x16x32_f16 v[94:97], v[208:211], v[16:19], 0
	v_mfma_f32_16x16x32_f16 v[16:19], v[216:219], v[16:19], 0
	s_waitcnt lgkmcnt(0)
	v_mfma_f32_16x16x32_f16 v[94:97], v[212:215], v[20:23], v[94:97]
	v_mfma_f32_16x16x32_f16 v[16:19], v[230:233], v[20:23], v[16:19]
	v_mfma_f32_16x16x32_f16 v[20:23], v[208:211], v[24:27], 0
	v_mfma_f32_16x16x32_f16 v[24:27], v[216:219], v[24:27], 0
	v_mfma_f32_16x16x32_f16 v[70:73], v[216:219], v[162:165], 0
	v_mfma_f32_16x16x32_f16 v[74:77], v[230:233], v[166:169], v[70:73]
	v_mfma_f32_16x16x32_f16 v[70:73], v[208:211], v[170:173], 0
	v_mfma_f32_16x16x32_f16 v[66:69], v[216:219], v[170:173], 0
	v_mfma_f32_16x16x32_f16 v[20:23], v[212:215], v[28:31], v[20:23]
	v_mfma_f32_16x16x32_f16 v[24:27], v[230:233], v[28:31], v[24:27]
	v_mfma_f32_16x16x32_f16 v[28:31], v[208:211], v[162:165], 0
	v_mfma_f32_16x16x32_f16 v[82:85], v[212:215], v[174:177], v[70:73]
	v_mfma_f32_16x16x32_f16 v[66:69], v[230:233], v[174:177], v[66:69]
	v_mfma_f32_16x16x32_f16 v[28:31], v[212:215], v[166:169], v[28:31]
	s_setprio 0
	s_mov_b32 m0, s23
	v_lshl_add_u64 v[240:241], s[18:19], 0, v[178:179]
	s_barrier
	ds_read_b128 v[70:73], v206 offset:16384
	ds_read_b128 v[86:89], v206 offset:18432
	ds_read_b128 v[162:165], v206 offset:20480
	ds_read_b128 v[170:173], v206 offset:22528
	ds_read_b128 v[78:81], v206 offset:17408
	ds_read_b128 v[90:93], v206 offset:19456
	ds_read_b128 v[166:169], v206 offset:21504
	ds_read_b128 v[174:177], v206 offset:23552
	global_load_lds_dwordx4 v[240:241], off
	v_lshl_add_u64 v[242:243], s[18:19], 0, v[180:181]
	s_mov_b32 m0, s24
	s_nop 0
	global_load_lds_dwordx4 v[242:243], off
	s_barrier
	s_waitcnt lgkmcnt(7)
	s_setprio 1
	v_mfma_f32_16x16x32_f16 v[126:129], v[0:3], v[70:73], 0
	v_mfma_f32_16x16x32_f16 v[110:113], v[8:11], v[70:73], 0
	s_waitcnt lgkmcnt(6)
	v_mfma_f32_16x16x32_f16 v[118:121], v[0:3], v[86:89], 0
	v_mfma_f32_16x16x32_f16 v[102:105], v[8:11], v[86:89], 0
	s_waitcnt lgkmcnt(5)
	v_mfma_f32_16x16x32_f16 v[122:125], v[0:3], v[162:165], 0
	v_mfma_f32_16x16x32_f16 v[106:109], v[8:11], v[162:165], 0
	s_waitcnt lgkmcnt(3)
	v_mfma_f32_16x16x32_f16 v[0:3], v[0:3], v[170:173], 0
	v_mfma_f32_16x16x32_f16 v[126:129], v[4:7], v[78:81], v[126:129]
	s_waitcnt lgkmcnt(2)
	v_mfma_f32_16x16x32_f16 v[110:113], v[12:15], v[78:81], v[110:113]
	v_mfma_f32_16x16x32_f16 v[118:121], v[4:7], v[90:93], v[118:121]
	s_waitcnt lgkmcnt(1)
	v_mfma_f32_16x16x32_f16 v[102:105], v[12:15], v[90:93], v[102:105]
	v_mfma_f32_16x16x32_f16 v[122:125], v[4:7], v[166:169], v[122:125]
	s_waitcnt lgkmcnt(0)
	v_mfma_f32_16x16x32_f16 v[106:109], v[12:15], v[166:169], v[106:109]
	v_mfma_f32_16x16x32_f16 v[0:3], v[4:7], v[174:177], v[0:3]
	v_mfma_f32_16x16x32_f16 v[4:7], v[8:11], v[170:173], 0
	v_mfma_f32_16x16x32_f16 v[4:7], v[12:15], v[174:177], v[4:7]
	s_setprio 0
	s_barrier
	s_add_u32 s4, s16, 0x40000
	s_addc_u32 s5, s17, 0
	s_add_i32 s38, s39, s22
	v_lshl_add_u64 v[8:9], s[4:5], 0, v[178:179]
	s_mov_b32 m0, s38
	s_nop 0
	global_load_lds_dwordx4 v[8:9], off
	v_lshl_add_u64 v[8:9], s[4:5], 0, v[180:181]
	s_add_i32 m0, s38, 0x2000
	s_nop 0
	global_load_lds_dwordx4 v[8:9], off
	s_waitcnt vmcnt(6)
	s_barrier
	s_setprio 1
	v_mfma_f32_16x16x32_f16 v[12:15], v[216:219], v[70:73], 0
	v_mfma_f32_16x16x32_f16 v[46:49], v[208:211], v[86:89], 0
	v_mfma_f32_16x16x32_f16 v[54:57], v[212:215], v[90:93], v[46:49]
	v_mfma_f32_16x16x32_f16 v[46:49], v[208:211], v[162:165], 0
	v_mfma_f32_16x16x32_f16 v[38:41], v[216:219], v[86:89], 0
	v_mfma_f32_16x16x32_f16 v[58:61], v[212:215], v[166:169], v[46:49]
	v_mfma_f32_16x16x32_f16 v[42:45], v[216:219], v[162:165], 0
	v_mfma_f32_16x16x32_f16 v[46:49], v[208:211], v[170:173], 0
	v_mfma_f32_16x16x32_f16 v[34:37], v[216:219], v[170:173], 0
	v_mfma_f32_16x16x32_f16 v[8:11], v[208:211], v[70:73], 0
	v_mfma_f32_16x16x32_f16 v[38:41], v[230:233], v[90:93], v[38:41]
	v_mfma_f32_16x16x32_f16 v[42:45], v[230:233], v[166:169], v[42:45]
	v_mfma_f32_16x16x32_f16 v[50:53], v[212:215], v[174:177], v[46:49]
	v_mfma_f32_16x16x32_f16 v[34:37], v[230:233], v[174:177], v[34:37]
	v_mfma_f32_16x16x32_f16 v[8:11], v[212:215], v[78:81], v[8:11]
	v_mfma_f32_16x16x32_f16 v[12:15], v[230:233], v[78:81], v[12:15]
	s_setprio 0
	s_add_i32 s38, 0, 0x18000
	v_add_u32_e32 v32, s38, v193
	s_barrier
	ds_read_b128 v[46:49], v32
	ds_read_b128 v[62:65], v32 offset:1024
	ds_read_b128 v[98:101], v32 offset:2048
	ds_read_b128 v[162:165], v32 offset:3072
	s_add_u32 s4, s18, 0x40000
	s_addc_u32 s5, s19, 0
	s_mov_b32 m0, s25
	v_lshl_add_u64 v[86:87], s[4:5], 0, v[178:179]
	ds_read_b128 v[70:73], v206 offset:32768
	ds_read_b128 v[78:81], v206 offset:33792
	ds_read_b128 v[90:93], v206 offset:34816
	ds_read_b128 v[114:117], v206 offset:35840
	ds_read_b128 v[166:169], v206 offset:36864
	ds_read_b128 v[170:173], v206 offset:37888
	ds_read_b128 v[174:177], v206 offset:38912
	ds_read_b128 v[208:211], v206 offset:39936
	global_load_lds_dwordx4 v[86:87], off
	v_lshl_add_u64 v[86:87], s[4:5], 0, v[180:181]
	s_mov_b32 m0, s26
	s_nop 0
	global_load_lds_dwordx4 v[86:87], off
	s_waitcnt lgkmcnt(8)
	s_barrier
	s_waitcnt lgkmcnt(6)
	s_setprio 1
	v_mfma_f32_16x16x32_f16 v[86:89], v[46:49], v[70:73], v[158:161]
	v_mfma_f32_16x16x32_f16 v[158:161], v[62:65], v[78:81], v[86:89]
	v_mfma_f32_16x16x32_f16 v[86:89], v[98:101], v[70:73], v[142:145]
	v_mfma_f32_16x16x32_f16 v[142:145], v[162:165], v[78:81], v[86:89]
	s_waitcnt lgkmcnt(4)
	v_mfma_f32_16x16x32_f16 v[86:89], v[46:49], v[90:93], v[150:153]
	v_mfma_f32_16x16x32_f16 v[150:153], v[62:65], v[114:117], v[86:89]
	v_mfma_f32_16x16x32_f16 v[86:89], v[98:101], v[90:93], v[134:137]
	v_mfma_f32_16x16x32_f16 v[134:137], v[162:165], v[114:117], v[86:89]
	s_waitcnt lgkmcnt(2)
	v_mfma_f32_16x16x32_f16 v[86:89], v[46:49], v[166:169], v[154:157]
	v_mfma_f32_16x16x32_f16 v[154:157], v[62:65], v[170:173], v[86:89]
	v_mfma_f32_16x16x32_f16 v[86:89], v[98:101], v[166:169], v[138:141]
	v_mfma_f32_16x16x32_f16 v[138:141], v[162:165], v[170:173], v[86:89]
	s_waitcnt lgkmcnt(0)
	v_mfma_f32_16x16x32_f16 v[86:89], v[46:49], v[174:177], v[146:149]
	v_mfma_f32_16x16x32_f16 v[146:149], v[62:65], v[208:211], v[86:89]
	v_mfma_f32_16x16x32_f16 v[86:89], v[98:101], v[174:177], v[130:133]
	v_mfma_f32_16x16x32_f16 v[130:133], v[162:165], v[208:211], v[86:89]
	s_setprio 0
	s_barrier
	s_add_i32 s18, 0, 0x1c000
	s_add_i32 s4, s38, s22
	v_add_u32_e32 v32, s18, v193
	s_nop 1
	v_lshl_add_u64 v[86:87], v[190:191], 0, s[84:85]
	s_mov_b32 m0, s4
	ds_read_b128 v[212:215], v32
	ds_read_b128 v[230:233], v32 offset:2048
	ds_read_b128 v[216:219], v32 offset:1024
	ds_read_b128 v[234:237], v32 offset:3072
	global_load_lds_dwordx4 v[86:87], off
	v_lshl_add_u64 v[86:87], v[238:239], 0, s[84:85]
	s_add_i32 m0, s4, 0x2000
	s_nop 0
	global_load_lds_dwordx4 v[86:87], off
	s_barrier
	s_waitcnt lgkmcnt(2)
	s_setprio 1
	v_mfma_f32_16x16x32_f16 v[86:89], v[212:215], v[70:73], v[94:97]
	v_mfma_f32_16x16x32_f16 v[16:19], v[230:233], v[70:73], v[16:19]
	s_waitcnt lgkmcnt(0)
	v_mfma_f32_16x16x32_f16 v[94:97], v[216:219], v[78:81], v[86:89]
	v_mfma_f32_16x16x32_f16 v[78:81], v[234:237], v[78:81], v[16:19]
	v_mfma_f32_16x16x32_f16 v[16:19], v[212:215], v[90:93], v[20:23]
	v_mfma_f32_16x16x32_f16 v[86:89], v[216:219], v[114:117], v[16:19]
	v_mfma_f32_16x16x32_f16 v[16:19], v[230:233], v[90:93], v[24:27]
	v_mfma_f32_16x16x32_f16 v[70:73], v[234:237], v[114:117], v[16:19]
	v_mfma_f32_16x16x32_f16 v[16:19], v[212:215], v[166:169], v[28:31]
	v_mfma_f32_16x16x32_f16 v[90:93], v[216:219], v[170:173], v[16:19]
	v_mfma_f32_16x16x32_f16 v[16:19], v[230:233], v[166:169], v[74:77]
	v_mfma_f32_16x16x32_f16 v[74:77], v[234:237], v[170:173], v[16:19]
	v_mfma_f32_16x16x32_f16 v[16:19], v[212:215], v[174:177], v[82:85]
	v_mfma_f32_16x16x32_f16 v[82:85], v[216:219], v[208:211], v[16:19]
	v_mfma_f32_16x16x32_f16 v[16:19], v[230:233], v[174:177], v[66:69]
	v_mfma_f32_16x16x32_f16 v[66:69], v[234:237], v[208:211], v[16:19]
	s_setprio 0
	s_mov_b32 m0, s28
	v_lshl_add_u64 v[114:115], v[240:241], 0, s[84:85]
	s_barrier
	s_nop 2
	ds_read_b128 v[16:19], v206 offset:49152
	ds_read_b128 v[20:23], v206 offset:50176
	ds_read_b128 v[24:27], v206 offset:51200
	ds_read_b128 v[28:31], v206 offset:52224
	ds_read_b128 v[166:169], v206 offset:53248
	ds_read_b128 v[174:177], v206 offset:55296
	ds_read_b128 v[170:173], v206 offset:54272
	ds_read_b128 v[208:211], v206 offset:56320
	global_load_lds_dwordx4 v[114:115], off
	v_lshl_add_u64 v[114:115], v[242:243], 0, s[84:85]
	s_mov_b32 m0, s29
	s_nop 0
	global_load_lds_dwordx4 v[114:115], off
	s_barrier
	s_waitcnt lgkmcnt(6)
	s_setprio 1
	v_mfma_f32_16x16x32_f16 v[114:117], v[46:49], v[16:19], v[126:129]
	v_mfma_f32_16x16x32_f16 v[126:129], v[62:65], v[20:23], v[114:117]
	s_waitcnt lgkmcnt(4)
	v_mfma_f32_16x16x32_f16 v[114:117], v[46:49], v[24:27], v[118:121]
	v_mfma_f32_16x16x32_f16 v[118:121], v[62:65], v[28:31], v[114:117]
	s_waitcnt lgkmcnt(2)
	v_mfma_f32_16x16x32_f16 v[114:117], v[46:49], v[166:169], v[122:125]
	v_mfma_f32_16x16x32_f16 v[0:3], v[46:49], v[174:177], v[0:3]
	v_mfma_f32_16x16x32_f16 v[110:113], v[98:101], v[16:19], v[110:113]
	v_mfma_f32_16x16x32_f16 v[102:105], v[98:101], v[24:27], v[102:105]
	s_waitcnt lgkmcnt(1)
	v_mfma_f32_16x16x32_f16 v[122:125], v[62:65], v[170:173], v[114:117]
	v_mfma_f32_16x16x32_f16 v[106:109], v[98:101], v[166:169], v[106:109]
	s_waitcnt lgkmcnt(0)
	v_mfma_f32_16x16x32_f16 v[114:117], v[62:65], v[208:211], v[0:3]
	v_mfma_f32_16x16x32_f16 v[0:3], v[98:101], v[174:177], v[4:7]
	v_mfma_f32_16x16x32_f16 v[110:113], v[162:165], v[20:23], v[110:113]
	v_mfma_f32_16x16x32_f16 v[102:105], v[162:165], v[28:31], v[102:105]
	v_mfma_f32_16x16x32_f16 v[106:109], v[162:165], v[170:173], v[106:109]
	v_mfma_f32_16x16x32_f16 v[98:101], v[162:165], v[208:211], v[0:3]
	s_setprio 0
	s_barrier
	s_add_u32 s4, s16, 0x40080
	s_addc_u32 s5, s17, 0
	s_add_i32 s16, s18, s22
	v_lshl_add_u64 v[0:1], s[4:5], 0, v[178:179]
	s_mov_b32 m0, s16
	s_nop 0
	global_load_lds_dwordx4 v[0:1], off
	v_lshl_add_u64 v[0:1], s[4:5], 0, v[180:181]
	s_add_i32 m0, s16, 0x2000
	s_nop 0
	global_load_lds_dwordx4 v[0:1], off
	s_waitcnt vmcnt(6)
	s_barrier
	s_setprio 1
	v_mfma_f32_16x16x32_f16 v[0:3], v[212:215], v[16:19], v[8:11]
	v_mfma_f32_16x16x32_f16 v[62:65], v[216:219], v[20:23], v[0:3]
	v_mfma_f32_16x16x32_f16 v[0:3], v[230:233], v[16:19], v[12:15]
	v_mfma_f32_16x16x32_f16 v[46:49], v[234:237], v[20:23], v[0:3]
	v_mfma_f32_16x16x32_f16 v[0:3], v[212:215], v[24:27], v[54:57]
	v_mfma_f32_16x16x32_f16 v[54:57], v[216:219], v[28:31], v[0:3]
	v_mfma_f32_16x16x32_f16 v[0:3], v[230:233], v[24:27], v[38:41]
	v_mfma_f32_16x16x32_f16 v[38:41], v[234:237], v[28:31], v[0:3]
	v_mfma_f32_16x16x32_f16 v[0:3], v[212:215], v[166:169], v[58:61]
	v_mfma_f32_16x16x32_f16 v[58:61], v[216:219], v[170:173], v[0:3]
	v_mfma_f32_16x16x32_f16 v[0:3], v[230:233], v[166:169], v[42:45]
	v_mfma_f32_16x16x32_f16 v[42:45], v[234:237], v[170:173], v[0:3]
	v_mfma_f32_16x16x32_f16 v[0:3], v[212:215], v[174:177], v[50:53]
	v_mfma_f32_16x16x32_f16 v[50:53], v[216:219], v[208:211], v[0:3]
	v_mfma_f32_16x16x32_f16 v[0:3], v[230:233], v[174:177], v[34:37]
	v_mfma_f32_16x16x32_f16 v[34:37], v[234:237], v[208:211], v[0:3]
	s_setprio 0
	s_add_i32 s37, s37, 2
	s_add_u32 s7, s7, 0x100
	s_addc_u32 s36, s36, 0
	s_cmp_gt_u32 s37, 13
	s_mov_b64 s[4:5], s[14:15]
	s_barrier
	s_cbranch_scc0 .LBB0_403
	s_branch .Lpeelx0

.Lpeelx0:
	s_lshl_b32 s7, s34, 8
	s_cmp_lt_i32 s35, 28
	s_mov_b64 s[4:5], -1
	s_cbranch_scc0 .LBB0_431
	s_add_i32 s16, s7, s27
	v_or_b32_e32 v207, s16, v192
	s_cmp_gt_i32 s35, 3
	s_cbranch_scc0 .LBB0_411
	s_add_i32 s4, s35, -12
	s_cmp_gt_u32 s4, 7
	s_mov_b64 s[4:5], -1
	s_cbranch_scc0 .LBB0_408
	s_lshl_b32 s4, s35, 8
	s_add_i32 s5, s4, 0xfffffc00
	s_cmp_lt_u32 s35, 12
	s_cselect_b32 s4, s4, s5
	v_and_b32_e32 v10, 7, v220
	v_and_b32_e32 v11, 8, v220
	v_cmp_ne_u32_e32 vcc, 0, v11
	v_and_b32_e32 v12, 0x60, v194
	v_lshlrev_b32_e32 v12, 1, v12
	v_lshl_or_b32 v12, v11, 2, v12
	v_and_b32_e32 v13, 0x18, v194
	v_or_b32_e32 v12, v12, v13
	v_or_b32_e32 v32, s4, v12
	v_or_b32_e32 v14, s16, v10
	v_mov_b64_e32 v[4:5], s[70:71]
	v_mad_i64_i32 v[0:1], s[4:5], v14, s33, v[4:5]
	v_lshlrev_b64 v[6:7], 1, v[32:33]
	v_lshl_add_u64 v[16:17], v[0:1], 0, v[6:7]
	v_mov_b32_e32 v32, 0x30000
	v_lshl_add_u64 v[18:19], v[16:17], 0, v[32:33]
	v_lshl_add_u64 v[20:21], v[18:19], 0, v[32:33]
	v_lshl_add_u64 v[22:23], v[20:21], 0, v[32:33]
	v_mov_b32_e32 v8, 0x180000
	v_mov_b32_e32 v9, 0
	v_lshl_add_u64 v[24:25], v[16:17], 0, v[8:9]
	v_lshl_add_u64 v[26:27], v[24:25], 0, v[32:33]
	v_lshl_add_u64 v[28:29], v[26:27], 0, v[32:33]
	v_lshl_add_u64 v[30:31], v[28:29], 0, v[32:33]
	v_mov_b32_e32 v8, 0x18000
	v_cvt_pk_f16_f32 v158, v158, v159
	v_cvt_pk_f16_f32 v159, v160, v161
	v_cvt_pk_f16_f32 v160, v142, v143
	v_cvt_pk_f16_f32 v161, v144, v145
	v_cvt_pk_f16_f32 v94, v94, v95
	v_cvt_pk_f16_f32 v95, v96, v97
	v_cvt_pk_f16_f32 v96, v78, v79
	v_cvt_pk_f16_f32 v97, v80, v81
	v_mov_b32_dpp v0, v158 row_ror:8 row_mask:0xf bank_mask:0xf
	v_mov_b32_dpp v1, v159 row_ror:8 row_mask:0xf bank_mask:0xf
	v_mov_b32_dpp v2, v160 row_ror:8 row_mask:0xf bank_mask:0xf
	v_mov_b32_dpp v3, v161 row_ror:8 row_mask:0xf bank_mask:0xf
	v_mov_b32_dpp v4, v94 row_ror:8 row_mask:0xf bank_mask:0xf
	v_mov_b32_dpp v5, v95 row_ror:8 row_mask:0xf bank_mask:0xf
	v_mov_b32_dpp v6, v96 row_ror:8 row_mask:0xf bank_mask:0xf
	v_mov_b32_dpp v7, v97 row_ror:8 row_mask:0xf bank_mask:0xf
	v_cndmask_b32_e32 v158, v158, v4, vcc
	v_cndmask_b32_e32 v159, v159, v5, vcc
	v_cndmask_b32_e32 v160, v160, v6, vcc
	v_cndmask_b32_e32 v161, v161, v7, vcc
	v_cndmask_b32_e32 v94, v0, v94, vcc
	v_cndmask_b32_e32 v95, v1, v95, vcc
	v_cndmask_b32_e32 v96, v2, v96, vcc
	v_cndmask_b32_e32 v97, v3, v97, vcc
	v_lshl_add_u64 v[10:11], v[16:17], 0, v[8:9]
	global_store_dwordx4 v[16:17], v[158:161], off
	global_store_dwordx4 v[10:11], v[94:97], off
	v_cvt_pk_f16_f32 v150, v150, v151
	v_cvt_pk_f16_f32 v151, v152, v153
	v_cvt_pk_f16_f32 v152, v134, v135
	v_cvt_pk_f16_f32 v153, v136, v137
	v_cvt_pk_f16_f32 v86, v86, v87
	v_cvt_pk_f16_f32 v87, v88, v89
	v_cvt_pk_f16_f32 v88, v70, v71
	v_cvt_pk_f16_f32 v89, v72, v73
	v_mov_b32_dpp v0, v150 row_ror:8 row_mask:0xf bank_mask:0xf
	v_mov_b32_dpp v1, v151 row_ror:8 row_mask:0xf bank_mask:0xf
	v_mov_b32_dpp v2, v152 row_ror:8 row_mask:0xf bank_mask:0xf
	v_mov_b32_dpp v3, v153 row_ror:8 row_mask:0xf bank_mask:0xf
	v_mov_b32_dpp v4, v86 row_ror:8 row_mask:0xf bank_mask:0xf
	v_mov_b32_dpp v5, v87 row_ror:8 row_mask:0xf bank_mask:0xf
	v_mov_b32_dpp v6, v88 row_ror:8 row_mask:0xf bank_mask:0xf
	v_mov_b32_dpp v7, v89 row_ror:8 row_mask:0xf bank_mask:0xf
	v_cndmask_b32_e32 v150, v150, v4, vcc
	v_cndmask_b32_e32 v151, v151, v5, vcc
	v_cndmask_b32_e32 v152, v152, v6, vcc
	v_cndmask_b32_e32 v153, v153, v7, vcc
	v_cndmask_b32_e32 v86, v0, v86, vcc
	v_cndmask_b32_e32 v87, v1, v87, vcc
	v_cndmask_b32_e32 v88, v2, v88, vcc
	v_cndmask_b32_e32 v89, v3, v89, vcc
	v_lshl_add_u64 v[10:11], v[18:19], 0, v[8:9]
	global_store_dwordx4 v[18:19], v[150:153], off
	global_store_dwordx4 v[10:11], v[86:89], off
	v_cvt_pk_f16_f32 v154, v154, v155
	v_cvt_pk_f16_f32 v155, v156, v157
	v_cvt_pk_f16_f32 v156, v138, v139
	v_cvt_pk_f16_f32 v157, v140, v141
	v_cvt_pk_f16_f32 v90, v90, v91
	v_cvt_pk_f16_f32 v91, v92, v93
	v_cvt_pk_f16_f32 v92, v74, v75
	v_cvt_pk_f16_f32 v93, v76, v77
	v_mov_b32_dpp v0, v154 row_ror:8 row_mask:0xf bank_mask:0xf
	v_mov_b32_dpp v1, v155 row_ror:8 row_mask:0xf bank_mask:0xf
	v_mov_b32_dpp v2, v156 row_ror:8 row_mask:0xf bank_mask:0xf
	v_mov_b32_dpp v3, v157 row_ror:8 row_mask:0xf bank_mask:0xf
	v_mov_b32_dpp v4, v90 row_ror:8 row_mask:0xf bank_mask:0xf
	v_mov_b32_dpp v5, v91 row_ror:8 row_mask:0xf bank_mask:0xf
	v_mov_b32_dpp v6, v92 row_ror:8 row_mask:0xf bank_mask:0xf
	v_mov_b32_dpp v7, v93 row_ror:8 row_mask:0xf bank_mask:0xf
	v_cndmask_b32_e32 v154, v154, v4, vcc
	v_cndmask_b32_e32 v155, v155, v5, vcc
	v_cndmask_b32_e32 v156, v156, v6, vcc
	v_cndmask_b32_e32 v157, v157, v7, vcc
	v_cndmask_b32_e32 v90, v0, v90, vcc
	v_cndmask_b32_e32 v91, v1, v91, vcc
	v_cndmask_b32_e32 v92, v2, v92, vcc
	v_cndmask_b32_e32 v93, v3, v93, vcc
	v_lshl_add_u64 v[10:11], v[20:21], 0, v[8:9]
	global_store_dwordx4 v[20:21], v[154:157], off
	global_store_dwordx4 v[10:11], v[90:93], off
	v_cvt_pk_f16_f32 v146, v146, v147
	v_cvt_pk_f16_f32 v147, v148, v149
	v_cvt_pk_f16_f32 v148, v130, v131
	v_cvt_pk_f16_f32 v149, v132, v133
	v_cvt_pk_f16_f32 v82, v82, v83
	v_cvt_pk_f16_f32 v83, v84, v85
	v_cvt_pk_f16_f32 v84, v66, v67
	v_cvt_pk_f16_f32 v85, v68, v69
	v_mov_b32_dpp v0, v146 row_ror:8 row_mask:0xf bank_mask:0xf
	v_mov_b32_dpp v1, v147 row_ror:8 row_mask:0xf bank_mask:0xf
	v_mov_b32_dpp v2, v148 row_ror:8 row_mask:0xf bank_mask:0xf
	v_mov_b32_dpp v3, v149 row_ror:8 row_mask:0xf bank_mask:0xf
	v_mov_b32_dpp v4, v82 row_ror:8 row_mask:0xf bank_mask:0xf
	v_mov_b32_dpp v5, v83 row_ror:8 row_mask:0xf bank_mask:0xf
	v_mov_b32_dpp v6, v84 row_ror:8 row_mask:0xf bank_mask:0xf
	v_mov_b32_dpp v7, v85 row_ror:8 row_mask:0xf bank_mask:0xf
	v_cndmask_b32_e32 v146, v146, v4, vcc
	v_cndmask_b32_e32 v147, v147, v5, vcc
	v_cndmask_b32_e32 v148, v148, v6, vcc
	v_cndmask_b32_e32 v149, v149, v7, vcc
	v_cndmask_b32_e32 v82, v0, v82, vcc
	v_cndmask_b32_e32 v83, v1, v83, vcc
	v_cndmask_b32_e32 v84, v2, v84, vcc
	v_cndmask_b32_e32 v85, v3, v85, vcc
	v_lshl_add_u64 v[10:11], v[22:23], 0, v[8:9]
	global_store_dwordx4 v[22:23], v[146:149], off
	global_store_dwordx4 v[10:11], v[82:85], off
	v_cvt_pk_f16_f32 v126, v126, v127
	v_cvt_pk_f16_f32 v127, v128, v129
	v_cvt_pk_f16_f32 v128, v110, v111
	v_cvt_pk_f16_f32 v129, v112, v113
	v_cvt_pk_f16_f32 v62, v62, v63
	v_cvt_pk_f16_f32 v63, v64, v65
	v_cvt_pk_f16_f32 v64, v46, v47
	v_cvt_pk_f16_f32 v65, v48, v49
	v_mov_b32_dpp v0, v126 row_ror:8 row_mask:0xf bank_mask:0xf
	v_mov_b32_dpp v1, v127 row_ror:8 row_mask:0xf bank_mask:0xf
	v_mov_b32_dpp v2, v128 row_ror:8 row_mask:0xf bank_mask:0xf
	v_mov_b32_dpp v3, v129 row_ror:8 row_mask:0xf bank_mask:0xf
	v_mov_b32_dpp v4, v62 row_ror:8 row_mask:0xf bank_mask:0xf
	v_mov_b32_dpp v5, v63 row_ror:8 row_mask:0xf bank_mask:0xf
	v_mov_b32_dpp v6, v64 row_ror:8 row_mask:0xf bank_mask:0xf
	v_mov_b32_dpp v7, v65 row_ror:8 row_mask:0xf bank_mask:0xf
	v_cndmask_b32_e32 v126, v126, v4, vcc
	v_cndmask_b32_e32 v127, v127, v5, vcc
	v_cndmask_b32_e32 v128, v128, v6, vcc
	v_cndmask_b32_e32 v129, v129, v7, vcc
	v_cndmask_b32_e32 v62, v0, v62, vcc
	v_cndmask_b32_e32 v63, v1, v63, vcc
	v_cndmask_b32_e32 v64, v2, v64, vcc
	v_cndmask_b32_e32 v65, v3, v65, vcc
	v_lshl_add_u64 v[10:11], v[24:25], 0, v[8:9]
	global_store_dwordx4 v[24:25], v[126:129], off
	global_store_dwordx4 v[10:11], v[62:65], off
	v_cvt_pk_f16_f32 v118, v118, v119
	v_cvt_pk_f16_f32 v119, v120, v121
	v_cvt_pk_f16_f32 v120, v102, v103
	v_cvt_pk_f16_f32 v121, v104, v105
	v_cvt_pk_f16_f32 v54, v54, v55
	v_cvt_pk_f16_f32 v55, v56, v57
	v_cvt_pk_f16_f32 v56, v38, v39
	v_cvt_pk_f16_f32 v57, v40, v41
	v_mov_b32_dpp v0, v118 row_ror:8 row_mask:0xf bank_mask:0xf
	v_mov_b32_dpp v1, v119 row_ror:8 row_mask:0xf bank_mask:0xf
	v_mov_b32_dpp v2, v120 row_ror:8 row_mask:0xf bank_mask:0xf
	v_mov_b32_dpp v3, v121 row_ror:8 row_mask:0xf bank_mask:0xf
	v_mov_b32_dpp v4, v54 row_ror:8 row_mask:0xf bank_mask:0xf
	v_mov_b32_dpp v5, v55 row_ror:8 row_mask:0xf bank_mask:0xf
	v_mov_b32_dpp v6, v56 row_ror:8 row_mask:0xf bank_mask:0xf
	v_mov_b32_dpp v7, v57 row_ror:8 row_mask:0xf bank_mask:0xf
	v_cndmask_b32_e32 v118, v118, v4, vcc
	v_cndmask_b32_e32 v119, v119, v5, vcc
	v_cndmask_b32_e32 v120, v120, v6, vcc
	v_cndmask_b32_e32 v121, v121, v7, vcc
	v_cndmask_b32_e32 v54, v0, v54, vcc
	v_cndmask_b32_e32 v55, v1, v55, vcc
	v_cndmask_b32_e32 v56, v2, v56, vcc
	v_cndmask_b32_e32 v57, v3, v57, vcc
	v_lshl_add_u64 v[10:11], v[26:27], 0, v[8:9]
	global_store_dwordx4 v[26:27], v[118:121], off
	global_store_dwordx4 v[10:11], v[54:57], off
	v_cvt_pk_f16_f32 v122, v122, v123
	v_cvt_pk_f16_f32 v123, v124, v125
	v_cvt_pk_f16_f32 v124, v106, v107
	v_cvt_pk_f16_f32 v125, v108, v109
	v_cvt_pk_f16_f32 v58, v58, v59
	v_cvt_pk_f16_f32 v59, v60, v61
	v_cvt_pk_f16_f32 v60, v42, v43
	v_cvt_pk_f16_f32 v61, v44, v45
	v_mov_b32_dpp v0, v122 row_ror:8 row_mask:0xf bank_mask:0xf
	v_mov_b32_dpp v1, v123 row_ror:8 row_mask:0xf bank_mask:0xf
	v_mov_b32_dpp v2, v124 row_ror:8 row_mask:0xf bank_mask:0xf
	v_mov_b32_dpp v3, v125 row_ror:8 row_mask:0xf bank_mask:0xf
	v_mov_b32_dpp v4, v58 row_ror:8 row_mask:0xf bank_mask:0xf
	v_mov_b32_dpp v5, v59 row_ror:8 row_mask:0xf bank_mask:0xf
	v_mov_b32_dpp v6, v60 row_ror:8 row_mask:0xf bank_mask:0xf
	v_mov_b32_dpp v7, v61 row_ror:8 row_mask:0xf bank_mask:0xf
	v_cndmask_b32_e32 v122, v122, v4, vcc
	v_cndmask_b32_e32 v123, v123, v5, vcc
	v_cndmask_b32_e32 v124, v124, v6, vcc
	v_cndmask_b32_e32 v125, v125, v7, vcc
	v_cndmask_b32_e32 v58, v0, v58, vcc
	v_cndmask_b32_e32 v59, v1, v59, vcc
	v_cndmask_b32_e32 v60, v2, v60, vcc
	v_cndmask_b32_e32 v61, v3, v61, vcc
	v_lshl_add_u64 v[10:11], v[28:29], 0, v[8:9]
	global_store_dwordx4 v[28:29], v[122:125], off
	global_store_dwordx4 v[10:11], v[58:61], off
	v_cvt_pk_f16_f32 v114, v114, v115
	v_cvt_pk_f16_f32 v115, v116, v117
	v_cvt_pk_f16_f32 v116, v98, v99
	v_cvt_pk_f16_f32 v117, v100, v101
	v_cvt_pk_f16_f32 v50, v50, v51
	v_cvt_pk_f16_f32 v51, v52, v53
	v_cvt_pk_f16_f32 v52, v34, v35
	v_cvt_pk_f16_f32 v53, v36, v37
	v_mov_b32_dpp v0, v114 row_ror:8 row_mask:0xf bank_mask:0xf
	v_mov_b32_dpp v1, v115 row_ror:8 row_mask:0xf bank_mask:0xf
	v_mov_b32_dpp v2, v116 row_ror:8 row_mask:0xf bank_mask:0xf
	v_mov_b32_dpp v3, v117 row_ror:8 row_mask:0xf bank_mask:0xf
	v_mov_b32_dpp v4, v50 row_ror:8 row_mask:0xf bank_mask:0xf
	v_mov_b32_dpp v5, v51 row_ror:8 row_mask:0xf bank_mask:0xf
	v_mov_b32_dpp v6, v52 row_ror:8 row_mask:0xf bank_mask:0xf
	v_mov_b32_dpp v7, v53 row_ror:8 row_mask:0xf bank_mask:0xf
	v_cndmask_b32_e32 v114, v114, v4, vcc
	v_cndmask_b32_e32 v115, v115, v5, vcc
	v_cndmask_b32_e32 v116, v116, v6, vcc
	v_cndmask_b32_e32 v117, v117, v7, vcc
	v_cndmask_b32_e32 v50, v0, v50, vcc
	v_cndmask_b32_e32 v51, v1, v51, vcc
	v_cndmask_b32_e32 v52, v2, v52, vcc
	v_cndmask_b32_e32 v53, v3, v53, vcc
	v_lshl_add_u64 v[10:11], v[30:31], 0, v[8:9]
	global_store_dwordx4 v[30:31], v[114:117], off
	global_store_dwordx4 v[10:11], v[50:53], off
	s_mov_b64 s[4:5], 0

.LBB0_957:
	s_add_u32 s35, s12, 0x100
	s_addc_u32 s36, s13, 0
	s_mov_b32 s37, -2
	s_add_u32 s12, s10, 0x100
	s_addc_u32 s13, s11, 0
	s_add_i32 s38, 0, 0x10000
	v_add_u32_e32 v142, s38, v196
	ds_read_b128 v[122:125], v142
	ds_read_b128 v[138:141], v142 offset:2048
	ds_read_b128 v[130:133], v142 offset:1024
	ds_read_b128 v[142:145], v142 offset:3072
	s_cmp_eq_u32 s37, 12
	s_cselect_b32 s17, s7, s13
	s_cselect_b32 s16, s6, s12
	s_cselect_b32 s15, s9, s36
	s_cselect_b32 s14, s8, s35
	v_lshl_add_u64 v[230:231], s[10:11], 0, v[188:189]
	s_add_i32 m0, s21, 0xc000
	ds_read_b128 v[146:149], v198
	ds_read_b128 v[192:195], v198 offset:2048
	ds_read_b128 v[204:207], v198 offset:4096
	ds_read_b128 v[212:215], v198 offset:6144
	ds_read_b128 v[150:153], v198 offset:1024
	ds_read_b128 v[200:203], v198 offset:3072
	ds_read_b128 v[208:211], v198 offset:5120
	ds_read_b128 v[216:219], v198 offset:7168
	global_load_lds_dwordx4 v[230:231], off
	v_lshl_add_u64 v[230:231], s[10:11], 0, v[190:191]
	s_add_i32 m0, s21, 0xe000
	s_nop 0
	global_load_lds_dwordx4 v[230:231], off
	s_waitcnt lgkmcnt(8)
	s_barrier
	s_waitcnt lgkmcnt(7)
	s_setprio 1
	v_mfma_f32_16x16x32_f16 v[134:137], v[122:125], v[146:149], 0
	v_mfma_f32_16x16x32_f16 v[126:129], v[138:141], v[146:149], 0
	s_waitcnt lgkmcnt(6)
	v_mfma_f32_16x16x32_f16 v[110:113], v[122:125], v[192:195], 0
	v_mfma_f32_16x16x32_f16 v[106:109], v[138:141], v[192:195], 0
	s_waitcnt lgkmcnt(5)
	v_mfma_f32_16x16x32_f16 v[94:97], v[122:125], v[204:207], 0
	v_mfma_f32_16x16x32_f16 v[90:93], v[138:141], v[204:207], 0
	s_waitcnt lgkmcnt(4)
	v_mfma_f32_16x16x32_f16 v[78:81], v[122:125], v[212:215], 0
	v_mfma_f32_16x16x32_f16 v[74:77], v[138:141], v[212:215], 0
	s_waitcnt lgkmcnt(3)
	v_mfma_f32_16x16x32_f16 v[134:137], v[130:133], v[150:153], v[134:137]
	v_mfma_f32_16x16x32_f16 v[126:129], v[142:145], v[150:153], v[126:129]
	s_waitcnt lgkmcnt(2)
	v_mfma_f32_16x16x32_f16 v[110:113], v[130:133], v[200:203], v[110:113]
	v_mfma_f32_16x16x32_f16 v[106:109], v[142:145], v[200:203], v[106:109]
	s_waitcnt lgkmcnt(1)
	v_mfma_f32_16x16x32_f16 v[94:97], v[130:133], v[208:211], v[94:97]
	v_mfma_f32_16x16x32_f16 v[90:93], v[142:145], v[208:211], v[90:93]
	s_waitcnt lgkmcnt(0)
	v_mfma_f32_16x16x32_f16 v[78:81], v[130:133], v[216:219], v[78:81]
	v_mfma_f32_16x16x32_f16 v[74:77], v[142:145], v[216:219], v[74:77]
	s_setprio 0
	s_barrier
	s_add_i32 s39, 0, 0x14000
	s_add_i32 s10, s38, s20
	v_add_u32_e32 v199, s39, v196
	v_lshl_add_u64 v[246:247], s[14:15], 0, v[32:33]
	s_mov_b32 m0, s10
	ds_read_b128 v[230:233], v199
	ds_read_b128 v[238:241], v199 offset:2048
	ds_read_b128 v[234:237], v199 offset:1024
	ds_read_b128 v[242:245], v199 offset:3072
	global_load_lds_dwordx4 v[246:247], off
	v_lshl_add_u64 v[248:249], s[14:15], 0, v[154:155]
	s_add_i32 m0, s10, 0x2000
	s_nop 0
	global_load_lds_dwordx4 v[248:249], off
	s_barrier
	s_waitcnt lgkmcnt(2)
	s_setprio 1
	v_mfma_f32_16x16x32_f16 v[118:121], v[230:233], v[146:149], 0
	v_mfma_f32_16x16x32_f16 v[114:117], v[238:241], v[146:149], 0
	v_mfma_f32_16x16x32_f16 v[102:105], v[230:233], v[192:195], 0
	v_mfma_f32_16x16x32_f16 v[98:101], v[238:241], v[192:195], 0
	v_mfma_f32_16x16x32_f16 v[86:89], v[230:233], v[204:207], 0
	v_mfma_f32_16x16x32_f16 v[82:85], v[238:241], v[204:207], 0
	v_mfma_f32_16x16x32_f16 v[70:73], v[230:233], v[212:215], 0
	v_mfma_f32_16x16x32_f16 v[66:69], v[238:241], v[212:215], 0
	s_waitcnt lgkmcnt(0)
	v_mfma_f32_16x16x32_f16 v[118:121], v[234:237], v[150:153], v[118:121]
	v_mfma_f32_16x16x32_f16 v[114:117], v[242:245], v[150:153], v[114:117]
	v_mfma_f32_16x16x32_f16 v[102:105], v[234:237], v[200:203], v[102:105]
	v_mfma_f32_16x16x32_f16 v[98:101], v[242:245], v[200:203], v[98:101]
	v_mfma_f32_16x16x32_f16 v[86:89], v[234:237], v[208:211], v[86:89]
	v_mfma_f32_16x16x32_f16 v[82:85], v[242:245], v[208:211], v[82:85]
	v_mfma_f32_16x16x32_f16 v[70:73], v[234:237], v[216:219], v[70:73]
	v_mfma_f32_16x16x32_f16 v[66:69], v[242:245], v[216:219], v[66:69]
	s_setprio 0
	s_mov_b32 m0, s21
	v_lshl_add_u64 v[228:229], s[16:17], 0, v[32:33]
	s_barrier
	ds_read_b128 v[146:149], v198 offset:16384
	ds_read_b128 v[192:195], v198 offset:18432
	ds_read_b128 v[204:207], v198 offset:20480
	ds_read_b128 v[212:215], v198 offset:22528
	ds_read_b128 v[150:153], v198 offset:17408
	ds_read_b128 v[200:203], v198 offset:19456
	ds_read_b128 v[208:211], v198 offset:21504
	ds_read_b128 v[216:219], v198 offset:23552
	global_load_lds_dwordx4 v[228:229], off
	v_lshl_add_u64 v[222:223], s[16:17], 0, v[154:155]
	s_mov_b32 m0, s22
	s_nop 0
	global_load_lds_dwordx4 v[222:223], off
	s_barrier
	s_waitcnt lgkmcnt(7)
	s_setprio 1
	v_mfma_f32_16x16x32_f16 v[62:65], v[122:125], v[146:149], 0
	v_mfma_f32_16x16x32_f16 v[58:61], v[138:141], v[146:149], 0
	s_waitcnt lgkmcnt(6)
	v_mfma_f32_16x16x32_f16 v[46:49], v[122:125], v[192:195], 0
	v_mfma_f32_16x16x32_f16 v[42:45], v[138:141], v[192:195], 0
	s_waitcnt lgkmcnt(5)
	v_mfma_f32_16x16x32_f16 v[28:31], v[122:125], v[204:207], 0
	v_mfma_f32_16x16x32_f16 v[24:27], v[138:141], v[204:207], 0
	s_waitcnt lgkmcnt(4)
	v_mfma_f32_16x16x32_f16 v[12:15], v[122:125], v[212:215], 0
	v_mfma_f32_16x16x32_f16 v[8:11], v[138:141], v[212:215], 0
	s_waitcnt lgkmcnt(3)
	v_mfma_f32_16x16x32_f16 v[62:65], v[130:133], v[150:153], v[62:65]
	v_mfma_f32_16x16x32_f16 v[58:61], v[142:145], v[150:153], v[58:61]
	s_waitcnt lgkmcnt(2)
	v_mfma_f32_16x16x32_f16 v[46:49], v[130:133], v[200:203], v[46:49]
	v_mfma_f32_16x16x32_f16 v[42:45], v[142:145], v[200:203], v[42:45]
	s_waitcnt lgkmcnt(1)
	v_mfma_f32_16x16x32_f16 v[28:31], v[130:133], v[208:211], v[28:31]
	v_mfma_f32_16x16x32_f16 v[24:27], v[142:145], v[208:211], v[24:27]
	s_waitcnt lgkmcnt(0)
	v_mfma_f32_16x16x32_f16 v[12:15], v[130:133], v[216:219], v[12:15]
	v_mfma_f32_16x16x32_f16 v[8:11], v[142:145], v[216:219], v[8:11]
	s_setprio 0
	s_barrier
	s_add_u32 s10, s14, 0x40000
	s_addc_u32 s11, s15, 0
	s_add_i32 s38, s39, s20
	v_lshl_add_u64 v[122:123], s[10:11], 0, v[32:33]
	s_mov_b32 m0, s38
	s_nop 0
	global_load_lds_dwordx4 v[122:123], off
	v_lshl_add_u64 v[122:123], s[10:11], 0, v[154:155]
	s_add_i32 m0, s38, 0x2000
	s_nop 0
	global_load_lds_dwordx4 v[122:123], off
	s_waitcnt vmcnt(6)
	s_barrier
	s_setprio 1
	v_mfma_f32_16x16x32_f16 v[54:57], v[230:233], v[146:149], 0
	v_mfma_f32_16x16x32_f16 v[50:53], v[238:241], v[146:149], 0
	v_mfma_f32_16x16x32_f16 v[38:41], v[230:233], v[192:195], 0
	v_mfma_f32_16x16x32_f16 v[34:37], v[238:241], v[192:195], 0
	v_mfma_f32_16x16x32_f16 v[20:23], v[230:233], v[204:207], 0
	v_mfma_f32_16x16x32_f16 v[16:19], v[238:241], v[204:207], 0
	v_mfma_f32_16x16x32_f16 v[4:7], v[230:233], v[212:215], 0
	v_mfma_f32_16x16x32_f16 v[0:3], v[238:241], v[212:215], 0
	v_mfma_f32_16x16x32_f16 v[54:57], v[234:237], v[150:153], v[54:57]
	v_mfma_f32_16x16x32_f16 v[50:53], v[242:245], v[150:153], v[50:53]
	v_mfma_f32_16x16x32_f16 v[38:41], v[234:237], v[200:203], v[38:41]
	v_mfma_f32_16x16x32_f16 v[34:37], v[242:245], v[200:203], v[34:37]
	v_mfma_f32_16x16x32_f16 v[20:23], v[234:237], v[208:211], v[20:23]
	v_mfma_f32_16x16x32_f16 v[16:19], v[242:245], v[208:211], v[16:19]
	v_mfma_f32_16x16x32_f16 v[4:7], v[234:237], v[216:219], v[4:7]
	v_mfma_f32_16x16x32_f16 v[0:3], v[242:245], v[216:219], v[0:3]
	s_setprio 0
	s_add_i32 s38, 0, 0x18000
	v_add_u32_e32 v142, s38, v196
	s_barrier
	ds_read_b128 v[122:125], v142
	ds_read_b128 v[138:141], v142 offset:2048
	ds_read_b128 v[130:133], v142 offset:1024
	ds_read_b128 v[142:145], v142 offset:3072
	s_add_u32 s10, s16, 0x40000
	s_addc_u32 s11, s17, 0
	s_mov_b32 m0, s23
	v_lshl_add_u64 v[230:231], s[10:11], 0, v[32:33]
	ds_read_b128 v[146:149], v198 offset:32768
	ds_read_b128 v[192:195], v198 offset:34816
	ds_read_b128 v[204:207], v198 offset:36864
	ds_read_b128 v[212:215], v198 offset:38912
	ds_read_b128 v[150:153], v198 offset:33792
	ds_read_b128 v[200:203], v198 offset:35840
	ds_read_b128 v[208:211], v198 offset:37888
	ds_read_b128 v[216:219], v198 offset:39936
	global_load_lds_dwordx4 v[230:231], off
	v_lshl_add_u64 v[230:231], s[10:11], 0, v[154:155]
	s_mov_b32 m0, s24
	s_nop 0
	global_load_lds_dwordx4 v[230:231], off
	s_waitcnt lgkmcnt(8)
	s_barrier
	s_waitcnt lgkmcnt(7)
	s_setprio 1
	v_mfma_f32_16x16x32_f16 v[134:137], v[122:125], v[146:149], v[134:137]
	v_mfma_f32_16x16x32_f16 v[126:129], v[138:141], v[146:149], v[126:129]
	s_waitcnt lgkmcnt(6)
	v_mfma_f32_16x16x32_f16 v[110:113], v[122:125], v[192:195], v[110:113]
	v_mfma_f32_16x16x32_f16 v[106:109], v[138:141], v[192:195], v[106:109]
	s_waitcnt lgkmcnt(5)
	v_mfma_f32_16x16x32_f16 v[94:97], v[122:125], v[204:207], v[94:97]
	v_mfma_f32_16x16x32_f16 v[90:93], v[138:141], v[204:207], v[90:93]
	s_waitcnt lgkmcnt(4)
	v_mfma_f32_16x16x32_f16 v[78:81], v[122:125], v[212:215], v[78:81]
	v_mfma_f32_16x16x32_f16 v[74:77], v[138:141], v[212:215], v[74:77]
	s_waitcnt lgkmcnt(3)
	v_mfma_f32_16x16x32_f16 v[134:137], v[130:133], v[150:153], v[134:137]
	v_mfma_f32_16x16x32_f16 v[126:129], v[142:145], v[150:153], v[126:129]
	s_waitcnt lgkmcnt(2)
	v_mfma_f32_16x16x32_f16 v[110:113], v[130:133], v[200:203], v[110:113]
	v_mfma_f32_16x16x32_f16 v[106:109], v[142:145], v[200:203], v[106:109]
	s_waitcnt lgkmcnt(1)
	v_mfma_f32_16x16x32_f16 v[94:97], v[130:133], v[208:211], v[94:97]
	v_mfma_f32_16x16x32_f16 v[90:93], v[142:145], v[208:211], v[90:93]
	s_waitcnt lgkmcnt(0)
	v_mfma_f32_16x16x32_f16 v[78:81], v[130:133], v[216:219], v[78:81]
	v_mfma_f32_16x16x32_f16 v[74:77], v[142:145], v[216:219], v[74:77]
	s_setprio 0
	s_barrier
	s_add_i32 s16, 0, 0x1c000
	s_add_i32 s10, s38, s20
	v_add_u32_e32 v199, s16, v196
	v_lshl_add_u64 v[246:247], v[246:247], 0, s[84:85]
	s_mov_b32 m0, s10
	ds_read_b128 v[230:233], v199
	ds_read_b128 v[238:241], v199 offset:2048
	ds_read_b128 v[234:237], v199 offset:1024
	ds_read_b128 v[242:245], v199 offset:3072
	global_load_lds_dwordx4 v[246:247], off
	v_lshl_add_u64 v[246:247], v[248:249], 0, s[84:85]
	s_add_i32 m0, s10, 0x2000
	s_nop 0
	global_load_lds_dwordx4 v[246:247], off
	s_barrier
	s_waitcnt lgkmcnt(2)
	s_setprio 1
	v_mfma_f32_16x16x32_f16 v[118:121], v[230:233], v[146:149], v[118:121]
	v_mfma_f32_16x16x32_f16 v[114:117], v[238:241], v[146:149], v[114:117]
	v_mfma_f32_16x16x32_f16 v[102:105], v[230:233], v[192:195], v[102:105]
	v_mfma_f32_16x16x32_f16 v[98:101], v[238:241], v[192:195], v[98:101]
	v_mfma_f32_16x16x32_f16 v[86:89], v[230:233], v[204:207], v[86:89]
	v_mfma_f32_16x16x32_f16 v[82:85], v[238:241], v[204:207], v[82:85]
	v_mfma_f32_16x16x32_f16 v[70:73], v[230:233], v[212:215], v[70:73]
	v_mfma_f32_16x16x32_f16 v[66:69], v[238:241], v[212:215], v[66:69]
	s_waitcnt lgkmcnt(0)
	v_mfma_f32_16x16x32_f16 v[118:121], v[234:237], v[150:153], v[118:121]
	v_mfma_f32_16x16x32_f16 v[114:117], v[242:245], v[150:153], v[114:117]
	v_mfma_f32_16x16x32_f16 v[102:105], v[234:237], v[200:203], v[102:105]
	v_mfma_f32_16x16x32_f16 v[98:101], v[242:245], v[200:203], v[98:101]
	v_mfma_f32_16x16x32_f16 v[86:89], v[234:237], v[208:211], v[86:89]
	v_mfma_f32_16x16x32_f16 v[82:85], v[242:245], v[208:211], v[82:85]
	v_mfma_f32_16x16x32_f16 v[70:73], v[234:237], v[216:219], v[70:73]
	v_mfma_f32_16x16x32_f16 v[66:69], v[242:245], v[216:219], v[66:69]
	s_setprio 0
	s_mov_b32 m0, s25
	v_lshl_add_u64 v[228:229], v[228:229], 0, s[84:85]
	s_barrier
	ds_read_b128 v[146:149], v198 offset:49152
	ds_read_b128 v[192:195], v198 offset:51200
	ds_read_b128 v[204:207], v198 offset:53248
	ds_read_b128 v[212:215], v198 offset:55296
	ds_read_b128 v[150:153], v198 offset:50176
	ds_read_b128 v[200:203], v198 offset:52224
	ds_read_b128 v[208:211], v198 offset:54272
	ds_read_b128 v[216:219], v198 offset:56320
	global_load_lds_dwordx4 v[228:229], off
	v_lshl_add_u64 v[222:223], v[222:223], 0, s[84:85]
	s_mov_b32 m0, s27
	s_nop 0
	global_load_lds_dwordx4 v[222:223], off
	s_barrier
	s_waitcnt lgkmcnt(7)
	s_setprio 1
	v_mfma_f32_16x16x32_f16 v[62:65], v[122:125], v[146:149], v[62:65]
	v_mfma_f32_16x16x32_f16 v[58:61], v[138:141], v[146:149], v[58:61]
	s_waitcnt lgkmcnt(6)
	v_mfma_f32_16x16x32_f16 v[46:49], v[122:125], v[192:195], v[46:49]
	v_mfma_f32_16x16x32_f16 v[42:45], v[138:141], v[192:195], v[42:45]
	s_waitcnt lgkmcnt(5)
	v_mfma_f32_16x16x32_f16 v[28:31], v[122:125], v[204:207], v[28:31]
	v_mfma_f32_16x16x32_f16 v[24:27], v[138:141], v[204:207], v[24:27]
	s_waitcnt lgkmcnt(4)
	v_mfma_f32_16x16x32_f16 v[12:15], v[122:125], v[212:215], v[12:15]
	v_mfma_f32_16x16x32_f16 v[8:11], v[138:141], v[212:215], v[8:11]
	s_waitcnt lgkmcnt(3)
	v_mfma_f32_16x16x32_f16 v[62:65], v[130:133], v[150:153], v[62:65]
	v_mfma_f32_16x16x32_f16 v[58:61], v[142:145], v[150:153], v[58:61]
	s_waitcnt lgkmcnt(2)
	v_mfma_f32_16x16x32_f16 v[46:49], v[130:133], v[200:203], v[46:49]
	v_mfma_f32_16x16x32_f16 v[42:45], v[142:145], v[200:203], v[42:45]
	s_waitcnt lgkmcnt(1)
	v_mfma_f32_16x16x32_f16 v[28:31], v[130:133], v[208:211], v[28:31]
	v_mfma_f32_16x16x32_f16 v[24:27], v[142:145], v[208:211], v[24:27]
	s_waitcnt lgkmcnt(0)
	v_mfma_f32_16x16x32_f16 v[12:15], v[130:133], v[216:219], v[12:15]
	v_mfma_f32_16x16x32_f16 v[8:11], v[142:145], v[216:219], v[8:11]
	s_setprio 0
	s_barrier
	s_add_u32 s10, s14, 0x40080
	s_addc_u32 s11, s15, 0
	s_add_i32 s14, s16, s20
	v_lshl_add_u64 v[122:123], s[10:11], 0, v[32:33]
	s_mov_b32 m0, s14
	s_nop 0
	global_load_lds_dwordx4 v[122:123], off
	v_lshl_add_u64 v[122:123], s[10:11], 0, v[154:155]
	s_add_i32 m0, s14, 0x2000
	s_nop 0
	global_load_lds_dwordx4 v[122:123], off
	s_waitcnt vmcnt(6)
	s_barrier
	s_setprio 1
	v_mfma_f32_16x16x32_f16 v[54:57], v[230:233], v[146:149], v[54:57]
	v_mfma_f32_16x16x32_f16 v[50:53], v[238:241], v[146:149], v[50:53]
	v_mfma_f32_16x16x32_f16 v[38:41], v[230:233], v[192:195], v[38:41]
	v_mfma_f32_16x16x32_f16 v[34:37], v[238:241], v[192:195], v[34:37]
	v_mfma_f32_16x16x32_f16 v[20:23], v[230:233], v[204:207], v[20:23]
	v_mfma_f32_16x16x32_f16 v[16:19], v[238:241], v[204:207], v[16:19]
	v_mfma_f32_16x16x32_f16 v[4:7], v[230:233], v[212:215], v[4:7]
	v_mfma_f32_16x16x32_f16 v[0:3], v[238:241], v[212:215], v[0:3]
	v_mfma_f32_16x16x32_f16 v[54:57], v[234:237], v[150:153], v[54:57]
	v_mfma_f32_16x16x32_f16 v[50:53], v[242:245], v[150:153], v[50:53]
	v_mfma_f32_16x16x32_f16 v[38:41], v[234:237], v[200:203], v[38:41]
	v_mfma_f32_16x16x32_f16 v[34:37], v[242:245], v[200:203], v[34:37]
	v_mfma_f32_16x16x32_f16 v[20:23], v[234:237], v[208:211], v[20:23]
	v_mfma_f32_16x16x32_f16 v[16:19], v[242:245], v[208:211], v[16:19]
	v_mfma_f32_16x16x32_f16 v[4:7], v[234:237], v[216:219], v[4:7]
	v_mfma_f32_16x16x32_f16 v[0:3], v[242:245], v[216:219], v[0:3]
	s_setprio 0
	s_add_i32 s37, s37, 2
	s_add_u32 s35, s35, 0x100
	s_addc_u32 s36, s36, 0
	s_cmp_gt_u32 s37, 13
	s_mov_b64 s[10:11], s[12:13]
	s_barrier
	s_cbranch_scc0 .LBB0_958
	s_branch .Lpeelx2

.Lpeelx2:
	s_cmp_eq_u32 s34, 2
	s_movk_i32 s6, 0x2800
	v_lshl_or_b32 v122, s31, 8, v197
	s_cselect_b32 s6, 0x2000, s6
	s_mov_b32 s7, 0x23a3c000
	s_cselect_b32 s8, s7, 0x23abc000
	s_add_u32 s6, s70, s6
	v_ashrrev_i32_e32 v123, 31, v122
	s_addc_u32 s7, s71, 0
	v_lshlrev_b64 v[192:193], 1, v[122:123]
	v_lshl_add_u64 v[194:195], s[6:7], 0, v[192:193]
	v_lshl_add_u64 v[122:123], v[194:195], 0, v[156:157]
	v_lshl_add_u64 v[124:125], v[194:195], 0, v[158:159]
	v_lshl_add_u64 v[130:131], v[194:195], 0, v[160:161]
	v_lshl_add_u64 v[208:209], v[194:195], 0, v[162:163]
	global_load_dwordx4 v[200:203], v[122:123], off
	global_load_dwordx4 v[204:207], v[122:123], off offset:256
	global_load_dwordx4 v[150:153], v[124:125], off
	global_load_dwordx4 v[146:149], v[124:125], off offset:256
	global_load_dwordx4 v[142:145], v[130:131], off
	global_load_dwordx4 v[138:141], v[130:131], off offset:256
	s_nop 0
	global_load_dwordx4 v[130:133], v[208:209], off
	global_load_dwordx4 v[122:125], v[208:209], off offset:256
	v_readlane_b32 s36, v252, 26
	v_readlane_b32 s42, v252, 32
	v_readlane_b32 s43, v252, 33
	s_add_u32 s6, s42, s8
	s_addc_u32 s7, s43, 0
	v_readlane_b32 s37, v252, 27
	v_readlane_b32 s38, v252, 28
	v_readlane_b32 s39, v252, 29
	v_readlane_b32 s40, v252, 30
	v_readlane_b32 s41, v252, 31
	v_lshl_add_u64 v[192:193], s[6:7], 0, v[192:193]
	s_waitcnt vmcnt(0)
	v_cvt_f32_f16_e32 v199, v200
	v_cvt_f32_f16_sdwa v200, v200 dst_sel:DWORD dst_unused:UNUSED_PAD src0_sel:WORD_1
	v_cvt_f32_f16_e32 v210, v201
	v_lshl_add_u64 v[208:209], v[192:193], 0, v[164:165]
	v_max_f32_e32 v199, 0xc1f00000, v199
	v_mul_f32_e32 v199, 0xbfb8aa3b, v199
	v_exp_f32_e32 v199, v199
	v_max_f32_e32 v200, 0xc1f00000, v200
	v_max_f32_e32 v210, 0xc1f00000, v210
	v_mul_f32_e32 v200, 0xbfb8aa3b, v200
	v_add_f32_e32 v199, 1.0, v199
	v_rcp_f32_e32 v199, v199
	v_exp_f32_e32 v200, v200
	v_mul_f32_e32 v210, 0xbfb8aa3b, v210
	v_exp_f32_e32 v211, v210
	v_fma_mixlo_f16 v199, v134, v199, 0
	v_add_f32_e32 v134, 1.0, v200
	v_rcp_f32_e32 v210, v134
	v_add_f32_e32 v134, 1.0, v211
	v_cvt_f32_f16_sdwa v200, v201 dst_sel:DWORD dst_unused:UNUSED_PAD src0_sel:WORD_1
	v_rcp_f32_e32 v211, v134
	v_mov_b32_e32 v134, v135
	v_mov_b32_e32 v135, v136
	v_cvt_f32_f16_e32 v136, v202
	v_max_f32_e32 v200, 0xc1f00000, v200
	v_mul_f32_e32 v200, 0xbfb8aa3b, v200
	v_exp_f32_e32 v200, v200
	v_max_f32_e32 v136, 0xc1f00000, v136
	v_mul_f32_e32 v136, 0xbfb8aa3b, v136
	v_exp_f32_e32 v136, v136
	v_pk_mul_f32 v[134:135], v[134:135], v[210:211]
	s_nop 0
	v_cvt_pk_f16_f32 v135, v134, v135
	v_add_f32_e32 v134, 1.0, v200
	v_rcp_f32_e32 v200, v134
	v_add_f32_e32 v134, 1.0, v136
	v_rcp_f32_e32 v201, v134
	v_pk_mov_b32 v[136:137], v[136:137], v[126:127] op_sel:[1,0]
	v_cvt_f32_f16_sdwa v126, v202 dst_sel:DWORD dst_unused:UNUSED_PAD src0_sel:WORD_1
	v_pack_b32_f16 v134, v199, v135
	v_pk_mul_f32 v[136:137], v[136:137], v[200:201]
	v_cvt_f32_f16_sdwa v200, v203 dst_sel:DWORD dst_unused:UNUSED_PAD src0_sel:WORD_1
	v_cvt_pk_f16_f32 v199, v136, v137
	v_cvt_f32_f16_e32 v136, v203
	v_max_f32_e32 v126, 0xc1f00000, v126
	v_mul_f32_e32 v126, 0xbfb8aa3b, v126
	v_exp_f32_e32 v126, v126
	v_max_f32_e32 v136, 0xc1f00000, v136
	v_mul_f32_e32 v136, 0xbfb8aa3b, v136
	v_exp_f32_e32 v137, v136
	v_add_f32_e32 v126, 1.0, v126
	v_rcp_f32_e32 v136, v126
	v_alignbit_b32 v135, v199, v135, 16
	v_add_f32_e32 v126, 1.0, v137
	v_rcp_f32_e32 v137, v126
	v_mov_b32_e32 v126, v127
	v_mov_b32_e32 v127, v128
	v_cvt_f32_f16_e32 v128, v204
	v_pk_mul_f32 v[126:127], v[126:127], v[136:137]
	s_nop 0
	v_cvt_pk_f16_f32 v126, v126, v127
	v_max_f32_e32 v127, 0xc1f00000, v200
	v_mul_f32_e32 v127, 0xbfb8aa3b, v127
	v_exp_f32_e32 v127, v127
	v_alignbit_b32 v136, v126, v199, 16
	v_lshrrev_b32_e32 v137, 16, v126
	v_add_f32_e32 v126, 1.0, v127
	v_rcp_f32_e32 v126, v126
	v_max_f32_e32 v127, 0xc1f00000, v128
	v_mul_f32_e32 v127, 0xbfb8aa3b, v127
	v_exp_f32_e32 v127, v127
	v_fma_mixhi_f16 v137, v129, v126, 0
	v_cvt_f32_f16_sdwa v126, v204 dst_sel:DWORD dst_unused:UNUSED_PAD src0_sel:WORD_1
	v_cvt_f32_f16_e32 v128, v205
	v_add_f32_e32 v127, 1.0, v127
	v_rcp_f32_e32 v127, v127
	v_max_f32_e32 v126, 0xc1f00000, v126
	v_mul_f32_e32 v126, 0xbfb8aa3b, v126
	v_max_f32_e32 v128, 0xc1f00000, v128
	v_exp_f32_e32 v126, v126
	v_mul_f32_e32 v128, 0xbfb8aa3b, v128
	v_exp_f32_e32 v128, v128
	v_fma_mixlo_f16 v129, v118, v127, 0
	v_add_f32_e32 v118, 1.0, v126
	v_rcp_f32_e32 v126, v118
	v_add_f32_e32 v118, 1.0, v128
	v_rcp_f32_e32 v127, v118
	v_cvt_f32_f16_sdwa v128, v205 dst_sel:DWORD dst_unused:UNUSED_PAD src0_sel:WORD_1
	v_mov_b32_e32 v118, v119
	v_mov_b32_e32 v119, v120
	v_cvt_f32_f16_e32 v120, v206
	v_max_f32_e32 v128, 0xc1f00000, v128
	v_mul_f32_e32 v128, 0xbfb8aa3b, v128
	v_exp_f32_e32 v128, v128
	v_max_f32_e32 v120, 0xc1f00000, v120
	v_mul_f32_e32 v120, 0xbfb8aa3b, v120
	v_exp_f32_e32 v120, v120
	v_pk_mul_f32 v[118:119], v[118:119], v[126:127]
	v_add_f32_e32 v126, 1.0, v128
	v_rcp_f32_e32 v126, v126
	v_add_f32_e32 v120, 1.0, v120
	v_rcp_f32_e32 v127, v120
	v_pk_mov_b32 v[120:121], v[120:121], v[114:115] op_sel:[1,0]
	v_cvt_f32_f16_sdwa v114, v206 dst_sel:DWORD dst_unused:UNUSED_PAD src0_sel:WORD_1
	v_cvt_pk_f16_f32 v119, v118, v119
	v_pk_mul_f32 v[120:121], v[120:121], v[126:127]
	v_cvt_f32_f16_sdwa v127, v207 dst_sel:DWORD dst_unused:UNUSED_PAD src0_sel:WORD_1
	v_cvt_pk_f16_f32 v126, v120, v121
	v_cvt_f32_f16_e32 v120, v207
	v_max_f32_e32 v114, 0xc1f00000, v114
	v_mul_f32_e32 v114, 0xbfb8aa3b, v114
	v_exp_f32_e32 v114, v114
	v_max_f32_e32 v120, 0xc1f00000, v120
	v_mul_f32_e32 v120, 0xbfb8aa3b, v120
	v_exp_f32_e32 v121, v120
	v_add_f32_e32 v114, 1.0, v114
	v_rcp_f32_e32 v120, v114
	v_pack_b32_f16 v118, v129, v119
	v_add_f32_e32 v114, 1.0, v121
	v_rcp_f32_e32 v121, v114
	v_mov_b32_e32 v114, v115
	v_max_f32_e32 v115, 0xc1f00000, v127
	v_mul_f32_e32 v115, 0xbfb8aa3b, v115
	v_exp_f32_e32 v127, v115
	v_mov_b32_e32 v115, v116
	v_pk_mul_f32 v[114:115], v[114:115], v[120:121]
	v_cvt_f32_f16_e32 v116, v150
	v_cvt_pk_f16_f32 v114, v114, v115
	v_add_f32_e32 v115, 1.0, v127
	v_rcp_f32_e32 v115, v115
	v_alignbit_b32 v120, v114, v126, 16
	v_lshrrev_b32_e32 v121, 16, v114
	v_max_f32_e32 v114, 0xc1f00000, v116
	v_alignbit_b32 v119, v126, v119, 16
	v_fma_mixhi_f16 v121, v117, v115, 0
	v_mul_f32_e32 v114, 0xbfb8aa3b, v114
	v_cvt_f32_f16_sdwa v117, v150 dst_sel:DWORD dst_unused:UNUSED_PAD src0_sel:WORD_1
	v_exp_f32_e32 v116, v114
	global_store_dwordx4 v[208:209], v[118:121], off offset:256
	v_lshl_add_u64 v[114:115], v[192:193], 0, v[166:167]
	v_max_f32_e32 v117, 0xc1f00000, v117
	v_cvt_f32_f16_e32 v118, v151
	v_add_f32_e32 v116, 1.0, v116
	v_mul_f32_e32 v117, 0xbfb8aa3b, v117
	v_rcp_f32_e32 v116, v116
	v_max_f32_e32 v118, 0xc1f00000, v118
	v_exp_f32_e32 v117, v117
	v_mul_f32_e32 v118, 0xbfb8aa3b, v118
	v_exp_f32_e32 v118, v118
	v_fma_mixlo_f16 v119, v110, v116, 0
	v_add_f32_e32 v110, 1.0, v117
	v_rcp_f32_e32 v116, v110
	v_add_f32_e32 v110, 1.0, v118
	v_rcp_f32_e32 v117, v110
	v_cvt_f32_f16_sdwa v118, v151 dst_sel:DWORD dst_unused:UNUSED_PAD src0_sel:WORD_1
	v_mov_b32_e32 v110, v111
	v_mov_b32_e32 v111, v112
	v_cvt_f32_f16_e32 v112, v152
	v_pk_mul_f32 v[110:111], v[110:111], v[116:117]
	v_max_f32_e32 v116, 0xc1f00000, v118
	v_mul_f32_e32 v116, 0xbfb8aa3b, v116
	v_max_f32_e32 v112, 0xc1f00000, v112
	v_exp_f32_e32 v116, v116
	v_mul_f32_e32 v112, 0xbfb8aa3b, v112
	v_exp_f32_e32 v112, v112
	v_cvt_pk_f16_f32 v111, v110, v111
	v_add_f32_e32 v110, 1.0, v116
	v_rcp_f32_e32 v116, v110
	v_add_f32_e32 v110, 1.0, v112
	v_rcp_f32_e32 v117, v110
	v_pk_mov_b32 v[112:113], v[112:113], v[106:107] op_sel:[1,0]
	v_cvt_f32_f16_sdwa v106, v152 dst_sel:DWORD dst_unused:UNUSED_PAD src0_sel:WORD_1
	v_pack_b32_f16 v110, v119, v111
	v_pk_mul_f32 v[112:113], v[112:113], v[116:117]
	v_cvt_f32_f16_sdwa v117, v153 dst_sel:DWORD dst_unused:UNUSED_PAD src0_sel:WORD_1
	v_cvt_pk_f16_f32 v116, v112, v113
	v_cvt_f32_f16_e32 v112, v153
	v_max_f32_e32 v106, 0xc1f00000, v106
	v_mul_f32_e32 v106, 0xbfb8aa3b, v106
	v_exp_f32_e32 v106, v106
	v_max_f32_e32 v112, 0xc1f00000, v112
	v_mul_f32_e32 v112, 0xbfb8aa3b, v112
	v_exp_f32_e32 v113, v112
	v_add_f32_e32 v106, 1.0, v106
	v_rcp_f32_e32 v112, v106
	v_alignbit_b32 v111, v116, v111, 16
	v_add_f32_e32 v106, 1.0, v113
	v_rcp_f32_e32 v113, v106
	v_mov_b32_e32 v106, v107
	v_mov_b32_e32 v107, v108
	v_cvt_f32_f16_e32 v108, v146
	v_pk_mul_f32 v[106:107], v[106:107], v[112:113]
	global_store_dwordx4 v[208:209], v[134:137], off
	v_cvt_pk_f16_f32 v106, v106, v107
	v_max_f32_e32 v107, 0xc1f00000, v117
	v_mul_f32_e32 v107, 0xbfb8aa3b, v107
	v_exp_f32_e32 v107, v107
	v_alignbit_b32 v112, v106, v116, 16
	v_lshrrev_b32_e32 v113, 16, v106
	v_add_f32_e32 v106, 1.0, v107
	v_rcp_f32_e32 v106, v106
	v_max_f32_e32 v107, 0xc1f00000, v108
	v_mul_f32_e32 v107, 0xbfb8aa3b, v107
	v_exp_f32_e32 v107, v107
	v_fma_mixhi_f16 v113, v109, v106, 0
	v_cvt_f32_f16_sdwa v106, v146 dst_sel:DWORD dst_unused:UNUSED_PAD src0_sel:WORD_1
	v_cvt_f32_f16_e32 v108, v147
	v_add_f32_e32 v107, 1.0, v107
	v_rcp_f32_e32 v107, v107
	v_max_f32_e32 v106, 0xc1f00000, v106
	v_mul_f32_e32 v106, 0xbfb8aa3b, v106
	v_max_f32_e32 v108, 0xc1f00000, v108
	v_exp_f32_e32 v106, v106
	v_mul_f32_e32 v108, 0xbfb8aa3b, v108
	v_exp_f32_e32 v108, v108
	v_fma_mixlo_f16 v109, v102, v107, 0
	v_add_f32_e32 v102, 1.0, v106
	v_rcp_f32_e32 v106, v102
	v_add_f32_e32 v102, 1.0, v108
	v_rcp_f32_e32 v107, v102
	v_cvt_f32_f16_sdwa v108, v147 dst_sel:DWORD dst_unused:UNUSED_PAD src0_sel:WORD_1
	v_mov_b32_e32 v102, v103
	v_mov_b32_e32 v103, v104
	v_cvt_f32_f16_e32 v104, v148
	v_max_f32_e32 v108, 0xc1f00000, v108
	v_mul_f32_e32 v108, 0xbfb8aa3b, v108
	v_exp_f32_e32 v108, v108
	v_max_f32_e32 v104, 0xc1f00000, v104
	v_mul_f32_e32 v104, 0xbfb8aa3b, v104
	v_exp_f32_e32 v104, v104
	v_pk_mul_f32 v[102:103], v[102:103], v[106:107]
	v_add_f32_e32 v106, 1.0, v108
	v_rcp_f32_e32 v106, v106
	v_add_f32_e32 v104, 1.0, v104
	v_rcp_f32_e32 v107, v104
	v_pk_mov_b32 v[104:105], v[104:105], v[98:99] op_sel:[1,0]
	v_cvt_f32_f16_sdwa v98, v148 dst_sel:DWORD dst_unused:UNUSED_PAD src0_sel:WORD_1
	v_cvt_pk_f16_f32 v103, v102, v103
	v_pk_mul_f32 v[104:105], v[104:105], v[106:107]
	v_cvt_f32_f16_sdwa v107, v149 dst_sel:DWORD dst_unused:UNUSED_PAD src0_sel:WORD_1
	v_cvt_pk_f16_f32 v106, v104, v105
	v_cvt_f32_f16_e32 v104, v149
	v_max_f32_e32 v98, 0xc1f00000, v98
	v_mul_f32_e32 v98, 0xbfb8aa3b, v98
	v_exp_f32_e32 v98, v98
	v_max_f32_e32 v104, 0xc1f00000, v104
	v_mul_f32_e32 v104, 0xbfb8aa3b, v104
	v_exp_f32_e32 v105, v104
	v_add_f32_e32 v98, 1.0, v98
	v_rcp_f32_e32 v104, v98
	v_pack_b32_f16 v102, v109, v103
	v_add_f32_e32 v98, 1.0, v105
	v_rcp_f32_e32 v105, v98
	v_mov_b32_e32 v98, v99
	v_max_f32_e32 v99, 0xc1f00000, v107
	v_mul_f32_e32 v99, 0xbfb8aa3b, v99
	v_exp_f32_e32 v107, v99
	v_mov_b32_e32 v99, v100
	v_pk_mul_f32 v[98:99], v[98:99], v[104:105]
	v_cvt_f32_f16_e32 v100, v142
	v_cvt_pk_f16_f32 v98, v98, v99
	v_add_f32_e32 v99, 1.0, v107
	v_rcp_f32_e32 v99, v99
	v_alignbit_b32 v104, v98, v106, 16
	v_lshrrev_b32_e32 v105, 16, v98
	v_max_f32_e32 v98, 0xc1f00000, v100
	v_alignbit_b32 v103, v106, v103, 16
	v_fma_mixhi_f16 v105, v101, v99, 0
	v_mul_f32_e32 v98, 0xbfb8aa3b, v98
	v_cvt_f32_f16_sdwa v101, v142 dst_sel:DWORD dst_unused:UNUSED_PAD src0_sel:WORD_1
	v_exp_f32_e32 v100, v98
	global_store_dwordx4 v[114:115], v[102:105], off offset:256
	v_lshl_add_u64 v[98:99], v[192:193], 0, v[168:169]
	v_max_f32_e32 v101, 0xc1f00000, v101
	v_cvt_f32_f16_e32 v102, v143
	v_add_f32_e32 v100, 1.0, v100
	v_mul_f32_e32 v101, 0xbfb8aa3b, v101
	v_rcp_f32_e32 v100, v100
	v_max_f32_e32 v102, 0xc1f00000, v102
	v_exp_f32_e32 v101, v101
	v_mul_f32_e32 v102, 0xbfb8aa3b, v102
	v_exp_f32_e32 v102, v102
	v_fma_mixlo_f16 v103, v94, v100, 0
	v_add_f32_e32 v94, 1.0, v101
	v_rcp_f32_e32 v100, v94
	v_add_f32_e32 v94, 1.0, v102
	v_rcp_f32_e32 v101, v94
	v_cvt_f32_f16_sdwa v102, v143 dst_sel:DWORD dst_unused:UNUSED_PAD src0_sel:WORD_1
	v_mov_b32_e32 v94, v95
	v_mov_b32_e32 v95, v96
	v_cvt_f32_f16_e32 v96, v144
	v_pk_mul_f32 v[94:95], v[94:95], v[100:101]
	v_max_f32_e32 v100, 0xc1f00000, v102
	v_mul_f32_e32 v100, 0xbfb8aa3b, v100
	v_max_f32_e32 v96, 0xc1f00000, v96
	v_exp_f32_e32 v100, v100
	v_mul_f32_e32 v96, 0xbfb8aa3b, v96
	v_exp_f32_e32 v96, v96
	v_cvt_pk_f16_f32 v95, v94, v95
	v_add_f32_e32 v94, 1.0, v100
	v_rcp_f32_e32 v100, v94
	v_add_f32_e32 v94, 1.0, v96
	v_rcp_f32_e32 v101, v94
	v_pk_mov_b32 v[96:97], v[96:97], v[90:91] op_sel:[1,0]
	v_cvt_f32_f16_sdwa v90, v144 dst_sel:DWORD dst_unused:UNUSED_PAD src0_sel:WORD_1
	v_pack_b32_f16 v94, v103, v95
	v_pk_mul_f32 v[96:97], v[96:97], v[100:101]
	v_cvt_f32_f16_sdwa v101, v145 dst_sel:DWORD dst_unused:UNUSED_PAD src0_sel:WORD_1
	v_cvt_pk_f16_f32 v100, v96, v97
	v_cvt_f32_f16_e32 v96, v145
	v_max_f32_e32 v90, 0xc1f00000, v90
	v_mul_f32_e32 v90, 0xbfb8aa3b, v90
	v_exp_f32_e32 v90, v90
	v_max_f32_e32 v96, 0xc1f00000, v96
	v_mul_f32_e32 v96, 0xbfb8aa3b, v96
	v_exp_f32_e32 v97, v96
	v_add_f32_e32 v90, 1.0, v90
	v_rcp_f32_e32 v96, v90
	v_alignbit_b32 v95, v100, v95, 16
	v_add_f32_e32 v90, 1.0, v97
	v_rcp_f32_e32 v97, v90
	v_mov_b32_e32 v90, v91
	v_mov_b32_e32 v91, v92
	v_cvt_f32_f16_e32 v92, v138
	v_pk_mul_f32 v[90:91], v[90:91], v[96:97]
	global_store_dwordx4 v[114:115], v[110:113], off
	v_cvt_pk_f16_f32 v90, v90, v91
	v_max_f32_e32 v91, 0xc1f00000, v101
	v_mul_f32_e32 v91, 0xbfb8aa3b, v91
	v_exp_f32_e32 v91, v91
	v_alignbit_b32 v96, v90, v100, 16
	v_lshrrev_b32_e32 v97, 16, v90
	v_add_f32_e32 v90, 1.0, v91
	v_rcp_f32_e32 v90, v90
	v_max_f32_e32 v91, 0xc1f00000, v92
	v_mul_f32_e32 v91, 0xbfb8aa3b, v91
	v_exp_f32_e32 v91, v91
	v_fma_mixhi_f16 v97, v93, v90, 0
	v_cvt_f32_f16_sdwa v90, v138 dst_sel:DWORD dst_unused:UNUSED_PAD src0_sel:WORD_1
	v_cvt_f32_f16_e32 v92, v139
	v_add_f32_e32 v91, 1.0, v91
	v_rcp_f32_e32 v91, v91
	v_max_f32_e32 v90, 0xc1f00000, v90
	v_mul_f32_e32 v90, 0xbfb8aa3b, v90
	v_max_f32_e32 v92, 0xc1f00000, v92
	v_exp_f32_e32 v90, v90
	v_mul_f32_e32 v92, 0xbfb8aa3b, v92
	v_exp_f32_e32 v92, v92
	v_fma_mixlo_f16 v93, v86, v91, 0
	v_add_f32_e32 v86, 1.0, v90
	v_rcp_f32_e32 v90, v86
	v_add_f32_e32 v86, 1.0, v92
	v_rcp_f32_e32 v91, v86
	v_cvt_f32_f16_sdwa v92, v139 dst_sel:DWORD dst_unused:UNUSED_PAD src0_sel:WORD_1
	v_mov_b32_e32 v86, v87
	v_mov_b32_e32 v87, v88
	v_cvt_f32_f16_e32 v88, v140
	v_max_f32_e32 v92, 0xc1f00000, v92
	v_mul_f32_e32 v92, 0xbfb8aa3b, v92
	v_exp_f32_e32 v92, v92
	v_max_f32_e32 v88, 0xc1f00000, v88
	v_mul_f32_e32 v88, 0xbfb8aa3b, v88
	v_exp_f32_e32 v88, v88
	v_pk_mul_f32 v[86:87], v[86:87], v[90:91]
	v_add_f32_e32 v90, 1.0, v92
	v_rcp_f32_e32 v90, v90
	v_add_f32_e32 v88, 1.0, v88
	v_rcp_f32_e32 v91, v88
	v_pk_mov_b32 v[88:89], v[88:89], v[82:83] op_sel:[1,0]
	v_cvt_f32_f16_sdwa v82, v140 dst_sel:DWORD dst_unused:UNUSED_PAD src0_sel:WORD_1
	v_cvt_pk_f16_f32 v87, v86, v87
	v_pk_mul_f32 v[88:89], v[88:89], v[90:91]
	v_cvt_f32_f16_sdwa v91, v141 dst_sel:DWORD dst_unused:UNUSED_PAD src0_sel:WORD_1
	v_cvt_pk_f16_f32 v90, v88, v89
	v_cvt_f32_f16_e32 v88, v141
	v_max_f32_e32 v82, 0xc1f00000, v82
	v_mul_f32_e32 v82, 0xbfb8aa3b, v82
	v_exp_f32_e32 v82, v82
	v_max_f32_e32 v88, 0xc1f00000, v88
	v_mul_f32_e32 v88, 0xbfb8aa3b, v88
	v_exp_f32_e32 v89, v88
	v_add_f32_e32 v82, 1.0, v82
	v_rcp_f32_e32 v88, v82
	v_pack_b32_f16 v86, v93, v87
	v_add_f32_e32 v82, 1.0, v89
	v_rcp_f32_e32 v89, v82
	v_mov_b32_e32 v82, v83
	v_max_f32_e32 v83, 0xc1f00000, v91
	v_mul_f32_e32 v83, 0xbfb8aa3b, v83
	v_exp_f32_e32 v91, v83
	v_mov_b32_e32 v83, v84
	v_pk_mul_f32 v[82:83], v[82:83], v[88:89]
	v_cvt_f32_f16_e32 v84, v130
	v_cvt_pk_f16_f32 v82, v82, v83
	v_add_f32_e32 v83, 1.0, v91
	v_rcp_f32_e32 v83, v83
	v_alignbit_b32 v88, v82, v90, 16
	v_lshrrev_b32_e32 v89, 16, v82
	v_max_f32_e32 v82, 0xc1f00000, v84
	v_alignbit_b32 v87, v90, v87, 16
	v_fma_mixhi_f16 v89, v85, v83, 0
	v_mul_f32_e32 v82, 0xbfb8aa3b, v82
	v_cvt_f32_f16_sdwa v85, v130 dst_sel:DWORD dst_unused:UNUSED_PAD src0_sel:WORD_1
	v_exp_f32_e32 v84, v82
	global_store_dwordx4 v[98:99], v[86:89], off offset:256
	v_lshl_add_u64 v[82:83], v[192:193], 0, v[170:171]
	v_max_f32_e32 v85, 0xc1f00000, v85
	v_cvt_f32_f16_e32 v86, v131
	v_add_f32_e32 v84, 1.0, v84
	v_mul_f32_e32 v85, 0xbfb8aa3b, v85
	v_rcp_f32_e32 v84, v84
	v_max_f32_e32 v86, 0xc1f00000, v86
	v_exp_f32_e32 v85, v85
	v_mul_f32_e32 v86, 0xbfb8aa3b, v86
	v_exp_f32_e32 v86, v86
	v_fma_mixlo_f16 v87, v78, v84, 0
	v_add_f32_e32 v78, 1.0, v85
	v_rcp_f32_e32 v84, v78
	v_add_f32_e32 v78, 1.0, v86
	v_rcp_f32_e32 v85, v78
	v_cvt_f32_f16_sdwa v86, v131 dst_sel:DWORD dst_unused:UNUSED_PAD src0_sel:WORD_1
	v_mov_b32_e32 v78, v79
	v_mov_b32_e32 v79, v80
	v_cvt_f32_f16_e32 v80, v132
	v_pk_mul_f32 v[78:79], v[78:79], v[84:85]
	v_max_f32_e32 v84, 0xc1f00000, v86
	v_mul_f32_e32 v84, 0xbfb8aa3b, v84
	v_max_f32_e32 v80, 0xc1f00000, v80
	v_exp_f32_e32 v84, v84
	v_mul_f32_e32 v80, 0xbfb8aa3b, v80
	v_exp_f32_e32 v80, v80
	v_cvt_pk_f16_f32 v79, v78, v79
	v_add_f32_e32 v78, 1.0, v84
	v_rcp_f32_e32 v84, v78
	v_add_f32_e32 v78, 1.0, v80
	v_rcp_f32_e32 v85, v78
	v_pk_mov_b32 v[80:81], v[80:81], v[74:75] op_sel:[1,0]
	v_cvt_f32_f16_sdwa v74, v132 dst_sel:DWORD dst_unused:UNUSED_PAD src0_sel:WORD_1
	v_pack_b32_f16 v78, v87, v79
	v_pk_mul_f32 v[80:81], v[80:81], v[84:85]
	v_cvt_f32_f16_sdwa v85, v133 dst_sel:DWORD dst_unused:UNUSED_PAD src0_sel:WORD_1
	v_cvt_pk_f16_f32 v84, v80, v81
	v_cvt_f32_f16_e32 v80, v133
	v_max_f32_e32 v74, 0xc1f00000, v74
	v_mul_f32_e32 v74, 0xbfb8aa3b, v74
	v_exp_f32_e32 v74, v74
	v_max_f32_e32 v80, 0xc1f00000, v80
	v_mul_f32_e32 v80, 0xbfb8aa3b, v80
	v_exp_f32_e32 v81, v80
	v_add_f32_e32 v74, 1.0, v74
	v_rcp_f32_e32 v80, v74
	v_alignbit_b32 v79, v84, v79, 16
	v_add_f32_e32 v74, 1.0, v81
	v_rcp_f32_e32 v81, v74
	v_mov_b32_e32 v74, v75
	v_mov_b32_e32 v75, v76
	v_cvt_f32_f16_e32 v76, v122
	v_pk_mul_f32 v[74:75], v[74:75], v[80:81]
	global_store_dwordx4 v[98:99], v[94:97], off
	v_cvt_pk_f16_f32 v74, v74, v75
	v_max_f32_e32 v75, 0xc1f00000, v85
	v_mul_f32_e32 v75, 0xbfb8aa3b, v75
	v_exp_f32_e32 v75, v75
	v_alignbit_b32 v80, v74, v84, 16
	v_lshrrev_b32_e32 v81, 16, v74
	v_add_f32_e32 v74, 1.0, v75
	v_rcp_f32_e32 v74, v74
	v_max_f32_e32 v75, 0xc1f00000, v76
	v_mul_f32_e32 v75, 0xbfb8aa3b, v75
	v_exp_f32_e32 v75, v75
	v_fma_mixhi_f16 v81, v77, v74, 0
	v_cvt_f32_f16_sdwa v74, v122 dst_sel:DWORD dst_unused:UNUSED_PAD src0_sel:WORD_1
	v_cvt_f32_f16_e32 v76, v123
	v_add_f32_e32 v75, 1.0, v75
	v_rcp_f32_e32 v75, v75
	v_max_f32_e32 v74, 0xc1f00000, v74
	v_mul_f32_e32 v74, 0xbfb8aa3b, v74
	v_max_f32_e32 v76, 0xc1f00000, v76
	v_exp_f32_e32 v74, v74
	v_mul_f32_e32 v76, 0xbfb8aa3b, v76
	v_exp_f32_e32 v76, v76
	v_fma_mixlo_f16 v77, v70, v75, 0
	v_add_f32_e32 v70, 1.0, v74
	v_rcp_f32_e32 v74, v70
	v_add_f32_e32 v70, 1.0, v76
	v_rcp_f32_e32 v75, v70
	v_cvt_f32_f16_sdwa v76, v123 dst_sel:DWORD dst_unused:UNUSED_PAD src0_sel:WORD_1
	v_mov_b32_e32 v70, v71
	v_mov_b32_e32 v71, v72
	v_cvt_f32_f16_e32 v72, v124
	v_max_f32_e32 v76, 0xc1f00000, v76
	v_mul_f32_e32 v76, 0xbfb8aa3b, v76
	v_exp_f32_e32 v76, v76
	v_max_f32_e32 v72, 0xc1f00000, v72
	v_mul_f32_e32 v72, 0xbfb8aa3b, v72
	v_exp_f32_e32 v72, v72
	v_pk_mul_f32 v[70:71], v[70:71], v[74:75]
	v_add_f32_e32 v74, 1.0, v76
	v_rcp_f32_e32 v74, v74
	v_add_f32_e32 v72, 1.0, v72
	v_rcp_f32_e32 v75, v72
	v_pk_mov_b32 v[72:73], v[72:73], v[66:67] op_sel:[1,0]
	v_cvt_f32_f16_sdwa v66, v124 dst_sel:DWORD dst_unused:UNUSED_PAD src0_sel:WORD_1
	v_cvt_pk_f16_f32 v71, v70, v71
	v_pk_mul_f32 v[72:73], v[72:73], v[74:75]
	v_cvt_f32_f16_sdwa v75, v125 dst_sel:DWORD dst_unused:UNUSED_PAD src0_sel:WORD_1
	v_cvt_pk_f16_f32 v74, v72, v73
	v_cvt_f32_f16_e32 v72, v125
	v_max_f32_e32 v66, 0xc1f00000, v66
	v_mul_f32_e32 v66, 0xbfb8aa3b, v66
	v_exp_f32_e32 v66, v66
	v_max_f32_e32 v72, 0xc1f00000, v72
	v_mul_f32_e32 v72, 0xbfb8aa3b, v72
	v_exp_f32_e32 v73, v72
	v_add_f32_e32 v66, 1.0, v66
	v_rcp_f32_e32 v72, v66
	v_pack_b32_f16 v70, v77, v71
	v_add_f32_e32 v66, 1.0, v73
	v_rcp_f32_e32 v73, v66
	v_max_f32_e32 v66, 0xc1f00000, v75
	v_mul_f32_e32 v66, 0xbfb8aa3b, v66
	v_exp_f32_e32 v75, v66
	v_mov_b32_e32 v66, v67
	v_mov_b32_e32 v67, v68
	v_pk_mul_f32 v[66:67], v[66:67], v[72:73]
	v_add_f32_e32 v68, 1.0, v75
	v_rcp_f32_e32 v68, v68
	v_cvt_pk_f16_f32 v66, v66, v67
	v_lshrrev_b32_e32 v73, 16, v66
	v_alignbit_b32 v71, v74, v71, 16
	v_alignbit_b32 v72, v66, v74, 16
	v_fma_mixhi_f16 v73, v69, v68, 0
	global_store_dwordx4 v[82:83], v[78:81], off
	global_store_dwordx4 v[82:83], v[70:73], off offset:256
	v_lshl_add_u64 v[66:67], v[194:195], 0, v[172:173]
	v_lshl_add_u64 v[68:69], v[194:195], 0, v[174:175]
	v_lshl_add_u64 v[70:71], v[194:195], 0, v[176:177]
	v_lshl_add_u64 v[98:99], v[194:195], 0, v[178:179]
	global_load_dwordx4 v[90:93], v[66:67], off
	global_load_dwordx4 v[94:97], v[66:67], off offset:256
	global_load_dwordx4 v[86:89], v[68:69], off
	global_load_dwordx4 v[82:85], v[68:69], off offset:256
	global_load_dwordx4 v[78:81], v[70:71], off
	global_load_dwordx4 v[74:77], v[70:71], off offset:256
	s_nop 0
	global_load_dwordx4 v[70:73], v[98:99], off
	global_load_dwordx4 v[66:69], v[98:99], off offset:256
	s_waitcnt vmcnt(0)
	v_cvt_f32_f16_e32 v100, v90
	v_cvt_f32_f16_sdwa v90, v90 dst_sel:DWORD dst_unused:UNUSED_PAD src0_sel:WORD_1
	v_cvt_f32_f16_e32 v101, v91
	v_lshl_add_u64 v[98:99], v[192:193], 0, v[180:181]
	v_max_f32_e32 v100, 0xc1f00000, v100
	v_mul_f32_e32 v100, 0xbfb8aa3b, v100
	v_exp_f32_e32 v100, v100
	v_max_f32_e32 v90, 0xc1f00000, v90
	v_max_f32_e32 v101, 0xc1f00000, v101
	v_mul_f32_e32 v90, 0xbfb8aa3b, v90
	v_add_f32_e32 v100, 1.0, v100
	v_rcp_f32_e32 v100, v100
	v_exp_f32_e32 v90, v90
	v_mul_f32_e32 v101, 0xbfb8aa3b, v101
	v_exp_f32_e32 v101, v101
	v_fma_mixlo_f16 v102, v62, v100, 0
	v_add_f32_e32 v62, 1.0, v90
	v_rcp_f32_e32 v100, v62
	v_add_f32_e32 v62, 1.0, v101
	v_cvt_f32_f16_sdwa v90, v91 dst_sel:DWORD dst_unused:UNUSED_PAD src0_sel:WORD_1
	v_rcp_f32_e32 v101, v62
	v_mov_b32_e32 v62, v63
	v_mov_b32_e32 v63, v64
	v_cvt_f32_f16_e32 v64, v92
	v_max_f32_e32 v90, 0xc1f00000, v90
	v_mul_f32_e32 v90, 0xbfb8aa3b, v90
	v_exp_f32_e32 v90, v90
	v_max_f32_e32 v64, 0xc1f00000, v64
	v_mul_f32_e32 v64, 0xbfb8aa3b, v64
	v_exp_f32_e32 v64, v64
	v_pk_mul_f32 v[62:63], v[62:63], v[100:101]
	s_nop 0
	v_cvt_pk_f16_f32 v63, v62, v63
	v_add_f32_e32 v62, 1.0, v90
	v_rcp_f32_e32 v90, v62
	v_add_f32_e32 v62, 1.0, v64
	v_rcp_f32_e32 v91, v62
	v_pk_mov_b32 v[64:65], v[64:65], v[58:59] op_sel:[1,0]
	v_cvt_f32_f16_sdwa v58, v92 dst_sel:DWORD dst_unused:UNUSED_PAD src0_sel:WORD_1
	v_pack_b32_f16 v62, v102, v63
	v_pk_mul_f32 v[64:65], v[64:65], v[90:91]
	v_cvt_f32_f16_sdwa v91, v93 dst_sel:DWORD dst_unused:UNUSED_PAD src0_sel:WORD_1
	v_cvt_pk_f16_f32 v90, v64, v65
	v_cvt_f32_f16_e32 v64, v93
	v_max_f32_e32 v58, 0xc1f00000, v58
	v_mul_f32_e32 v58, 0xbfb8aa3b, v58
	v_exp_f32_e32 v58, v58
	v_max_f32_e32 v64, 0xc1f00000, v64
	v_mul_f32_e32 v64, 0xbfb8aa3b, v64
	v_exp_f32_e32 v65, v64
	v_add_f32_e32 v58, 1.0, v58
	v_rcp_f32_e32 v64, v58
	v_alignbit_b32 v63, v90, v63, 16
	v_add_f32_e32 v58, 1.0, v65
	v_rcp_f32_e32 v65, v58
	v_mov_b32_e32 v58, v59
	v_mov_b32_e32 v59, v60
	v_cvt_f32_f16_e32 v60, v94
	v_pk_mul_f32 v[58:59], v[58:59], v[64:65]
	s_nop 0
	v_cvt_pk_f16_f32 v58, v58, v59
	v_max_f32_e32 v59, 0xc1f00000, v91
	v_mul_f32_e32 v59, 0xbfb8aa3b, v59
	v_exp_f32_e32 v59, v59
	v_alignbit_b32 v64, v58, v90, 16
	v_lshrrev_b32_e32 v65, 16, v58
	v_add_f32_e32 v58, 1.0, v59
	v_rcp_f32_e32 v58, v58
	v_max_f32_e32 v59, 0xc1f00000, v60
	v_mul_f32_e32 v59, 0xbfb8aa3b, v59
	v_exp_f32_e32 v59, v59
	v_fma_mixhi_f16 v65, v61, v58, 0
	v_cvt_f32_f16_sdwa v58, v94 dst_sel:DWORD dst_unused:UNUSED_PAD src0_sel:WORD_1
	v_cvt_f32_f16_e32 v60, v95
	v_add_f32_e32 v59, 1.0, v59
	v_rcp_f32_e32 v59, v59
	v_max_f32_e32 v58, 0xc1f00000, v58
	v_mul_f32_e32 v58, 0xbfb8aa3b, v58
	v_max_f32_e32 v60, 0xc1f00000, v60
	v_exp_f32_e32 v58, v58
	v_mul_f32_e32 v60, 0xbfb8aa3b, v60
	v_exp_f32_e32 v60, v60
	v_fma_mixlo_f16 v61, v54, v59, 0
	v_add_f32_e32 v54, 1.0, v58
	v_rcp_f32_e32 v58, v54
	v_add_f32_e32 v54, 1.0, v60
	v_rcp_f32_e32 v59, v54
	v_cvt_f32_f16_sdwa v60, v95 dst_sel:DWORD dst_unused:UNUSED_PAD src0_sel:WORD_1
	v_mov_b32_e32 v54, v55
	v_mov_b32_e32 v55, v56
	v_cvt_f32_f16_e32 v56, v96
	v_max_f32_e32 v60, 0xc1f00000, v60
	v_mul_f32_e32 v60, 0xbfb8aa3b, v60
	v_exp_f32_e32 v60, v60
	v_max_f32_e32 v56, 0xc1f00000, v56
	v_mul_f32_e32 v56, 0xbfb8aa3b, v56
	v_exp_f32_e32 v56, v56
	v_pk_mul_f32 v[54:55], v[54:55], v[58:59]
	v_add_f32_e32 v58, 1.0, v60
	v_rcp_f32_e32 v58, v58
	v_add_f32_e32 v56, 1.0, v56
	v_rcp_f32_e32 v59, v56
	v_pk_mov_b32 v[56:57], v[56:57], v[50:51] op_sel:[1,0]
	v_cvt_f32_f16_sdwa v50, v96 dst_sel:DWORD dst_unused:UNUSED_PAD src0_sel:WORD_1
	v_cvt_pk_f16_f32 v55, v54, v55
	v_pk_mul_f32 v[56:57], v[56:57], v[58:59]
	v_cvt_f32_f16_sdwa v59, v97 dst_sel:DWORD dst_unused:UNUSED_PAD src0_sel:WORD_1
	v_cvt_pk_f16_f32 v58, v56, v57
	v_cvt_f32_f16_e32 v56, v97
	v_max_f32_e32 v50, 0xc1f00000, v50
	v_mul_f32_e32 v50, 0xbfb8aa3b, v50
	v_exp_f32_e32 v50, v50
	v_max_f32_e32 v56, 0xc1f00000, v56
	v_mul_f32_e32 v56, 0xbfb8aa3b, v56
	v_exp_f32_e32 v57, v56
	v_add_f32_e32 v50, 1.0, v50
	v_rcp_f32_e32 v56, v50
	v_pack_b32_f16 v54, v61, v55
	v_add_f32_e32 v50, 1.0, v57
	v_rcp_f32_e32 v57, v50
	v_mov_b32_e32 v50, v51
	v_max_f32_e32 v51, 0xc1f00000, v59
	v_mul_f32_e32 v51, 0xbfb8aa3b, v51
	v_exp_f32_e32 v59, v51
	v_mov_b32_e32 v51, v52
	v_pk_mul_f32 v[50:51], v[50:51], v[56:57]
	v_cvt_f32_f16_e32 v52, v86
	v_cvt_pk_f16_f32 v50, v50, v51
	v_add_f32_e32 v51, 1.0, v59
	v_rcp_f32_e32 v51, v51
	v_alignbit_b32 v56, v50, v58, 16
	v_lshrrev_b32_e32 v57, 16, v50
	v_max_f32_e32 v50, 0xc1f00000, v52
	v_alignbit_b32 v55, v58, v55, 16
	v_fma_mixhi_f16 v57, v53, v51, 0
	v_mul_f32_e32 v50, 0xbfb8aa3b, v50
	v_cvt_f32_f16_sdwa v53, v86 dst_sel:DWORD dst_unused:UNUSED_PAD src0_sel:WORD_1
	v_exp_f32_e32 v52, v50
	global_store_dwordx4 v[98:99], v[54:57], off offset:256
	v_lshl_add_u64 v[50:51], v[192:193], 0, v[182:183]
	v_max_f32_e32 v53, 0xc1f00000, v53
	v_cvt_f32_f16_e32 v54, v87
	v_add_f32_e32 v52, 1.0, v52
	v_mul_f32_e32 v53, 0xbfb8aa3b, v53
	v_rcp_f32_e32 v52, v52
	v_max_f32_e32 v54, 0xc1f00000, v54
	v_exp_f32_e32 v53, v53
	v_mul_f32_e32 v54, 0xbfb8aa3b, v54
	v_exp_f32_e32 v54, v54
	v_fma_mixlo_f16 v55, v46, v52, 0
	v_add_f32_e32 v46, 1.0, v53
	v_rcp_f32_e32 v52, v46
	v_add_f32_e32 v46, 1.0, v54
	v_rcp_f32_e32 v53, v46
	v_cvt_f32_f16_sdwa v54, v87 dst_sel:DWORD dst_unused:UNUSED_PAD src0_sel:WORD_1
	v_mov_b32_e32 v46, v47
	v_mov_b32_e32 v47, v48
	v_cvt_f32_f16_e32 v48, v88
	v_pk_mul_f32 v[46:47], v[46:47], v[52:53]
	v_max_f32_e32 v52, 0xc1f00000, v54
	v_mul_f32_e32 v52, 0xbfb8aa3b, v52
	v_max_f32_e32 v48, 0xc1f00000, v48
	v_exp_f32_e32 v52, v52
	v_mul_f32_e32 v48, 0xbfb8aa3b, v48
	v_exp_f32_e32 v48, v48
	v_cvt_pk_f16_f32 v47, v46, v47
	v_add_f32_e32 v46, 1.0, v52
	v_rcp_f32_e32 v52, v46
	v_add_f32_e32 v46, 1.0, v48
	v_rcp_f32_e32 v53, v46
	v_pk_mov_b32 v[48:49], v[48:49], v[42:43] op_sel:[1,0]
	v_cvt_f32_f16_sdwa v42, v88 dst_sel:DWORD dst_unused:UNUSED_PAD src0_sel:WORD_1
	v_pack_b32_f16 v46, v55, v47
	v_pk_mul_f32 v[48:49], v[48:49], v[52:53]
	v_cvt_f32_f16_sdwa v53, v89 dst_sel:DWORD dst_unused:UNUSED_PAD src0_sel:WORD_1
	v_cvt_pk_f16_f32 v52, v48, v49
	v_cvt_f32_f16_e32 v48, v89
	v_max_f32_e32 v42, 0xc1f00000, v42
	v_mul_f32_e32 v42, 0xbfb8aa3b, v42
	v_exp_f32_e32 v42, v42
	v_max_f32_e32 v48, 0xc1f00000, v48
	v_mul_f32_e32 v48, 0xbfb8aa3b, v48
	v_exp_f32_e32 v49, v48
	v_add_f32_e32 v42, 1.0, v42
	v_rcp_f32_e32 v48, v42
	v_alignbit_b32 v47, v52, v47, 16
	v_add_f32_e32 v42, 1.0, v49
	v_rcp_f32_e32 v49, v42
	v_mov_b32_e32 v42, v43
	v_mov_b32_e32 v43, v44
	v_cvt_f32_f16_e32 v44, v82
	v_pk_mul_f32 v[42:43], v[42:43], v[48:49]
	global_store_dwordx4 v[98:99], v[62:65], off
	v_cvt_pk_f16_f32 v42, v42, v43
	v_max_f32_e32 v43, 0xc1f00000, v53
	v_mul_f32_e32 v43, 0xbfb8aa3b, v43
	v_exp_f32_e32 v43, v43
	v_alignbit_b32 v48, v42, v52, 16
	v_lshrrev_b32_e32 v49, 16, v42
	v_add_f32_e32 v42, 1.0, v43
	v_rcp_f32_e32 v42, v42
	v_max_f32_e32 v43, 0xc1f00000, v44
	v_mul_f32_e32 v43, 0xbfb8aa3b, v43
	v_exp_f32_e32 v43, v43
	v_fma_mixhi_f16 v49, v45, v42, 0
	v_cvt_f32_f16_sdwa v42, v82 dst_sel:DWORD dst_unused:UNUSED_PAD src0_sel:WORD_1
	v_cvt_f32_f16_e32 v44, v83
	v_add_f32_e32 v43, 1.0, v43
	v_rcp_f32_e32 v43, v43
	v_max_f32_e32 v42, 0xc1f00000, v42
	v_mul_f32_e32 v42, 0xbfb8aa3b, v42
	v_max_f32_e32 v44, 0xc1f00000, v44
	v_exp_f32_e32 v42, v42
	v_mul_f32_e32 v44, 0xbfb8aa3b, v44
	v_exp_f32_e32 v44, v44
	v_fma_mixlo_f16 v45, v38, v43, 0
	v_add_f32_e32 v38, 1.0, v42
	v_rcp_f32_e32 v42, v38
	v_add_f32_e32 v38, 1.0, v44
	v_rcp_f32_e32 v43, v38
	v_cvt_f32_f16_sdwa v44, v83 dst_sel:DWORD dst_unused:UNUSED_PAD src0_sel:WORD_1
	v_mov_b32_e32 v38, v39
	v_mov_b32_e32 v39, v40
	v_cvt_f32_f16_e32 v40, v84
	v_max_f32_e32 v44, 0xc1f00000, v44
	v_mul_f32_e32 v44, 0xbfb8aa3b, v44
	v_exp_f32_e32 v44, v44
	v_max_f32_e32 v40, 0xc1f00000, v40
	v_mul_f32_e32 v40, 0xbfb8aa3b, v40
	v_exp_f32_e32 v40, v40
	v_pk_mul_f32 v[38:39], v[38:39], v[42:43]
	v_add_f32_e32 v42, 1.0, v44
	v_rcp_f32_e32 v42, v42
	v_add_f32_e32 v40, 1.0, v40
	v_rcp_f32_e32 v43, v40
	v_pk_mov_b32 v[40:41], v[40:41], v[34:35] op_sel:[1,0]
	v_cvt_f32_f16_sdwa v34, v84 dst_sel:DWORD dst_unused:UNUSED_PAD src0_sel:WORD_1
	v_cvt_pk_f16_f32 v39, v38, v39
	v_pk_mul_f32 v[40:41], v[40:41], v[42:43]
	v_cvt_f32_f16_sdwa v43, v85 dst_sel:DWORD dst_unused:UNUSED_PAD src0_sel:WORD_1
	v_cvt_pk_f16_f32 v42, v40, v41
	v_cvt_f32_f16_e32 v40, v85
	v_max_f32_e32 v34, 0xc1f00000, v34
	v_mul_f32_e32 v34, 0xbfb8aa3b, v34
	v_exp_f32_e32 v34, v34
	v_max_f32_e32 v40, 0xc1f00000, v40
	v_mul_f32_e32 v40, 0xbfb8aa3b, v40
	v_exp_f32_e32 v41, v40
	v_add_f32_e32 v34, 1.0, v34
	v_rcp_f32_e32 v40, v34
	v_pack_b32_f16 v38, v45, v39
	v_add_f32_e32 v34, 1.0, v41
	v_rcp_f32_e32 v41, v34
	v_mov_b32_e32 v34, v35
	v_max_f32_e32 v35, 0xc1f00000, v43
	v_mul_f32_e32 v35, 0xbfb8aa3b, v35
	v_exp_f32_e32 v43, v35
	v_mov_b32_e32 v35, v36
	v_pk_mul_f32 v[34:35], v[34:35], v[40:41]
	v_cvt_f32_f16_e32 v36, v78
	v_cvt_pk_f16_f32 v34, v34, v35
	v_add_f32_e32 v35, 1.0, v43
	v_rcp_f32_e32 v35, v35
	v_alignbit_b32 v40, v34, v42, 16
	v_lshrrev_b32_e32 v41, 16, v34
	v_max_f32_e32 v34, 0xc1f00000, v36
	v_alignbit_b32 v39, v42, v39, 16
	v_fma_mixhi_f16 v41, v37, v35, 0
	v_mul_f32_e32 v34, 0xbfb8aa3b, v34
	v_cvt_f32_f16_sdwa v37, v78 dst_sel:DWORD dst_unused:UNUSED_PAD src0_sel:WORD_1
	v_exp_f32_e32 v36, v34
	global_store_dwordx4 v[50:51], v[38:41], off offset:256
	v_lshl_add_u64 v[34:35], v[192:193], 0, v[184:185]
	v_max_f32_e32 v37, 0xc1f00000, v37
	v_cvt_f32_f16_e32 v38, v79
	v_add_f32_e32 v36, 1.0, v36
	v_mul_f32_e32 v37, 0xbfb8aa3b, v37
	v_rcp_f32_e32 v36, v36
	v_max_f32_e32 v38, 0xc1f00000, v38
	v_exp_f32_e32 v37, v37
	v_mul_f32_e32 v38, 0xbfb8aa3b, v38
	v_exp_f32_e32 v38, v38
	v_fma_mixlo_f16 v39, v28, v36, 0
	v_add_f32_e32 v28, 1.0, v37
	v_rcp_f32_e32 v36, v28
	v_add_f32_e32 v28, 1.0, v38
	v_rcp_f32_e32 v37, v28
	v_cvt_f32_f16_sdwa v38, v79 dst_sel:DWORD dst_unused:UNUSED_PAD src0_sel:WORD_1
	v_mov_b32_e32 v28, v29
	v_mov_b32_e32 v29, v30
	v_cvt_f32_f16_e32 v30, v80
	v_pk_mul_f32 v[28:29], v[28:29], v[36:37]
	v_max_f32_e32 v36, 0xc1f00000, v38
	v_mul_f32_e32 v36, 0xbfb8aa3b, v36
	v_max_f32_e32 v30, 0xc1f00000, v30
	v_exp_f32_e32 v36, v36
	v_mul_f32_e32 v30, 0xbfb8aa3b, v30
	v_exp_f32_e32 v30, v30
	v_cvt_pk_f16_f32 v29, v28, v29
	v_add_f32_e32 v28, 1.0, v36
	v_rcp_f32_e32 v36, v28
	v_add_f32_e32 v28, 1.0, v30
	v_rcp_f32_e32 v37, v28
	v_pk_mov_b32 v[30:31], v[30:31], v[24:25] op_sel:[1,0]
	v_cvt_f32_f16_sdwa v24, v80 dst_sel:DWORD dst_unused:UNUSED_PAD src0_sel:WORD_1
	v_pack_b32_f16 v28, v39, v29
	v_pk_mul_f32 v[30:31], v[30:31], v[36:37]
	v_cvt_f32_f16_sdwa v37, v81 dst_sel:DWORD dst_unused:UNUSED_PAD src0_sel:WORD_1
	v_cvt_pk_f16_f32 v36, v30, v31
	v_cvt_f32_f16_e32 v30, v81
	v_max_f32_e32 v24, 0xc1f00000, v24
	v_mul_f32_e32 v24, 0xbfb8aa3b, v24
	v_exp_f32_e32 v24, v24
	v_max_f32_e32 v30, 0xc1f00000, v30
	v_mul_f32_e32 v30, 0xbfb8aa3b, v30
	v_exp_f32_e32 v31, v30
	v_add_f32_e32 v24, 1.0, v24
	v_rcp_f32_e32 v30, v24
	v_alignbit_b32 v29, v36, v29, 16
	v_add_f32_e32 v24, 1.0, v31
	v_rcp_f32_e32 v31, v24
	v_mov_b32_e32 v24, v25
	v_mov_b32_e32 v25, v26
	v_cvt_f32_f16_e32 v26, v74
	v_pk_mul_f32 v[24:25], v[24:25], v[30:31]
	global_store_dwordx4 v[50:51], v[46:49], off
	v_cvt_pk_f16_f32 v24, v24, v25
	v_max_f32_e32 v25, 0xc1f00000, v37
	v_mul_f32_e32 v25, 0xbfb8aa3b, v25
	v_exp_f32_e32 v25, v25
	v_alignbit_b32 v30, v24, v36, 16
	v_lshrrev_b32_e32 v31, 16, v24
	v_add_f32_e32 v24, 1.0, v25
	v_rcp_f32_e32 v24, v24
	v_max_f32_e32 v25, 0xc1f00000, v26
	v_mul_f32_e32 v25, 0xbfb8aa3b, v25
	v_exp_f32_e32 v25, v25
	v_fma_mixhi_f16 v31, v27, v24, 0
	v_cvt_f32_f16_sdwa v24, v74 dst_sel:DWORD dst_unused:UNUSED_PAD src0_sel:WORD_1
	v_cvt_f32_f16_e32 v26, v75
	v_add_f32_e32 v25, 1.0, v25
	v_rcp_f32_e32 v25, v25
	v_max_f32_e32 v24, 0xc1f00000, v24
	v_mul_f32_e32 v24, 0xbfb8aa3b, v24
	v_max_f32_e32 v26, 0xc1f00000, v26
	v_exp_f32_e32 v24, v24
	v_mul_f32_e32 v26, 0xbfb8aa3b, v26
	v_exp_f32_e32 v26, v26
	v_fma_mixlo_f16 v27, v20, v25, 0
	v_add_f32_e32 v20, 1.0, v24
	v_rcp_f32_e32 v24, v20
	v_add_f32_e32 v20, 1.0, v26
	v_rcp_f32_e32 v25, v20
	v_cvt_f32_f16_sdwa v26, v75 dst_sel:DWORD dst_unused:UNUSED_PAD src0_sel:WORD_1
	v_mov_b32_e32 v20, v21
	v_mov_b32_e32 v21, v22
	v_cvt_f32_f16_e32 v22, v76
	v_max_f32_e32 v26, 0xc1f00000, v26
	v_mul_f32_e32 v26, 0xbfb8aa3b, v26
	v_exp_f32_e32 v26, v26
	v_max_f32_e32 v22, 0xc1f00000, v22
	v_mul_f32_e32 v22, 0xbfb8aa3b, v22
	v_exp_f32_e32 v22, v22
	v_pk_mul_f32 v[20:21], v[20:21], v[24:25]
	v_add_f32_e32 v24, 1.0, v26
	v_rcp_f32_e32 v24, v24
	v_add_f32_e32 v22, 1.0, v22
	v_rcp_f32_e32 v25, v22
	v_pk_mov_b32 v[22:23], v[22:23], v[16:17] op_sel:[1,0]
	v_cvt_f32_f16_sdwa v16, v76 dst_sel:DWORD dst_unused:UNUSED_PAD src0_sel:WORD_1
	v_cvt_pk_f16_f32 v21, v20, v21
	v_pk_mul_f32 v[22:23], v[22:23], v[24:25]
	v_cvt_f32_f16_sdwa v25, v77 dst_sel:DWORD dst_unused:UNUSED_PAD src0_sel:WORD_1
	v_cvt_pk_f16_f32 v24, v22, v23
	v_cvt_f32_f16_e32 v22, v77
	v_max_f32_e32 v16, 0xc1f00000, v16
	v_mul_f32_e32 v16, 0xbfb8aa3b, v16
	v_exp_f32_e32 v16, v16
	v_max_f32_e32 v22, 0xc1f00000, v22
	v_mul_f32_e32 v22, 0xbfb8aa3b, v22
	v_exp_f32_e32 v23, v22
	v_add_f32_e32 v16, 1.0, v16
	v_rcp_f32_e32 v22, v16
	v_pack_b32_f16 v20, v27, v21
	v_add_f32_e32 v16, 1.0, v23
	v_rcp_f32_e32 v23, v16
	v_mov_b32_e32 v16, v17
	v_max_f32_e32 v17, 0xc1f00000, v25
	v_mul_f32_e32 v17, 0xbfb8aa3b, v17
	v_exp_f32_e32 v25, v17
	v_mov_b32_e32 v17, v18
	v_pk_mul_f32 v[16:17], v[16:17], v[22:23]
	v_cvt_f32_f16_e32 v18, v70
	v_cvt_pk_f16_f32 v16, v16, v17
	v_add_f32_e32 v17, 1.0, v25
	v_rcp_f32_e32 v17, v17
	v_alignbit_b32 v22, v16, v24, 16
	v_lshrrev_b32_e32 v23, 16, v16
	v_max_f32_e32 v16, 0xc1f00000, v18
	v_alignbit_b32 v21, v24, v21, 16
	v_fma_mixhi_f16 v23, v19, v17, 0
	v_mul_f32_e32 v16, 0xbfb8aa3b, v16
	v_cvt_f32_f16_sdwa v19, v70 dst_sel:DWORD dst_unused:UNUSED_PAD src0_sel:WORD_1
	v_exp_f32_e32 v18, v16
	global_store_dwordx4 v[34:35], v[20:23], off offset:256
	v_lshl_add_u64 v[16:17], v[192:193], 0, v[186:187]
	v_max_f32_e32 v19, 0xc1f00000, v19
	v_cvt_f32_f16_e32 v20, v71
	v_add_f32_e32 v18, 1.0, v18
	v_mul_f32_e32 v19, 0xbfb8aa3b, v19
	v_rcp_f32_e32 v18, v18
	v_max_f32_e32 v20, 0xc1f00000, v20
	v_exp_f32_e32 v19, v19
	v_mul_f32_e32 v20, 0xbfb8aa3b, v20
	v_exp_f32_e32 v20, v20
	v_fma_mixlo_f16 v21, v12, v18, 0
	v_add_f32_e32 v12, 1.0, v19
	v_rcp_f32_e32 v18, v12
	v_add_f32_e32 v12, 1.0, v20
	v_rcp_f32_e32 v19, v12
	v_cvt_f32_f16_sdwa v20, v71 dst_sel:DWORD dst_unused:UNUSED_PAD src0_sel:WORD_1
	v_mov_b32_e32 v12, v13
	v_mov_b32_e32 v13, v14
	v_cvt_f32_f16_e32 v14, v72
	v_pk_mul_f32 v[12:13], v[12:13], v[18:19]
	v_max_f32_e32 v18, 0xc1f00000, v20
	v_mul_f32_e32 v18, 0xbfb8aa3b, v18
	v_max_f32_e32 v14, 0xc1f00000, v14
	v_exp_f32_e32 v18, v18
	v_mul_f32_e32 v14, 0xbfb8aa3b, v14
	v_exp_f32_e32 v14, v14
	v_cvt_pk_f16_f32 v13, v12, v13
	v_add_f32_e32 v12, 1.0, v18
	v_rcp_f32_e32 v18, v12
	v_add_f32_e32 v12, 1.0, v14
	v_rcp_f32_e32 v19, v12
	v_pk_mov_b32 v[14:15], v[14:15], v[8:9] op_sel:[1,0]
	v_cvt_f32_f16_sdwa v8, v72 dst_sel:DWORD dst_unused:UNUSED_PAD src0_sel:WORD_1
	v_pack_b32_f16 v12, v21, v13
	v_pk_mul_f32 v[14:15], v[14:15], v[18:19]
	v_cvt_f32_f16_sdwa v19, v73 dst_sel:DWORD dst_unused:UNUSED_PAD src0_sel:WORD_1
	v_cvt_pk_f16_f32 v18, v14, v15
	v_cvt_f32_f16_e32 v14, v73
	v_max_f32_e32 v8, 0xc1f00000, v8
	v_mul_f32_e32 v8, 0xbfb8aa3b, v8
	v_exp_f32_e32 v8, v8
	v_max_f32_e32 v14, 0xc1f00000, v14
	v_mul_f32_e32 v14, 0xbfb8aa3b, v14
	v_exp_f32_e32 v15, v14
	v_add_f32_e32 v8, 1.0, v8
	v_rcp_f32_e32 v14, v8
	v_alignbit_b32 v13, v18, v13, 16
	v_add_f32_e32 v8, 1.0, v15
	v_rcp_f32_e32 v15, v8
	v_mov_b32_e32 v8, v9
	v_mov_b32_e32 v9, v10
	v_cvt_f32_f16_e32 v10, v66
	v_pk_mul_f32 v[8:9], v[8:9], v[14:15]
	global_store_dwordx4 v[34:35], v[28:31], off
	v_cvt_pk_f16_f32 v8, v8, v9
	v_max_f32_e32 v9, 0xc1f00000, v19
	v_mul_f32_e32 v9, 0xbfb8aa3b, v9
	v_exp_f32_e32 v9, v9
	v_alignbit_b32 v14, v8, v18, 16
	v_lshrrev_b32_e32 v15, 16, v8
	v_add_f32_e32 v8, 1.0, v9
	v_rcp_f32_e32 v8, v8
	v_max_f32_e32 v9, 0xc1f00000, v10
	v_mul_f32_e32 v9, 0xbfb8aa3b, v9
	v_exp_f32_e32 v9, v9
	v_fma_mixhi_f16 v15, v11, v8, 0
	v_cvt_f32_f16_sdwa v8, v66 dst_sel:DWORD dst_unused:UNUSED_PAD src0_sel:WORD_1
	v_cvt_f32_f16_e32 v10, v67
	v_add_f32_e32 v9, 1.0, v9
	v_rcp_f32_e32 v9, v9
	v_max_f32_e32 v8, 0xc1f00000, v8
	v_mul_f32_e32 v8, 0xbfb8aa3b, v8
	v_max_f32_e32 v10, 0xc1f00000, v10
	v_exp_f32_e32 v8, v8
	v_mul_f32_e32 v10, 0xbfb8aa3b, v10
	v_exp_f32_e32 v10, v10
	v_fma_mixlo_f16 v11, v4, v9, 0
	v_add_f32_e32 v4, 1.0, v8
	v_rcp_f32_e32 v8, v4
	v_add_f32_e32 v4, 1.0, v10
	v_rcp_f32_e32 v9, v4
	v_cvt_f32_f16_sdwa v10, v67 dst_sel:DWORD dst_unused:UNUSED_PAD src0_sel:WORD_1
	v_mov_b32_e32 v4, v5
	v_mov_b32_e32 v5, v6
	v_cvt_f32_f16_e32 v6, v68
	v_max_f32_e32 v10, 0xc1f00000, v10
	v_mul_f32_e32 v10, 0xbfb8aa3b, v10
	v_exp_f32_e32 v10, v10
	v_max_f32_e32 v6, 0xc1f00000, v6
	v_mul_f32_e32 v6, 0xbfb8aa3b, v6
	v_exp_f32_e32 v6, v6
	v_pk_mul_f32 v[4:5], v[4:5], v[8:9]
	v_add_f32_e32 v8, 1.0, v10
	v_rcp_f32_e32 v8, v8
	v_add_f32_e32 v6, 1.0, v6
	v_rcp_f32_e32 v9, v6
	v_pk_mov_b32 v[6:7], v[6:7], v[0:1] op_sel:[1,0]
	v_cvt_f32_f16_sdwa v0, v68 dst_sel:DWORD dst_unused:UNUSED_PAD src0_sel:WORD_1
	v_cvt_pk_f16_f32 v5, v4, v5
	v_pk_mul_f32 v[6:7], v[6:7], v[8:9]
	v_cvt_f32_f16_sdwa v9, v69 dst_sel:DWORD dst_unused:UNUSED_PAD src0_sel:WORD_1
	v_cvt_pk_f16_f32 v8, v6, v7
	v_cvt_f32_f16_e32 v6, v69
	v_max_f32_e32 v0, 0xc1f00000, v0
	v_mul_f32_e32 v0, 0xbfb8aa3b, v0
	v_exp_f32_e32 v0, v0
	v_max_f32_e32 v6, 0xc1f00000, v6
	v_mul_f32_e32 v6, 0xbfb8aa3b, v6
	v_exp_f32_e32 v7, v6
	v_add_f32_e32 v0, 1.0, v0
	v_rcp_f32_e32 v6, v0
	v_pack_b32_f16 v4, v11, v5
	v_add_f32_e32 v0, 1.0, v7
	v_rcp_f32_e32 v7, v0
	v_max_f32_e32 v0, 0xc1f00000, v9
	v_mul_f32_e32 v0, 0xbfb8aa3b, v0
	v_exp_f32_e32 v9, v0
	v_mov_b32_e32 v0, v1
	v_mov_b32_e32 v1, v2
	v_pk_mul_f32 v[0:1], v[0:1], v[6:7]
	v_add_f32_e32 v2, 1.0, v9
	v_rcp_f32_e32 v2, v2
	v_cvt_pk_f16_f32 v0, v0, v1
	v_lshrrev_b32_e32 v7, 16, v0
	v_alignbit_b32 v5, v8, v5, 16
	v_alignbit_b32 v6, v0, v8, 16
	v_fma_mixhi_f16 v7, v3, v2, 0
	global_store_dwordx4 v[16:17], v[12:15], off
	global_store_dwordx4 v[16:17], v[4:7], off offset:256
	s_and_b64 vcc, exec, s[4:5]
	s_mov_b32 s31, s30
	s_mov_b32 s34, s29
	s_mov_b64 s[12:13], s[0:1]
	s_mov_b64 s[10:11], s[2:3]
	s_cbranch_vccz .LBB0_955
	s_waitcnt vmcnt(0)
	s_cmpk_gt_u32 s19, 0xff
	s_cbranch_scc1 .LBB0_962
	s_barrier

.LBB0_1116:
	s_add_i32 s38, s37, -2
	s_add_u32 s39, s20, 0x100
	s_addc_u32 s40, s21, 0
	s_mov_b32 s22, 0
	s_add_i32 s41, s22, 2
	s_add_u32 s20, s14, 0x100
	s_addc_u32 s21, s15, 0
	s_add_i32 s42, 0, 0x10000
	s_waitcnt vmcnt(0)
	v_add_u32_e32 v102, s42, v230
	ds_read_b128 v[78:81], v102
	ds_read_b128 v[94:97], v102 offset:2048
	ds_read_b128 v[86:89], v102 offset:1024
	ds_read_b128 v[102:105], v102 offset:3072
	s_cmp_eq_u32 s38, s22
	s_cselect_b32 s22, s18, s39
	s_cselect_b32 s25, s17, s21
	s_cselect_b32 s24, s16, s20
	s_cselect_b32 s23, s19, s40
	v_lshl_add_u64 v[178:179], s[14:15], 0, v[200:201]
	s_add_i32 m0, s28, 0xc000
	ds_read_b128 v[122:125], v232
	ds_read_b128 v[130:133], v232 offset:2048
	ds_read_b128 v[154:157], v232 offset:4096
	ds_read_b128 v[170:173], v232 offset:6144
	ds_read_b128 v[126:129], v232 offset:1024
	ds_read_b128 v[134:137], v232 offset:3072
	ds_read_b128 v[158:161], v232 offset:5120
	ds_read_b128 v[174:177], v232 offset:7168
	global_load_lds_dwordx4 v[178:179], off
	v_lshl_add_u64 v[178:179], s[14:15], 0, v[202:203]
	s_add_i32 m0, s28, 0xe000
	s_nop 0
	global_load_lds_dwordx4 v[178:179], off
	s_waitcnt lgkmcnt(8)
	s_barrier
	s_waitcnt lgkmcnt(7)
	s_setprio 1
	v_mfma_f32_16x16x32_f16 v[166:169], v[78:81], v[122:125], 0
	v_mfma_f32_16x16x32_f16 v[162:165], v[94:97], v[122:125], 0
	s_waitcnt lgkmcnt(6)
	v_mfma_f32_16x16x32_f16 v[150:153], v[78:81], v[130:133], 0
	v_mfma_f32_16x16x32_f16 v[142:145], v[94:97], v[130:133], 0
	s_waitcnt lgkmcnt(5)
	v_mfma_f32_16x16x32_f16 v[110:113], v[78:81], v[154:157], 0
	v_mfma_f32_16x16x32_f16 v[106:109], v[94:97], v[154:157], 0
	s_waitcnt lgkmcnt(4)
	v_mfma_f32_16x16x32_f16 v[82:85], v[78:81], v[170:173], 0
	v_mfma_f32_16x16x32_f16 v[74:77], v[94:97], v[170:173], 0
	s_waitcnt lgkmcnt(3)
	v_mfma_f32_16x16x32_f16 v[166:169], v[86:89], v[126:129], v[166:169]
	v_mfma_f32_16x16x32_f16 v[162:165], v[102:105], v[126:129], v[162:165]
	s_waitcnt lgkmcnt(2)
	v_mfma_f32_16x16x32_f16 v[150:153], v[86:89], v[134:137], v[150:153]
	v_mfma_f32_16x16x32_f16 v[142:145], v[102:105], v[134:137], v[142:145]
	s_waitcnt lgkmcnt(1)
	v_mfma_f32_16x16x32_f16 v[110:113], v[86:89], v[158:161], v[110:113]
	v_mfma_f32_16x16x32_f16 v[106:109], v[102:105], v[158:161], v[106:109]
	s_waitcnt lgkmcnt(0)
	v_mfma_f32_16x16x32_f16 v[82:85], v[86:89], v[174:177], v[82:85]
	v_mfma_f32_16x16x32_f16 v[74:77], v[102:105], v[174:177], v[74:77]
	s_setprio 0
	s_barrier
	s_add_i32 s43, 0, 0x14000
	s_add_i32 s14, s42, s13
	v_add_u32_e32 v190, s43, v230
	v_lshl_add_u64 v[204:205], s[22:23], 0, v[32:33]
	s_mov_b32 m0, s14
	ds_read_b128 v[178:181], v190
	ds_read_b128 v[186:189], v190 offset:2048
	ds_read_b128 v[182:185], v190 offset:1024
	ds_read_b128 v[190:193], v190 offset:3072
	global_load_lds_dwordx4 v[204:205], off
	v_lshl_add_u64 v[206:207], s[22:23], 0, v[198:199]
	s_add_i32 m0, s14, 0x2000
	s_nop 0
	global_load_lds_dwordx4 v[206:207], off
	s_barrier
	s_waitcnt lgkmcnt(3)
	s_setprio 1
	v_mfma_f32_16x16x32_f16 v[146:149], v[178:181], v[122:125], 0
	v_mfma_f32_16x16x32_f16 v[118:121], v[178:181], v[130:133], 0
	s_waitcnt lgkmcnt(2)
	v_mfma_f32_16x16x32_f16 v[114:117], v[186:189], v[130:133], 0
	v_mfma_f32_16x16x32_f16 v[98:101], v[178:181], v[154:157], 0
	v_mfma_f32_16x16x32_f16 v[90:93], v[186:189], v[154:157], 0
	v_mfma_f32_16x16x32_f16 v[70:73], v[178:181], v[170:173], 0
	s_waitcnt lgkmcnt(1)
	v_mfma_f32_16x16x32_f16 v[66:69], v[186:189], v[170:173], 0
	v_mfma_f32_16x16x32_f16 v[146:149], v[182:185], v[126:129], v[146:149]
	v_mfma_f32_16x16x32_f16 v[122:125], v[186:189], v[122:125], 0
	v_mfma_f32_16x16x32_f16 v[118:121], v[182:185], v[134:137], v[118:121]
	s_waitcnt lgkmcnt(0)
	v_mfma_f32_16x16x32_f16 v[114:117], v[190:193], v[134:137], v[114:117]
	v_mfma_f32_16x16x32_f16 v[98:101], v[182:185], v[158:161], v[98:101]
	v_mfma_f32_16x16x32_f16 v[90:93], v[190:193], v[158:161], v[90:93]
	v_mfma_f32_16x16x32_f16 v[70:73], v[182:185], v[174:177], v[70:73]
	v_mfma_f32_16x16x32_f16 v[66:69], v[190:193], v[174:177], v[66:69]
	v_mfma_f32_16x16x32_f16 v[122:125], v[190:193], v[126:129], v[122:125]
	s_setprio 0
	s_mov_b32 m0, s28
	v_lshl_add_u64 v[208:209], s[24:25], 0, v[32:33]
	s_barrier
	ds_read_b128 v[126:129], v232 offset:16384
	ds_read_b128 v[134:137], v232 offset:18432
	ds_read_b128 v[154:157], v232 offset:20480
	ds_read_b128 v[170:173], v232 offset:22528
	ds_read_b128 v[130:133], v232 offset:17408
	ds_read_b128 v[138:141], v232 offset:19456
	ds_read_b128 v[158:161], v232 offset:21504
	ds_read_b128 v[174:177], v232 offset:23552
	global_load_lds_dwordx4 v[208:209], off
	v_lshl_add_u64 v[210:211], s[24:25], 0, v[198:199]
	s_mov_b32 m0, s29
	s_nop 0
	global_load_lds_dwordx4 v[210:211], off
	s_barrier
	s_waitcnt lgkmcnt(7)
	s_setprio 1
	v_mfma_f32_16x16x32_f16 v[62:65], v[78:81], v[126:129], 0
	v_mfma_f32_16x16x32_f16 v[58:61], v[94:97], v[126:129], 0
	s_waitcnt lgkmcnt(6)
	v_mfma_f32_16x16x32_f16 v[46:49], v[78:81], v[134:137], 0
	v_mfma_f32_16x16x32_f16 v[42:45], v[94:97], v[134:137], 0
	s_waitcnt lgkmcnt(5)
	v_mfma_f32_16x16x32_f16 v[28:31], v[78:81], v[154:157], 0
	v_mfma_f32_16x16x32_f16 v[24:27], v[94:97], v[154:157], 0
	s_waitcnt lgkmcnt(4)
	v_mfma_f32_16x16x32_f16 v[12:15], v[78:81], v[170:173], 0
	v_mfma_f32_16x16x32_f16 v[8:11], v[94:97], v[170:173], 0
	s_waitcnt lgkmcnt(3)
	v_mfma_f32_16x16x32_f16 v[62:65], v[86:89], v[130:133], v[62:65]
	v_mfma_f32_16x16x32_f16 v[58:61], v[102:105], v[130:133], v[58:61]
	s_waitcnt lgkmcnt(2)
	v_mfma_f32_16x16x32_f16 v[46:49], v[86:89], v[138:141], v[46:49]
	v_mfma_f32_16x16x32_f16 v[42:45], v[102:105], v[138:141], v[42:45]
	s_waitcnt lgkmcnt(1)
	v_mfma_f32_16x16x32_f16 v[28:31], v[86:89], v[158:161], v[28:31]
	v_mfma_f32_16x16x32_f16 v[24:27], v[102:105], v[158:161], v[24:27]
	s_waitcnt lgkmcnt(0)
	v_mfma_f32_16x16x32_f16 v[12:15], v[86:89], v[174:177], v[12:15]
	v_mfma_f32_16x16x32_f16 v[8:11], v[102:105], v[174:177], v[8:11]
	s_setprio 0
	s_barrier
	s_add_u32 s14, s22, 0x40000
	s_addc_u32 s15, s23, 0
	s_add_i32 s42, s43, s13
	v_lshl_add_u64 v[78:79], s[14:15], 0, v[32:33]
	s_mov_b32 m0, s42
	s_nop 0
	global_load_lds_dwordx4 v[78:79], off
	v_lshl_add_u64 v[78:79], s[14:15], 0, v[198:199]
	s_add_i32 m0, s42, 0x2000
	s_nop 0
	global_load_lds_dwordx4 v[78:79], off
	s_waitcnt vmcnt(6)
	s_barrier
	s_setprio 1
	v_mfma_f32_16x16x32_f16 v[54:57], v[178:181], v[126:129], 0
	v_mfma_f32_16x16x32_f16 v[50:53], v[186:189], v[126:129], 0
	v_mfma_f32_16x16x32_f16 v[38:41], v[178:181], v[134:137], 0
	v_mfma_f32_16x16x32_f16 v[34:37], v[186:189], v[134:137], 0
	v_mfma_f32_16x16x32_f16 v[20:23], v[178:181], v[154:157], 0
	v_mfma_f32_16x16x32_f16 v[16:19], v[186:189], v[154:157], 0
	v_mfma_f32_16x16x32_f16 v[4:7], v[178:181], v[170:173], 0
	v_mfma_f32_16x16x32_f16 v[0:3], v[186:189], v[170:173], 0
	v_mfma_f32_16x16x32_f16 v[54:57], v[182:185], v[130:133], v[54:57]
	v_mfma_f32_16x16x32_f16 v[50:53], v[190:193], v[130:133], v[50:53]
	v_mfma_f32_16x16x32_f16 v[38:41], v[182:185], v[138:141], v[38:41]
	v_mfma_f32_16x16x32_f16 v[34:37], v[190:193], v[138:141], v[34:37]
	v_mfma_f32_16x16x32_f16 v[20:23], v[182:185], v[158:161], v[20:23]
	v_mfma_f32_16x16x32_f16 v[16:19], v[190:193], v[158:161], v[16:19]
	v_mfma_f32_16x16x32_f16 v[4:7], v[182:185], v[174:177], v[4:7]
	v_mfma_f32_16x16x32_f16 v[0:3], v[190:193], v[174:177], v[0:3]
	s_setprio 0
	s_add_i32 s42, 0, 0x18000
	v_add_u32_e32 v102, s42, v230
	s_barrier
	ds_read_b128 v[78:81], v102
	ds_read_b128 v[86:89], v102 offset:1024
	ds_read_b128 v[94:97], v102 offset:2048
	ds_read_b128 v[102:105], v102 offset:3072
	s_add_u32 s14, s24, 0x40000
	s_addc_u32 s15, s25, 0
	s_mov_b32 m0, s30
	v_lshl_add_u64 v[138:139], s[14:15], 0, v[32:33]
	ds_read_b128 v[126:129], v232 offset:32768
	ds_read_b128 v[130:133], v232 offset:33792
	ds_read_b128 v[134:137], v232 offset:34816
	ds_read_b128 v[154:157], v232 offset:35840
	ds_read_b128 v[158:161], v232 offset:36864
	ds_read_b128 v[174:177], v232 offset:38912
	ds_read_b128 v[170:173], v232 offset:37888
	ds_read_b128 v[178:181], v232 offset:39936
	global_load_lds_dwordx4 v[138:139], off
	v_lshl_add_u64 v[138:139], s[14:15], 0, v[198:199]
	s_mov_b32 m0, s31
	s_nop 0
	global_load_lds_dwordx4 v[138:139], off
	s_waitcnt lgkmcnt(8)
	s_barrier
	s_waitcnt lgkmcnt(6)
	s_setprio 1
	v_mfma_f32_16x16x32_f16 v[138:141], v[78:81], v[126:129], v[166:169]
	v_mfma_f32_16x16x32_f16 v[166:169], v[86:89], v[130:133], v[138:141]
	v_mfma_f32_16x16x32_f16 v[138:141], v[94:97], v[126:129], v[162:165]
	v_mfma_f32_16x16x32_f16 v[162:165], v[102:105], v[130:133], v[138:141]
	s_waitcnt lgkmcnt(4)
	v_mfma_f32_16x16x32_f16 v[138:141], v[78:81], v[134:137], v[150:153]
	v_mfma_f32_16x16x32_f16 v[150:153], v[86:89], v[154:157], v[138:141]
	s_waitcnt lgkmcnt(3)
	v_mfma_f32_16x16x32_f16 v[138:141], v[94:97], v[134:137], v[142:145]
	v_mfma_f32_16x16x32_f16 v[110:113], v[78:81], v[158:161], v[110:113]
	s_waitcnt lgkmcnt(2)
	v_mfma_f32_16x16x32_f16 v[106:109], v[94:97], v[158:161], v[106:109]
	v_mfma_f32_16x16x32_f16 v[82:85], v[78:81], v[174:177], v[82:85]
	v_mfma_f32_16x16x32_f16 v[74:77], v[94:97], v[174:177], v[74:77]
	v_mfma_f32_16x16x32_f16 v[142:145], v[102:105], v[154:157], v[138:141]
	s_waitcnt lgkmcnt(1)
	v_mfma_f32_16x16x32_f16 v[110:113], v[86:89], v[170:173], v[110:113]
	v_mfma_f32_16x16x32_f16 v[106:109], v[102:105], v[170:173], v[106:109]
	s_waitcnt lgkmcnt(0)
	v_mfma_f32_16x16x32_f16 v[82:85], v[86:89], v[178:181], v[82:85]
	v_mfma_f32_16x16x32_f16 v[74:77], v[102:105], v[178:181], v[74:77]
	s_setprio 0
	s_barrier
	s_add_i32 s24, 0, 0x1c000
	v_add_u32_e32 v138, s24, v230
	s_add_i32 s14, s42, s13
	ds_read_b128 v[182:185], v138
	ds_read_b128 v[190:193], v138 offset:2048
	ds_read_b128 v[186:189], v138 offset:1024
	ds_read_b128 v[194:197], v138 offset:3072
	v_lshl_add_u64 v[138:139], v[204:205], 0, s[84:85]
	s_mov_b32 m0, s14
	s_nop 0
	global_load_lds_dwordx4 v[138:139], off
	v_lshl_add_u64 v[138:139], v[206:207], 0, s[84:85]
	s_add_i32 m0, s14, 0x2000
	s_nop 0
	global_load_lds_dwordx4 v[138:139], off
	s_barrier
	s_waitcnt lgkmcnt(2)
	s_setprio 1
	v_mfma_f32_16x16x32_f16 v[138:141], v[182:185], v[126:129], v[146:149]
	v_mfma_f32_16x16x32_f16 v[122:125], v[190:193], v[126:129], v[122:125]
	v_mfma_f32_16x16x32_f16 v[118:121], v[182:185], v[134:137], v[118:121]
	v_mfma_f32_16x16x32_f16 v[114:117], v[190:193], v[134:137], v[114:117]
	v_mfma_f32_16x16x32_f16 v[98:101], v[182:185], v[158:161], v[98:101]
	v_mfma_f32_16x16x32_f16 v[90:93], v[190:193], v[158:161], v[90:93]
	v_mfma_f32_16x16x32_f16 v[70:73], v[182:185], v[174:177], v[70:73]
	v_mfma_f32_16x16x32_f16 v[66:69], v[190:193], v[174:177], v[66:69]
	s_waitcnt lgkmcnt(0)
	v_mfma_f32_16x16x32_f16 v[146:149], v[186:189], v[130:133], v[138:141]
	v_mfma_f32_16x16x32_f16 v[138:141], v[194:197], v[130:133], v[122:125]
	v_mfma_f32_16x16x32_f16 v[118:121], v[186:189], v[154:157], v[118:121]
	v_mfma_f32_16x16x32_f16 v[114:117], v[194:197], v[154:157], v[114:117]
	v_mfma_f32_16x16x32_f16 v[98:101], v[186:189], v[170:173], v[98:101]
	v_mfma_f32_16x16x32_f16 v[90:93], v[194:197], v[170:173], v[90:93]
	v_mfma_f32_16x16x32_f16 v[70:73], v[186:189], v[178:181], v[70:73]
	v_mfma_f32_16x16x32_f16 v[66:69], v[194:197], v[178:181], v[66:69]
	s_setprio 0
	s_mov_b32 m0, s34
	v_lshl_add_u64 v[178:179], v[208:209], 0, s[84:85]
	s_barrier
	ds_read_b128 v[122:125], v232 offset:49152
	ds_read_b128 v[130:133], v232 offset:51200
	ds_read_b128 v[154:157], v232 offset:53248
	ds_read_b128 v[170:173], v232 offset:55296
	ds_read_b128 v[126:129], v232 offset:50176
	ds_read_b128 v[134:137], v232 offset:52224
	ds_read_b128 v[158:161], v232 offset:54272
	ds_read_b128 v[174:177], v232 offset:56320
	global_load_lds_dwordx4 v[178:179], off
	v_lshl_add_u64 v[178:179], v[210:211], 0, s[84:85]
	s_mov_b32 m0, s35
	s_nop 0
	global_load_lds_dwordx4 v[178:179], off
	s_barrier
	s_waitcnt lgkmcnt(7)
	s_setprio 1
	v_mfma_f32_16x16x32_f16 v[62:65], v[78:81], v[122:125], v[62:65]
	v_mfma_f32_16x16x32_f16 v[58:61], v[94:97], v[122:125], v[58:61]
	s_waitcnt lgkmcnt(6)
	v_mfma_f32_16x16x32_f16 v[46:49], v[78:81], v[130:133], v[46:49]
	v_mfma_f32_16x16x32_f16 v[42:45], v[94:97], v[130:133], v[42:45]
	s_waitcnt lgkmcnt(5)
	v_mfma_f32_16x16x32_f16 v[28:31], v[78:81], v[154:157], v[28:31]
	v_mfma_f32_16x16x32_f16 v[24:27], v[94:97], v[154:157], v[24:27]
	s_waitcnt lgkmcnt(4)
	v_mfma_f32_16x16x32_f16 v[12:15], v[78:81], v[170:173], v[12:15]
	v_mfma_f32_16x16x32_f16 v[8:11], v[94:97], v[170:173], v[8:11]
	s_waitcnt lgkmcnt(3)
	v_mfma_f32_16x16x32_f16 v[62:65], v[86:89], v[126:129], v[62:65]
	v_mfma_f32_16x16x32_f16 v[58:61], v[102:105], v[126:129], v[58:61]
	s_waitcnt lgkmcnt(2)
	v_mfma_f32_16x16x32_f16 v[46:49], v[86:89], v[134:137], v[46:49]
	v_mfma_f32_16x16x32_f16 v[42:45], v[102:105], v[134:137], v[42:45]
	s_waitcnt lgkmcnt(1)
	v_mfma_f32_16x16x32_f16 v[28:31], v[86:89], v[158:161], v[28:31]
	v_mfma_f32_16x16x32_f16 v[24:27], v[102:105], v[158:161], v[24:27]
	s_waitcnt lgkmcnt(0)
	v_mfma_f32_16x16x32_f16 v[12:15], v[86:89], v[174:177], v[12:15]
	v_mfma_f32_16x16x32_f16 v[8:11], v[102:105], v[174:177], v[8:11]
	s_setprio 0
	s_barrier
	s_add_u32 s14, s22, 0x40080
	s_addc_u32 s15, s23, 0
	s_add_i32 s22, s24, s13
	v_lshl_add_u64 v[78:79], s[14:15], 0, v[32:33]
	s_mov_b32 m0, s22
	s_nop 0
	global_load_lds_dwordx4 v[78:79], off
	v_lshl_add_u64 v[78:79], s[14:15], 0, v[198:199]
	s_add_i32 m0, s22, 0x2000
	s_nop 0
	global_load_lds_dwordx4 v[78:79], off
	s_waitcnt vmcnt(6)
	s_barrier
	s_setprio 1
	v_mfma_f32_16x16x32_f16 v[54:57], v[182:185], v[122:125], v[54:57]
	v_mfma_f32_16x16x32_f16 v[50:53], v[190:193], v[122:125], v[50:53]
	v_mfma_f32_16x16x32_f16 v[38:41], v[182:185], v[130:133], v[38:41]
	v_mfma_f32_16x16x32_f16 v[34:37], v[190:193], v[130:133], v[34:37]
	v_mfma_f32_16x16x32_f16 v[20:23], v[182:185], v[154:157], v[20:23]
	v_mfma_f32_16x16x32_f16 v[16:19], v[190:193], v[154:157], v[16:19]
	v_mfma_f32_16x16x32_f16 v[4:7], v[182:185], v[170:173], v[4:7]
	v_mfma_f32_16x16x32_f16 v[0:3], v[190:193], v[170:173], v[0:3]
	v_mfma_f32_16x16x32_f16 v[54:57], v[186:189], v[126:129], v[54:57]
	v_mfma_f32_16x16x32_f16 v[50:53], v[194:197], v[126:129], v[50:53]
	v_mfma_f32_16x16x32_f16 v[38:41], v[186:189], v[134:137], v[38:41]
	v_mfma_f32_16x16x32_f16 v[34:37], v[194:197], v[134:137], v[34:37]
	v_mfma_f32_16x16x32_f16 v[20:23], v[186:189], v[158:161], v[20:23]
	v_mfma_f32_16x16x32_f16 v[16:19], v[194:197], v[158:161], v[16:19]
	v_mfma_f32_16x16x32_f16 v[4:7], v[186:189], v[174:177], v[4:7]
	v_mfma_f32_16x16x32_f16 v[0:3], v[194:197], v[174:177], v[0:3]
	s_setprio 0
	s_add_u32 s39, s39, 0x100
	s_addc_u32 s40, s40, 0
	s_cmp_ge_u32 s41, s37
	s_mov_b64 s[14:15], s[20:21]
	s_mov_b32 s22, s41
	s_barrier
	s_cbranch_scc0 .LBB0_1117
	s_branch .Lpeelx3

.Lpeelx3:
	v_lshl_or_b32 v124, s12, 8, v231
	s_cmp_eq_u32 s10, 0
	s_movk_i32 s12, 0x5000
	s_cselect_b32 s12, 0xe000, s12
	v_readlane_b32 s14, v252, 51
	s_add_u32 s14, s14, s12
	v_readlane_b32 s12, v252, 52
	s_addc_u32 s15, s12, 0
	v_ashrrev_i32_e32 v125, 31, v124
	v_lshl_add_u64 v[86:87], v[124:125], 2, s[14:15]
	global_load_dwordx4 v[94:97], v[86:87], off offset:16
	global_load_dwordx4 v[102:105], v[86:87], off
	global_load_dwordx4 v[78:81], v[86:87], off offset:528
	s_nop 0
	global_load_dwordx4 v[86:89], v[86:87], off offset:512
	v_lshl_add_u32 v130, s10, 8, v229
	v_or_b32_e32 v128, 16, v130
	v_or_b32_e32 v126, 32, v130
	v_or_b32_e32 v122, 48, v130
	s_cmp_eq_u32 s11, 0
	v_ashrrev_i32_e32 v131, 31, v130
	v_ashrrev_i32_e32 v129, 31, v128
	v_ashrrev_i32_e32 v127, 31, v126
	v_ashrrev_i32_e32 v123, 31, v122
	s_cbranch_scc1 .LBB0_1120
	s_add_i32 s96, s11, -1
	s_lshl_b64 s[10:11], s[96:97], 20
	v_readlane_b32 s14, v252, 11
	v_readlane_b32 s15, v252, 12
	s_add_u32 s10, s14, s10
	s_addc_u32 s11, s15, s11
	v_lshlrev_b64 v[132:133], 2, v[124:125]
	v_lshrrev_b32_e32 v134, 5, v220
	v_mul_u32_u24_e32 v134, 48, v134
	s_nop 0
	v_sub_co_u32_e32 v132, vcc, v132, v134
	s_nop 1
	v_subbrev_co_u32_e32 v133, vcc, 0, v133, vcc
	v_lshl_add_u64 v[132:133], s[10:11], 0, v[132:133]
	s_mov_b64 s[10:11], 0x80000
	v_lshlrev_b64 v[204:205], 12, v[130:131]
	v_lshl_add_u64 v[204:205], v[204:205], 0, v[132:133]
	v_lshl_add_u64 v[212:213], v[204:205], 0, s[10:11]
	v_lshlrev_b64 v[206:207], 12, v[128:129]
	v_lshl_add_u64 v[206:207], v[206:207], 0, v[132:133]
	v_lshl_add_u64 v[214:215], v[206:207], 0, s[10:11]
	v_lshlrev_b64 v[208:209], 12, v[126:127]
	v_lshl_add_u64 v[208:209], v[208:209], 0, v[132:133]
	v_lshl_add_u64 v[216:217], v[208:209], 0, s[10:11]
	v_lshlrev_b64 v[210:211], 12, v[122:123]
	v_lshl_add_u64 v[210:211], v[210:211], 0, v[132:133]
	v_lshl_add_u64 v[218:219], v[210:211], 0, s[10:11]
	s_waitcnt vmcnt(0)
	v_pk_mul_f32 v[172:173], v[166:167], v[102:103]
	v_pk_mul_f32 v[174:175], v[168:169], v[104:105]
	v_pk_mul_f32 v[176:177], v[162:163], v[94:95]
	v_pk_mul_f32 v[178:179], v[164:165], v[96:97]
	s_nop 1
	v_permlane32_swap_b32_e32 v172, v176
	v_permlane32_swap_b32_e32 v173, v177
	v_permlane32_swap_b32_e32 v174, v178
	v_permlane32_swap_b32_e32 v175, v179
	s_nop 0
	global_store_dwordx4 v[204:205], v[172:175], off
	global_store_dwordx4 v[204:205], v[176:179], off offset:64
	v_pk_mul_f32 v[180:181], v[146:147], v[86:87]
	v_pk_mul_f32 v[182:183], v[148:149], v[88:89]
	v_pk_mul_f32 v[184:185], v[138:139], v[78:79]
	v_pk_mul_f32 v[186:187], v[140:141], v[80:81]
	s_nop 1
	v_permlane32_swap_b32_e32 v180, v184
	v_permlane32_swap_b32_e32 v181, v185
	v_permlane32_swap_b32_e32 v182, v186
	v_permlane32_swap_b32_e32 v183, v187
	s_nop 0
	global_store_dwordx4 v[204:205], v[180:183], off offset:512
	global_store_dwordx4 v[204:205], v[184:187], off offset:576
	v_pk_mul_f32 v[188:189], v[150:151], v[102:103]
	v_pk_mul_f32 v[190:191], v[152:153], v[104:105]
	v_pk_mul_f32 v[192:193], v[142:143], v[94:95]
	v_pk_mul_f32 v[194:195], v[144:145], v[96:97]
	s_nop 1
	v_permlane32_swap_b32_e32 v188, v192
	v_permlane32_swap_b32_e32 v189, v193
	v_permlane32_swap_b32_e32 v190, v194
	v_permlane32_swap_b32_e32 v191, v195
	s_nop 0
	global_store_dwordx4 v[206:207], v[188:191], off
	global_store_dwordx4 v[206:207], v[192:195], off offset:64
	v_pk_mul_f32 v[154:155], v[118:119], v[86:87]
	v_pk_mul_f32 v[156:157], v[120:121], v[88:89]
	v_pk_mul_f32 v[158:159], v[114:115], v[78:79]
	v_pk_mul_f32 v[160:161], v[116:117], v[80:81]
	s_nop 1
	v_permlane32_swap_b32_e32 v154, v158
	v_permlane32_swap_b32_e32 v155, v159
	v_permlane32_swap_b32_e32 v156, v160
	v_permlane32_swap_b32_e32 v157, v161
	s_nop 0
	global_store_dwordx4 v[206:207], v[154:157], off offset:512
	global_store_dwordx4 v[206:207], v[158:161], off offset:576
	v_pk_mul_f32 v[172:173], v[110:111], v[102:103]
	v_pk_mul_f32 v[174:175], v[112:113], v[104:105]
	v_pk_mul_f32 v[176:177], v[106:107], v[94:95]
	v_pk_mul_f32 v[178:179], v[108:109], v[96:97]
	s_nop 1
	v_permlane32_swap_b32_e32 v172, v176
	v_permlane32_swap_b32_e32 v173, v177
	v_permlane32_swap_b32_e32 v174, v178
	v_permlane32_swap_b32_e32 v175, v179
	s_nop 0
	global_store_dwordx4 v[208:209], v[172:175], off
	global_store_dwordx4 v[208:209], v[176:179], off offset:64
	v_pk_mul_f32 v[180:181], v[98:99], v[86:87]
	v_pk_mul_f32 v[182:183], v[100:101], v[88:89]
	v_pk_mul_f32 v[184:185], v[90:91], v[78:79]
	v_pk_mul_f32 v[186:187], v[92:93], v[80:81]
	s_nop 1
	v_permlane32_swap_b32_e32 v180, v184
	v_permlane32_swap_b32_e32 v181, v185
	v_permlane32_swap_b32_e32 v182, v186
	v_permlane32_swap_b32_e32 v183, v187
	s_nop 0
	global_store_dwordx4 v[208:209], v[180:183], off offset:512
	global_store_dwordx4 v[208:209], v[184:187], off offset:576
	v_pk_mul_f32 v[188:189], v[82:83], v[102:103]
	v_pk_mul_f32 v[190:191], v[84:85], v[104:105]
	v_pk_mul_f32 v[192:193], v[74:75], v[94:95]
	v_pk_mul_f32 v[194:195], v[76:77], v[96:97]
	s_nop 1
	v_permlane32_swap_b32_e32 v188, v192
	v_permlane32_swap_b32_e32 v189, v193
	v_permlane32_swap_b32_e32 v190, v194
	v_permlane32_swap_b32_e32 v191, v195
	s_nop 0
	global_store_dwordx4 v[210:211], v[188:191], off
	global_store_dwordx4 v[210:211], v[192:195], off offset:64
	v_pk_mul_f32 v[154:155], v[70:71], v[86:87]
	v_pk_mul_f32 v[156:157], v[72:73], v[88:89]
	v_pk_mul_f32 v[158:159], v[66:67], v[78:79]
	v_pk_mul_f32 v[160:161], v[68:69], v[80:81]
	s_nop 1
	v_permlane32_swap_b32_e32 v154, v158
	v_permlane32_swap_b32_e32 v155, v159
	v_permlane32_swap_b32_e32 v156, v160
	v_permlane32_swap_b32_e32 v157, v161
	s_nop 0
	global_store_dwordx4 v[210:211], v[154:157], off offset:512
	global_store_dwordx4 v[210:211], v[158:161], off offset:576
	v_pk_mul_f32 v[172:173], v[62:63], v[102:103]
	v_pk_mul_f32 v[174:175], v[64:65], v[104:105]
	v_pk_mul_f32 v[176:177], v[58:59], v[94:95]
	v_pk_mul_f32 v[178:179], v[60:61], v[96:97]
	s_nop 1
	v_permlane32_swap_b32_e32 v172, v176
	v_permlane32_swap_b32_e32 v173, v177
	v_permlane32_swap_b32_e32 v174, v178
	v_permlane32_swap_b32_e32 v175, v179
	s_nop 0
	global_store_dwordx4 v[212:213], v[172:175], off
	global_store_dwordx4 v[212:213], v[176:179], off offset:64
	v_pk_mul_f32 v[180:181], v[54:55], v[86:87]
	v_pk_mul_f32 v[182:183], v[56:57], v[88:89]
	v_pk_mul_f32 v[184:185], v[50:51], v[78:79]
	v_pk_mul_f32 v[186:187], v[52:53], v[80:81]
	s_nop 1
	v_permlane32_swap_b32_e32 v180, v184
	v_permlane32_swap_b32_e32 v181, v185
	v_permlane32_swap_b32_e32 v182, v186
	v_permlane32_swap_b32_e32 v183, v187
	s_nop 0
	global_store_dwordx4 v[212:213], v[180:183], off offset:512
	global_store_dwordx4 v[212:213], v[184:187], off offset:576
	v_pk_mul_f32 v[188:189], v[46:47], v[102:103]
	v_pk_mul_f32 v[190:191], v[48:49], v[104:105]
	v_pk_mul_f32 v[192:193], v[42:43], v[94:95]
	v_pk_mul_f32 v[194:195], v[44:45], v[96:97]
	s_nop 1
	v_permlane32_swap_b32_e32 v188, v192
	v_permlane32_swap_b32_e32 v189, v193
	v_permlane32_swap_b32_e32 v190, v194
	v_permlane32_swap_b32_e32 v191, v195
	s_nop 0
	global_store_dwordx4 v[214:215], v[188:191], off
	global_store_dwordx4 v[214:215], v[192:195], off offset:64
	v_pk_mul_f32 v[154:155], v[38:39], v[86:87]
	v_pk_mul_f32 v[156:157], v[40:41], v[88:89]
	v_pk_mul_f32 v[158:159], v[34:35], v[78:79]
	v_pk_mul_f32 v[160:161], v[36:37], v[80:81]
	s_nop 1
	v_permlane32_swap_b32_e32 v154, v158
	v_permlane32_swap_b32_e32 v155, v159
	v_permlane32_swap_b32_e32 v156, v160
	v_permlane32_swap_b32_e32 v157, v161
	s_nop 0
	global_store_dwordx4 v[214:215], v[154:157], off offset:512
	global_store_dwordx4 v[214:215], v[158:161], off offset:576
	v_pk_mul_f32 v[172:173], v[28:29], v[102:103]
	v_pk_mul_f32 v[174:175], v[30:31], v[104:105]
	v_pk_mul_f32 v[176:177], v[24:25], v[94:95]
	v_pk_mul_f32 v[178:179], v[26:27], v[96:97]
	s_nop 1
	v_permlane32_swap_b32_e32 v172, v176
	v_permlane32_swap_b32_e32 v173, v177
	v_permlane32_swap_b32_e32 v174, v178
	v_permlane32_swap_b32_e32 v175, v179
	s_nop 0
	global_store_dwordx4 v[216:217], v[172:175], off
	global_store_dwordx4 v[216:217], v[176:179], off offset:64
	v_pk_mul_f32 v[180:181], v[20:21], v[86:87]
	v_pk_mul_f32 v[182:183], v[22:23], v[88:89]
	v_pk_mul_f32 v[184:185], v[16:17], v[78:79]
	v_pk_mul_f32 v[186:187], v[18:19], v[80:81]
	s_nop 1
	v_permlane32_swap_b32_e32 v180, v184
	v_permlane32_swap_b32_e32 v181, v185
	v_permlane32_swap_b32_e32 v182, v186
	v_permlane32_swap_b32_e32 v183, v187
	s_nop 0
	global_store_dwordx4 v[216:217], v[180:183], off offset:512
	global_store_dwordx4 v[216:217], v[184:187], off offset:576
	v_pk_mul_f32 v[188:189], v[12:13], v[102:103]
	v_pk_mul_f32 v[190:191], v[14:15], v[104:105]
	v_pk_mul_f32 v[192:193], v[8:9], v[94:95]
	v_pk_mul_f32 v[194:195], v[10:11], v[96:97]
	s_nop 1
	v_permlane32_swap_b32_e32 v188, v192
	v_permlane32_swap_b32_e32 v189, v193
	v_permlane32_swap_b32_e32 v190, v194
	v_permlane32_swap_b32_e32 v191, v195
	s_nop 0
	global_store_dwordx4 v[218:219], v[188:191], off
	global_store_dwordx4 v[218:219], v[192:195], off offset:64
	v_pk_mul_f32 v[154:155], v[4:5], v[86:87]
	v_pk_mul_f32 v[156:157], v[6:7], v[88:89]
	v_pk_mul_f32 v[158:159], v[0:1], v[78:79]
	v_pk_mul_f32 v[160:161], v[2:3], v[80:81]
	s_nop 1
	v_permlane32_swap_b32_e32 v154, v158
	v_permlane32_swap_b32_e32 v155, v159
	v_permlane32_swap_b32_e32 v156, v160
	v_permlane32_swap_b32_e32 v157, v161
	s_nop 0
	global_store_dwordx4 v[218:219], v[154:157], off offset:512
	global_store_dwordx4 v[218:219], v[158:161], off offset:576
	s_cbranch_execnz .LBB0_1104
	s_branch .LBB0_1103

.LBB0_1275:
	s_add_u32 s3, s16, 0x100
	s_addc_u32 s37, s17, 0
	s_mov_b32 s38, -2
	s_add_u32 s16, s14, 0x100
	s_addc_u32 s17, s15, 0
	s_add_i32 s39, 0, 0x10000
	v_add_u32_e32 v152, s39, v137
	ds_read_b128 v[140:143], v152
	ds_read_b128 v[148:151], v152 offset:2048
	ds_read_b128 v[144:147], v152 offset:1024
	ds_read_b128 v[152:155], v152 offset:3072
	s_cmp_eq_u32 s38, 12
	s_cselect_b32 s21, s11, s17
	s_cselect_b32 s20, s10, s16
	s_cselect_b32 s19, s13, s37
	s_cselect_b32 s18, s12, s3
	v_lshl_add_u64 v[188:189], s[14:15], 0, v[132:133]
	s_add_i32 m0, s9, 0xc000
	ds_read_b128 v[156:159], v139
	ds_read_b128 v[164:167], v139 offset:2048
	ds_read_b128 v[172:175], v139 offset:4096
	ds_read_b128 v[180:183], v139 offset:6144
	ds_read_b128 v[160:163], v139 offset:1024
	ds_read_b128 v[168:171], v139 offset:3072
	ds_read_b128 v[176:179], v139 offset:5120
	ds_read_b128 v[184:187], v139 offset:7168
	global_load_lds_dwordx4 v[188:189], off
	v_lshl_add_u64 v[188:189], s[14:15], 0, v[134:135]
	s_add_i32 m0, s9, 0xe000
	s_nop 0
	global_load_lds_dwordx4 v[188:189], off
	s_waitcnt lgkmcnt(8)
	s_barrier
	s_waitcnt lgkmcnt(7)
	s_setprio 1
	v_mfma_f32_16x16x32_f16 v[126:129], v[140:143], v[156:159], 0
	v_mfma_f32_16x16x32_f16 v[122:125], v[148:151], v[156:159], 0
	s_waitcnt lgkmcnt(6)
	v_mfma_f32_16x16x32_f16 v[110:113], v[140:143], v[164:167], 0
	v_mfma_f32_16x16x32_f16 v[106:109], v[148:151], v[164:167], 0
	s_waitcnt lgkmcnt(5)
	v_mfma_f32_16x16x32_f16 v[94:97], v[140:143], v[172:175], 0
	v_mfma_f32_16x16x32_f16 v[90:93], v[148:151], v[172:175], 0
	s_waitcnt lgkmcnt(4)
	v_mfma_f32_16x16x32_f16 v[78:81], v[140:143], v[180:183], 0
	v_mfma_f32_16x16x32_f16 v[74:77], v[148:151], v[180:183], 0
	s_waitcnt lgkmcnt(3)
	v_mfma_f32_16x16x32_f16 v[126:129], v[144:147], v[160:163], v[126:129]
	v_mfma_f32_16x16x32_f16 v[122:125], v[152:155], v[160:163], v[122:125]
	s_waitcnt lgkmcnt(2)
	v_mfma_f32_16x16x32_f16 v[110:113], v[144:147], v[168:171], v[110:113]
	v_mfma_f32_16x16x32_f16 v[106:109], v[152:155], v[168:171], v[106:109]
	s_waitcnt lgkmcnt(1)
	v_mfma_f32_16x16x32_f16 v[94:97], v[144:147], v[176:179], v[94:97]
	v_mfma_f32_16x16x32_f16 v[90:93], v[152:155], v[176:179], v[90:93]
	s_waitcnt lgkmcnt(0)
	v_mfma_f32_16x16x32_f16 v[78:81], v[144:147], v[184:187], v[78:81]
	v_mfma_f32_16x16x32_f16 v[74:77], v[152:155], v[184:187], v[74:77]
	s_setprio 0
	s_barrier
	s_add_i32 s40, 0, 0x14000
	s_add_i32 s14, s39, s26
	v_add_u32_e32 v200, s40, v137
	v_lshl_add_u64 v[204:205], s[18:19], 0, v[32:33]
	s_mov_b32 m0, s14
	ds_read_b128 v[188:191], v200
	ds_read_b128 v[196:199], v200 offset:2048
	ds_read_b128 v[192:195], v200 offset:1024
	ds_read_b128 v[200:203], v200 offset:3072
	global_load_lds_dwordx4 v[204:205], off
	v_lshl_add_u64 v[206:207], s[18:19], 0, v[130:131]
	s_add_i32 m0, s14, 0x2000
	s_nop 0
	global_load_lds_dwordx4 v[206:207], off
	s_barrier
	s_waitcnt lgkmcnt(2)
	s_setprio 1
	v_mfma_f32_16x16x32_f16 v[118:121], v[188:191], v[156:159], 0
	v_mfma_f32_16x16x32_f16 v[114:117], v[196:199], v[156:159], 0
	v_mfma_f32_16x16x32_f16 v[102:105], v[188:191], v[164:167], 0
	v_mfma_f32_16x16x32_f16 v[98:101], v[196:199], v[164:167], 0
	v_mfma_f32_16x16x32_f16 v[86:89], v[188:191], v[172:175], 0
	v_mfma_f32_16x16x32_f16 v[82:85], v[196:199], v[172:175], 0
	v_mfma_f32_16x16x32_f16 v[70:73], v[188:191], v[180:183], 0
	v_mfma_f32_16x16x32_f16 v[66:69], v[196:199], v[180:183], 0
	s_waitcnt lgkmcnt(0)
	v_mfma_f32_16x16x32_f16 v[118:121], v[192:195], v[160:163], v[118:121]
	v_mfma_f32_16x16x32_f16 v[114:117], v[200:203], v[160:163], v[114:117]
	v_mfma_f32_16x16x32_f16 v[102:105], v[192:195], v[168:171], v[102:105]
	v_mfma_f32_16x16x32_f16 v[98:101], v[200:203], v[168:171], v[98:101]
	v_mfma_f32_16x16x32_f16 v[86:89], v[192:195], v[176:179], v[86:89]
	v_mfma_f32_16x16x32_f16 v[82:85], v[200:203], v[176:179], v[82:85]
	v_mfma_f32_16x16x32_f16 v[70:73], v[192:195], v[184:187], v[70:73]
	v_mfma_f32_16x16x32_f16 v[66:69], v[200:203], v[184:187], v[66:69]
	s_setprio 0
	s_mov_b32 m0, s9
	v_lshl_add_u64 v[208:209], s[20:21], 0, v[32:33]
	s_barrier
	ds_read_b128 v[156:159], v139 offset:16384
	ds_read_b128 v[164:167], v139 offset:18432
	ds_read_b128 v[172:175], v139 offset:20480
	ds_read_b128 v[180:183], v139 offset:22528
	ds_read_b128 v[160:163], v139 offset:17408
	ds_read_b128 v[168:171], v139 offset:19456
	ds_read_b128 v[176:179], v139 offset:21504
	ds_read_b128 v[184:187], v139 offset:23552
	global_load_lds_dwordx4 v[208:209], off
	v_lshl_add_u64 v[210:211], s[20:21], 0, v[130:131]
	s_mov_b32 m0, s27
	s_nop 0
	global_load_lds_dwordx4 v[210:211], off
	s_barrier
	s_waitcnt lgkmcnt(7)
	s_setprio 1
	v_mfma_f32_16x16x32_f16 v[62:65], v[140:143], v[156:159], 0
	v_mfma_f32_16x16x32_f16 v[58:61], v[148:151], v[156:159], 0
	s_waitcnt lgkmcnt(6)
	v_mfma_f32_16x16x32_f16 v[46:49], v[140:143], v[164:167], 0
	v_mfma_f32_16x16x32_f16 v[42:45], v[148:151], v[164:167], 0
	s_waitcnt lgkmcnt(5)
	v_mfma_f32_16x16x32_f16 v[28:31], v[140:143], v[172:175], 0
	v_mfma_f32_16x16x32_f16 v[24:27], v[148:151], v[172:175], 0
	s_waitcnt lgkmcnt(4)
	v_mfma_f32_16x16x32_f16 v[12:15], v[140:143], v[180:183], 0
	v_mfma_f32_16x16x32_f16 v[8:11], v[148:151], v[180:183], 0
	s_waitcnt lgkmcnt(3)
	v_mfma_f32_16x16x32_f16 v[62:65], v[144:147], v[160:163], v[62:65]
	v_mfma_f32_16x16x32_f16 v[58:61], v[152:155], v[160:163], v[58:61]
	s_waitcnt lgkmcnt(2)
	v_mfma_f32_16x16x32_f16 v[46:49], v[144:147], v[168:171], v[46:49]
	v_mfma_f32_16x16x32_f16 v[42:45], v[152:155], v[168:171], v[42:45]
	s_waitcnt lgkmcnt(1)
	v_mfma_f32_16x16x32_f16 v[28:31], v[144:147], v[176:179], v[28:31]
	v_mfma_f32_16x16x32_f16 v[24:27], v[152:155], v[176:179], v[24:27]
	s_waitcnt lgkmcnt(0)
	v_mfma_f32_16x16x32_f16 v[12:15], v[144:147], v[184:187], v[12:15]
	v_mfma_f32_16x16x32_f16 v[8:11], v[152:155], v[184:187], v[8:11]
	s_setprio 0
	s_barrier
	s_add_u32 s14, s18, 0x40000
	s_addc_u32 s15, s19, 0
	s_add_i32 s39, s40, s26
	v_lshl_add_u64 v[140:141], s[14:15], 0, v[32:33]
	s_mov_b32 m0, s39
	s_nop 0
	global_load_lds_dwordx4 v[140:141], off
	v_lshl_add_u64 v[140:141], s[14:15], 0, v[130:131]
	s_add_i32 m0, s39, 0x2000
	s_nop 0
	global_load_lds_dwordx4 v[140:141], off
	s_waitcnt vmcnt(6)
	s_barrier
	s_setprio 1
	v_mfma_f32_16x16x32_f16 v[54:57], v[188:191], v[156:159], 0
	v_mfma_f32_16x16x32_f16 v[50:53], v[196:199], v[156:159], 0
	v_mfma_f32_16x16x32_f16 v[38:41], v[188:191], v[164:167], 0
	v_mfma_f32_16x16x32_f16 v[34:37], v[196:199], v[164:167], 0
	v_mfma_f32_16x16x32_f16 v[20:23], v[188:191], v[172:175], 0
	v_mfma_f32_16x16x32_f16 v[16:19], v[196:199], v[172:175], 0
	v_mfma_f32_16x16x32_f16 v[4:7], v[188:191], v[180:183], 0
	v_mfma_f32_16x16x32_f16 v[0:3], v[196:199], v[180:183], 0
	v_mfma_f32_16x16x32_f16 v[54:57], v[192:195], v[160:163], v[54:57]
	v_mfma_f32_16x16x32_f16 v[50:53], v[200:203], v[160:163], v[50:53]
	v_mfma_f32_16x16x32_f16 v[38:41], v[192:195], v[168:171], v[38:41]
	v_mfma_f32_16x16x32_f16 v[34:37], v[200:203], v[168:171], v[34:37]
	v_mfma_f32_16x16x32_f16 v[20:23], v[192:195], v[176:179], v[20:23]
	v_mfma_f32_16x16x32_f16 v[16:19], v[200:203], v[176:179], v[16:19]
	v_mfma_f32_16x16x32_f16 v[4:7], v[192:195], v[184:187], v[4:7]
	v_mfma_f32_16x16x32_f16 v[0:3], v[200:203], v[184:187], v[0:3]
	s_setprio 0
	s_add_i32 s39, 0, 0x18000
	v_add_u32_e32 v152, s39, v137
	s_barrier
	ds_read_b128 v[140:143], v152
	ds_read_b128 v[148:151], v152 offset:2048
	ds_read_b128 v[144:147], v152 offset:1024
	ds_read_b128 v[152:155], v152 offset:3072
	s_add_u32 s14, s20, 0x40000
	s_addc_u32 s15, s21, 0
	s_mov_b32 m0, s28
	v_lshl_add_u64 v[188:189], s[14:15], 0, v[32:33]
	ds_read_b128 v[156:159], v139 offset:32768
	ds_read_b128 v[164:167], v139 offset:34816
	ds_read_b128 v[172:175], v139 offset:36864
	ds_read_b128 v[180:183], v139 offset:38912
	ds_read_b128 v[160:163], v139 offset:33792
	ds_read_b128 v[168:171], v139 offset:35840
	ds_read_b128 v[176:179], v139 offset:37888
	ds_read_b128 v[184:187], v139 offset:39936
	global_load_lds_dwordx4 v[188:189], off
	v_lshl_add_u64 v[188:189], s[14:15], 0, v[130:131]
	s_mov_b32 m0, s29
	s_nop 0
	global_load_lds_dwordx4 v[188:189], off
	s_waitcnt lgkmcnt(8)
	s_barrier
	s_waitcnt lgkmcnt(7)
	s_setprio 1
	v_mfma_f32_16x16x32_f16 v[126:129], v[140:143], v[156:159], v[126:129]
	v_mfma_f32_16x16x32_f16 v[122:125], v[148:151], v[156:159], v[122:125]
	s_waitcnt lgkmcnt(6)
	v_mfma_f32_16x16x32_f16 v[110:113], v[140:143], v[164:167], v[110:113]
	v_mfma_f32_16x16x32_f16 v[106:109], v[148:151], v[164:167], v[106:109]
	s_waitcnt lgkmcnt(5)
	v_mfma_f32_16x16x32_f16 v[94:97], v[140:143], v[172:175], v[94:97]
	v_mfma_f32_16x16x32_f16 v[90:93], v[148:151], v[172:175], v[90:93]
	s_waitcnt lgkmcnt(4)
	v_mfma_f32_16x16x32_f16 v[78:81], v[140:143], v[180:183], v[78:81]
	v_mfma_f32_16x16x32_f16 v[74:77], v[148:151], v[180:183], v[74:77]
	s_waitcnt lgkmcnt(3)
	v_mfma_f32_16x16x32_f16 v[126:129], v[144:147], v[160:163], v[126:129]
	v_mfma_f32_16x16x32_f16 v[122:125], v[152:155], v[160:163], v[122:125]
	s_waitcnt lgkmcnt(2)
	v_mfma_f32_16x16x32_f16 v[110:113], v[144:147], v[168:171], v[110:113]
	v_mfma_f32_16x16x32_f16 v[106:109], v[152:155], v[168:171], v[106:109]
	s_waitcnt lgkmcnt(1)
	v_mfma_f32_16x16x32_f16 v[94:97], v[144:147], v[176:179], v[94:97]
	v_mfma_f32_16x16x32_f16 v[90:93], v[152:155], v[176:179], v[90:93]
	s_waitcnt lgkmcnt(0)
	v_mfma_f32_16x16x32_f16 v[78:81], v[144:147], v[184:187], v[78:81]
	v_mfma_f32_16x16x32_f16 v[74:77], v[152:155], v[184:187], v[74:77]
	s_setprio 0
	s_barrier
	s_add_i32 s20, 0, 0x1c000
	s_add_i32 s14, s39, s26
	v_add_u32_e32 v200, s20, v137
	v_lshl_add_u64 v[204:205], v[204:205], 0, s[84:85]
	s_mov_b32 m0, s14
	ds_read_b128 v[188:191], v200
	ds_read_b128 v[196:199], v200 offset:2048
	ds_read_b128 v[192:195], v200 offset:1024
	ds_read_b128 v[200:203], v200 offset:3072
	global_load_lds_dwordx4 v[204:205], off
	v_lshl_add_u64 v[204:205], v[206:207], 0, s[84:85]
	s_add_i32 m0, s14, 0x2000
	s_nop 0
	global_load_lds_dwordx4 v[204:205], off
	s_barrier
	s_waitcnt lgkmcnt(2)
	s_setprio 1
	v_mfma_f32_16x16x32_f16 v[118:121], v[188:191], v[156:159], v[118:121]
	v_mfma_f32_16x16x32_f16 v[114:117], v[196:199], v[156:159], v[114:117]
	v_mfma_f32_16x16x32_f16 v[102:105], v[188:191], v[164:167], v[102:105]
	v_mfma_f32_16x16x32_f16 v[98:101], v[196:199], v[164:167], v[98:101]
	v_mfma_f32_16x16x32_f16 v[86:89], v[188:191], v[172:175], v[86:89]
	v_mfma_f32_16x16x32_f16 v[82:85], v[196:199], v[172:175], v[82:85]
	v_mfma_f32_16x16x32_f16 v[70:73], v[188:191], v[180:183], v[70:73]
	v_mfma_f32_16x16x32_f16 v[66:69], v[196:199], v[180:183], v[66:69]
	s_waitcnt lgkmcnt(0)
	v_mfma_f32_16x16x32_f16 v[118:121], v[192:195], v[160:163], v[118:121]
	v_mfma_f32_16x16x32_f16 v[114:117], v[200:203], v[160:163], v[114:117]
	v_mfma_f32_16x16x32_f16 v[102:105], v[192:195], v[168:171], v[102:105]
	v_mfma_f32_16x16x32_f16 v[98:101], v[200:203], v[168:171], v[98:101]
	v_mfma_f32_16x16x32_f16 v[86:89], v[192:195], v[176:179], v[86:89]
	v_mfma_f32_16x16x32_f16 v[82:85], v[200:203], v[176:179], v[82:85]
	v_mfma_f32_16x16x32_f16 v[70:73], v[192:195], v[184:187], v[70:73]
	v_mfma_f32_16x16x32_f16 v[66:69], v[200:203], v[184:187], v[66:69]
	s_setprio 0
	s_mov_b32 m0, s30
	v_lshl_add_u64 v[204:205], v[208:209], 0, s[84:85]
	s_barrier
	ds_read_b128 v[156:159], v139 offset:49152
	ds_read_b128 v[164:167], v139 offset:51200
	ds_read_b128 v[172:175], v139 offset:53248
	ds_read_b128 v[180:183], v139 offset:55296
	ds_read_b128 v[160:163], v139 offset:50176
	ds_read_b128 v[168:171], v139 offset:52224
	ds_read_b128 v[176:179], v139 offset:54272
	ds_read_b128 v[184:187], v139 offset:56320
	global_load_lds_dwordx4 v[204:205], off
	v_lshl_add_u64 v[204:205], v[210:211], 0, s[84:85]
	s_mov_b32 m0, s31
	s_nop 0
	global_load_lds_dwordx4 v[204:205], off
	s_barrier
	s_waitcnt lgkmcnt(7)
	s_setprio 1
	v_mfma_f32_16x16x32_f16 v[62:65], v[140:143], v[156:159], v[62:65]
	v_mfma_f32_16x16x32_f16 v[58:61], v[148:151], v[156:159], v[58:61]
	s_waitcnt lgkmcnt(6)
	v_mfma_f32_16x16x32_f16 v[46:49], v[140:143], v[164:167], v[46:49]
	v_mfma_f32_16x16x32_f16 v[42:45], v[148:151], v[164:167], v[42:45]
	s_waitcnt lgkmcnt(5)
	v_mfma_f32_16x16x32_f16 v[28:31], v[140:143], v[172:175], v[28:31]
	v_mfma_f32_16x16x32_f16 v[24:27], v[148:151], v[172:175], v[24:27]
	s_waitcnt lgkmcnt(4)
	v_mfma_f32_16x16x32_f16 v[12:15], v[140:143], v[180:183], v[12:15]
	v_mfma_f32_16x16x32_f16 v[8:11], v[148:151], v[180:183], v[8:11]
	s_waitcnt lgkmcnt(3)
	v_mfma_f32_16x16x32_f16 v[62:65], v[144:147], v[160:163], v[62:65]
	v_mfma_f32_16x16x32_f16 v[58:61], v[152:155], v[160:163], v[58:61]
	s_waitcnt lgkmcnt(2)
	v_mfma_f32_16x16x32_f16 v[46:49], v[144:147], v[168:171], v[46:49]
	v_mfma_f32_16x16x32_f16 v[42:45], v[152:155], v[168:171], v[42:45]
	s_waitcnt lgkmcnt(1)
	v_mfma_f32_16x16x32_f16 v[28:31], v[144:147], v[176:179], v[28:31]
	v_mfma_f32_16x16x32_f16 v[24:27], v[152:155], v[176:179], v[24:27]
	s_waitcnt lgkmcnt(0)
	v_mfma_f32_16x16x32_f16 v[12:15], v[144:147], v[184:187], v[12:15]
	v_mfma_f32_16x16x32_f16 v[8:11], v[152:155], v[184:187], v[8:11]
	s_setprio 0
	s_barrier
	s_add_u32 s14, s18, 0x40080
	s_addc_u32 s15, s19, 0
	s_add_i32 s18, s20, s26
	v_lshl_add_u64 v[140:141], s[14:15], 0, v[32:33]
	s_mov_b32 m0, s18
	s_nop 0
	global_load_lds_dwordx4 v[140:141], off
	v_lshl_add_u64 v[140:141], s[14:15], 0, v[130:131]
	s_add_i32 m0, s18, 0x2000
	s_nop 0
	global_load_lds_dwordx4 v[140:141], off
	s_waitcnt vmcnt(6)
	s_barrier
	s_setprio 1
	v_mfma_f32_16x16x32_f16 v[54:57], v[188:191], v[156:159], v[54:57]
	v_mfma_f32_16x16x32_f16 v[50:53], v[196:199], v[156:159], v[50:53]
	v_mfma_f32_16x16x32_f16 v[38:41], v[188:191], v[164:167], v[38:41]
	v_mfma_f32_16x16x32_f16 v[34:37], v[196:199], v[164:167], v[34:37]
	v_mfma_f32_16x16x32_f16 v[20:23], v[188:191], v[172:175], v[20:23]
	v_mfma_f32_16x16x32_f16 v[16:19], v[196:199], v[172:175], v[16:19]
	v_mfma_f32_16x16x32_f16 v[4:7], v[188:191], v[180:183], v[4:7]
	v_mfma_f32_16x16x32_f16 v[0:3], v[196:199], v[180:183], v[0:3]
	v_mfma_f32_16x16x32_f16 v[54:57], v[192:195], v[160:163], v[54:57]
	v_mfma_f32_16x16x32_f16 v[50:53], v[200:203], v[160:163], v[50:53]
	v_mfma_f32_16x16x32_f16 v[38:41], v[192:195], v[168:171], v[38:41]
	v_mfma_f32_16x16x32_f16 v[34:37], v[200:203], v[168:171], v[34:37]
	v_mfma_f32_16x16x32_f16 v[20:23], v[192:195], v[176:179], v[20:23]
	v_mfma_f32_16x16x32_f16 v[16:19], v[200:203], v[176:179], v[16:19]
	v_mfma_f32_16x16x32_f16 v[4:7], v[192:195], v[184:187], v[4:7]
	v_mfma_f32_16x16x32_f16 v[0:3], v[200:203], v[184:187], v[0:3]
	s_setprio 0
	s_add_i32 s38, s38, 2
	s_add_u32 s3, s3, 0x100
	s_addc_u32 s37, s37, 0
	s_cmp_gt_u32 s38, 13
	s_mov_b64 s[14:15], s[16:17]
	s_barrier
	s_cbranch_scc0 .LBB0_1276
	s_branch .Lpeelx4

.Lpeelx4:
	v_mul_f32_e32 v144, 0xbfb8aa3b, v127
	v_mul_f32_e32 v141, 0xbfb8aa3b, v126
	v_exp_f32_e32 v145, v144
	v_mul_f32_e32 v144, 0xbfb8aa3b, v128
	v_exp_f32_e32 v141, v141
	v_exp_f32_e32 v146, v144
	v_mul_f32_e32 v144, 0xbfb8aa3b, v129
	v_exp_f32_e32 v147, v144
	v_mul_f32_e32 v144, 0xbfb8aa3b, v122
	v_exp_f32_e32 v148, v144
	v_mul_f32_e32 v144, 0xbfb8aa3b, v123
	v_exp_f32_e32 v149, v144
	v_mul_f32_e32 v144, 0xbfb8aa3b, v124
	v_exp_f32_e32 v150, v144
	v_mul_f32_e32 v144, 0xbfb8aa3b, v125
	v_add_f32_e32 v141, 1.0, v141
	v_exp_f32_e32 v151, v144
	v_rcp_f32_e32 v144, v141
	v_add_f32_e32 v141, 1.0, v145
	v_rcp_f32_e32 v145, v141
	v_add_f32_e32 v141, 1.0, v146
	v_rcp_f32_e32 v146, v141
	v_add_f32_e32 v141, 1.0, v147
	v_rcp_f32_e32 v147, v141
	v_add_f32_e32 v141, 1.0, v148
	v_rcp_f32_e32 v148, v141
	v_add_f32_e32 v141, 1.0, v149
	v_rcp_f32_e32 v149, v141
	v_add_f32_e32 v141, 1.0, v150
	v_rcp_f32_e32 v150, v141
	v_add_f32_e32 v141, 1.0, v151
	v_pk_mul_f32 v[126:127], v[126:127], v[144:145]
	v_rcp_f32_e32 v151, v141
	v_pk_mul_f32 v[118:119], v[126:127], v[118:119]
	v_pk_mul_f32 v[126:127], v[128:129], v[146:147]
	v_cvt_pk_f16_f32 v118, v118, v119
	v_pk_mul_f32 v[120:121], v[126:127], v[120:121]
	v_lshl_or_b32 v142, s36, 7, v138
	v_cvt_pk_f16_f32 v119, v120, v121
	v_pk_mul_f32 v[120:121], v[122:123], v[148:149]
	v_lshl_add_u32 v140, s8, 8, v136
	v_pk_mul_f32 v[114:115], v[120:121], v[114:115]
	v_ashrrev_i32_e32 v143, 31, v142
	v_cvt_pk_f16_f32 v120, v114, v115
	v_pk_mul_f32 v[114:115], v[124:125], v[150:151]
	s_movk_i32 s3, 0x1600
	v_pk_mul_f32 v[114:115], v[114:115], v[116:117]
	v_lshlrev_b64 v[116:117], 1, v[142:143]
	v_cvt_pk_f16_f32 v121, v114, v115
	v_mov_b64_e32 v[114:115], s[92:93]
	v_mad_i64_i32 v[122:123], s[10:11], v140, s3, v[114:115]
	v_lshl_add_u64 v[122:123], v[122:123], 0, v[116:117]
	global_store_dwordx4 v[122:123], v[118:121], off
	v_mul_f32_e32 v122, 0xbfb8aa3b, v106
	v_mul_f32_e32 v123, 0xbfb8aa3b, v107
	v_mul_f32_e32 v118, 0xbfb8aa3b, v110
	v_mul_f32_e32 v119, 0xbfb8aa3b, v111
	v_exp_f32_e32 v118, v118
	v_exp_f32_e32 v119, v119
	v_mul_f32_e32 v120, 0xbfb8aa3b, v112
	v_mul_f32_e32 v121, 0xbfb8aa3b, v113
	v_exp_f32_e32 v120, v120
	v_exp_f32_e32 v121, v121
	v_exp_f32_e32 v122, v122
	v_exp_f32_e32 v123, v123
	v_mul_f32_e32 v124, 0xbfb8aa3b, v108
	v_mul_f32_e32 v125, 0xbfb8aa3b, v109
	v_add_f32_e32 v118, 1.0, v118
	v_add_f32_e32 v119, 1.0, v119
	v_exp_f32_e32 v124, v124
	v_exp_f32_e32 v125, v125
	v_rcp_f32_e32 v118, v118
	v_rcp_f32_e32 v119, v119
	v_add_f32_e32 v120, 1.0, v120
	v_add_f32_e32 v121, 1.0, v121
	v_rcp_f32_e32 v120, v120
	v_rcp_f32_e32 v121, v121
	v_add_f32_e32 v122, 1.0, v122
	v_add_f32_e32 v123, 1.0, v123
	v_rcp_f32_e32 v122, v122
	v_rcp_f32_e32 v123, v123
	v_add_f32_e32 v124, 1.0, v124
	v_add_f32_e32 v125, 1.0, v125
	v_pk_mul_f32 v[110:111], v[110:111], v[118:119]
	v_rcp_f32_e32 v124, v124
	v_rcp_f32_e32 v125, v125
	v_pk_mul_f32 v[102:103], v[110:111], v[102:103]
	v_pk_mul_f32 v[110:111], v[112:113], v[120:121]
	v_cvt_pk_f16_f32 v102, v102, v103
	v_pk_mul_f32 v[104:105], v[110:111], v[104:105]
	s_and_b64 vcc, exec, s[0:1]
	v_cvt_pk_f16_f32 v103, v104, v105
	v_pk_mul_f32 v[104:105], v[106:107], v[122:123]
	s_mov_b32 s36, s35
	v_pk_mul_f32 v[98:99], v[104:105], v[98:99]
	s_mov_b32 s8, s2
	v_cvt_pk_f16_f32 v104, v98, v99
	v_pk_mul_f32 v[98:99], v[108:109], v[124:125]
	s_mov_b64 s[16:17], s[6:7]
	v_pk_mul_f32 v[98:99], v[98:99], v[100:101]
	v_mul_f32_e32 v100, 0xbfb8aa3b, v96
	v_cvt_pk_f16_f32 v105, v98, v99
	v_or_b32_e32 v98, 16, v140
	v_mad_i64_i32 v[98:99], s[10:11], v98, s3, v[114:115]
	v_lshl_add_u64 v[98:99], v[98:99], 0, v[116:117]
	global_store_dwordx4 v[98:99], v[102:105], off
	v_mul_f32_e32 v98, 0xbfb8aa3b, v94
	v_mul_f32_e32 v99, 0xbfb8aa3b, v95
	v_exp_f32_e32 v98, v98
	v_exp_f32_e32 v99, v99
	v_mul_f32_e32 v101, 0xbfb8aa3b, v97
	v_exp_f32_e32 v100, v100
	v_exp_f32_e32 v101, v101
	v_mul_f32_e32 v102, 0xbfb8aa3b, v90
	v_mul_f32_e32 v103, 0xbfb8aa3b, v91
	v_exp_f32_e32 v102, v102
	v_exp_f32_e32 v103, v103
	v_mul_f32_e32 v104, 0xbfb8aa3b, v92
	v_mul_f32_e32 v105, 0xbfb8aa3b, v93
	v_add_f32_e32 v98, 1.0, v98
	v_add_f32_e32 v99, 1.0, v99
	v_exp_f32_e32 v104, v104
	v_exp_f32_e32 v105, v105
	v_rcp_f32_e32 v98, v98
	v_rcp_f32_e32 v99, v99
	v_add_f32_e32 v100, 1.0, v100
	v_add_f32_e32 v101, 1.0, v101
	v_rcp_f32_e32 v100, v100
	v_rcp_f32_e32 v101, v101
	v_add_f32_e32 v102, 1.0, v102
	v_add_f32_e32 v103, 1.0, v103
	v_rcp_f32_e32 v102, v102
	v_rcp_f32_e32 v103, v103
	v_add_f32_e32 v104, 1.0, v104
	v_add_f32_e32 v105, 1.0, v105
	v_pk_mul_f32 v[94:95], v[94:95], v[98:99]
	v_rcp_f32_e32 v104, v104
	v_rcp_f32_e32 v105, v105
	v_pk_mul_f32 v[86:87], v[94:95], v[86:87]
	v_pk_mul_f32 v[94:95], v[96:97], v[100:101]
	v_cvt_pk_f16_f32 v86, v86, v87
	v_pk_mul_f32 v[88:89], v[94:95], v[88:89]
	s_mov_b64 s[14:15], s[4:5]
	v_cvt_pk_f16_f32 v87, v88, v89
	v_pk_mul_f32 v[88:89], v[90:91], v[102:103]
	s_nop 0
	v_pk_mul_f32 v[82:83], v[88:89], v[82:83]
	s_nop 0
	v_cvt_pk_f16_f32 v88, v82, v83
	v_pk_mul_f32 v[82:83], v[92:93], v[104:105]
	s_nop 0
	v_pk_mul_f32 v[82:83], v[82:83], v[84:85]
	v_mul_f32_e32 v84, 0xbfb8aa3b, v80
	v_cvt_pk_f16_f32 v89, v82, v83
	v_or_b32_e32 v82, 32, v140
	v_mad_i64_i32 v[82:83], s[10:11], v82, s3, v[114:115]
	v_lshl_add_u64 v[82:83], v[82:83], 0, v[116:117]
	global_store_dwordx4 v[82:83], v[86:89], off
	v_mul_f32_e32 v82, 0xbfb8aa3b, v78
	v_mul_f32_e32 v83, 0xbfb8aa3b, v79
	v_exp_f32_e32 v82, v82
	v_exp_f32_e32 v83, v83
	v_mul_f32_e32 v85, 0xbfb8aa3b, v81
	v_exp_f32_e32 v84, v84
	v_exp_f32_e32 v85, v85
	v_mul_f32_e32 v86, 0xbfb8aa3b, v74
	v_mul_f32_e32 v87, 0xbfb8aa3b, v75
	v_exp_f32_e32 v86, v86
	v_exp_f32_e32 v87, v87
	v_mul_f32_e32 v88, 0xbfb8aa3b, v76
	v_mul_f32_e32 v89, 0xbfb8aa3b, v77
	v_add_f32_e32 v82, 1.0, v82
	v_add_f32_e32 v83, 1.0, v83
	v_exp_f32_e32 v88, v88
	v_exp_f32_e32 v89, v89
	v_rcp_f32_e32 v82, v82
	v_rcp_f32_e32 v83, v83
	v_add_f32_e32 v84, 1.0, v84
	v_add_f32_e32 v85, 1.0, v85
	v_rcp_f32_e32 v84, v84
	v_rcp_f32_e32 v85, v85
	v_add_f32_e32 v86, 1.0, v86
	v_add_f32_e32 v87, 1.0, v87
	v_rcp_f32_e32 v86, v86
	v_rcp_f32_e32 v87, v87
	v_add_f32_e32 v88, 1.0, v88
	v_add_f32_e32 v89, 1.0, v89
	v_pk_mul_f32 v[78:79], v[78:79], v[82:83]
	v_rcp_f32_e32 v88, v88
	v_rcp_f32_e32 v89, v89
	v_pk_mul_f32 v[70:71], v[78:79], v[70:71]
	v_pk_mul_f32 v[78:79], v[80:81], v[84:85]
	v_cvt_pk_f16_f32 v70, v70, v71
	v_pk_mul_f32 v[72:73], v[78:79], v[72:73]
	s_nop 0
	v_cvt_pk_f16_f32 v71, v72, v73
	v_pk_mul_f32 v[72:73], v[74:75], v[86:87]
	v_add_u32_e32 v74, 0x80, v140
	v_pk_mul_f32 v[66:67], v[72:73], v[66:67]
	s_nop 0
	v_cvt_pk_f16_f32 v72, v66, v67
	v_pk_mul_f32 v[66:67], v[76:77], v[88:89]
	s_nop 0
	v_pk_mul_f32 v[66:67], v[66:67], v[68:69]
	v_mul_f32_e32 v68, 0xbfb8aa3b, v64
	v_cvt_pk_f16_f32 v73, v66, v67
	v_or_b32_e32 v66, 48, v140
	v_mad_i64_i32 v[66:67], s[10:11], v66, s3, v[114:115]
	v_lshl_add_u64 v[66:67], v[66:67], 0, v[116:117]
	global_store_dwordx4 v[66:67], v[70:73], off
	v_mul_f32_e32 v66, 0xbfb8aa3b, v62
	v_mul_f32_e32 v67, 0xbfb8aa3b, v63
	v_exp_f32_e32 v66, v66
	v_exp_f32_e32 v67, v67
	v_mul_f32_e32 v69, 0xbfb8aa3b, v65
	v_exp_f32_e32 v68, v68
	v_exp_f32_e32 v69, v69
	v_mul_f32_e32 v70, 0xbfb8aa3b, v58
	v_mul_f32_e32 v71, 0xbfb8aa3b, v59
	v_exp_f32_e32 v70, v70
	v_exp_f32_e32 v71, v71
	v_mul_f32_e32 v72, 0xbfb8aa3b, v60
	v_mul_f32_e32 v73, 0xbfb8aa3b, v61
	v_add_f32_e32 v66, 1.0, v66
	v_add_f32_e32 v67, 1.0, v67
	v_exp_f32_e32 v72, v72
	v_exp_f32_e32 v73, v73
	v_rcp_f32_e32 v66, v66
	v_rcp_f32_e32 v67, v67
	v_add_f32_e32 v68, 1.0, v68
	v_add_f32_e32 v69, 1.0, v69
	v_rcp_f32_e32 v68, v68
	v_rcp_f32_e32 v69, v69
	v_add_f32_e32 v70, 1.0, v70
	v_add_f32_e32 v71, 1.0, v71
	v_rcp_f32_e32 v70, v70
	v_rcp_f32_e32 v71, v71
	v_add_f32_e32 v72, 1.0, v72
	v_add_f32_e32 v73, 1.0, v73
	v_pk_mul_f32 v[62:63], v[62:63], v[66:67]
	v_rcp_f32_e32 v72, v72
	v_rcp_f32_e32 v73, v73
	v_pk_mul_f32 v[54:55], v[62:63], v[54:55]
	v_pk_mul_f32 v[62:63], v[64:65], v[68:69]
	v_cvt_pk_f16_f32 v54, v54, v55
	v_pk_mul_f32 v[56:57], v[62:63], v[56:57]
	s_nop 0
	v_cvt_pk_f16_f32 v55, v56, v57
	v_pk_mul_f32 v[56:57], v[58:59], v[70:71]
	s_nop 0
	v_pk_mul_f32 v[50:51], v[56:57], v[50:51]
	s_nop 0
	v_cvt_pk_f16_f32 v56, v50, v51
	v_pk_mul_f32 v[50:51], v[60:61], v[72:73]
	s_nop 0
	v_pk_mul_f32 v[50:51], v[50:51], v[52:53]
	v_mul_f32_e32 v52, 0xbfb8aa3b, v48
	v_cvt_pk_f16_f32 v57, v50, v51
	v_mad_i64_i32 v[50:51], s[10:11], v74, s3, v[114:115]
	v_lshl_add_u64 v[50:51], v[50:51], 0, v[116:117]
	global_store_dwordx4 v[50:51], v[54:57], off
	v_mul_f32_e32 v50, 0xbfb8aa3b, v46
	v_mul_f32_e32 v51, 0xbfb8aa3b, v47
	v_exp_f32_e32 v50, v50
	v_exp_f32_e32 v51, v51
	v_mul_f32_e32 v53, 0xbfb8aa3b, v49
	v_exp_f32_e32 v52, v52
	v_exp_f32_e32 v53, v53
	v_mul_f32_e32 v54, 0xbfb8aa3b, v42
	v_mul_f32_e32 v55, 0xbfb8aa3b, v43
	v_exp_f32_e32 v54, v54
	v_exp_f32_e32 v55, v55
	v_mul_f32_e32 v56, 0xbfb8aa3b, v44
	v_mul_f32_e32 v57, 0xbfb8aa3b, v45
	v_add_f32_e32 v50, 1.0, v50
	v_add_f32_e32 v51, 1.0, v51
	v_exp_f32_e32 v56, v56
	v_exp_f32_e32 v57, v57
	v_rcp_f32_e32 v50, v50
	v_rcp_f32_e32 v51, v51
	v_add_f32_e32 v52, 1.0, v52
	v_add_f32_e32 v53, 1.0, v53
	v_rcp_f32_e32 v52, v52
	v_rcp_f32_e32 v53, v53
	v_add_f32_e32 v54, 1.0, v54
	v_add_f32_e32 v55, 1.0, v55
	v_rcp_f32_e32 v54, v54
	v_rcp_f32_e32 v55, v55
	v_add_f32_e32 v56, 1.0, v56
	v_add_f32_e32 v57, 1.0, v57
	v_pk_mul_f32 v[46:47], v[46:47], v[50:51]
	v_rcp_f32_e32 v56, v56
	v_rcp_f32_e32 v57, v57
	v_pk_mul_f32 v[38:39], v[46:47], v[38:39]
	v_pk_mul_f32 v[46:47], v[48:49], v[52:53]
	v_cvt_pk_f16_f32 v38, v38, v39
	v_pk_mul_f32 v[40:41], v[46:47], v[40:41]
	s_nop 0
	v_cvt_pk_f16_f32 v39, v40, v41
	v_pk_mul_f32 v[40:41], v[42:43], v[54:55]
	s_nop 0
	v_pk_mul_f32 v[34:35], v[40:41], v[34:35]
	s_nop 0
	v_cvt_pk_f16_f32 v40, v34, v35
	v_pk_mul_f32 v[34:35], v[44:45], v[56:57]
	s_nop 0
	v_pk_mul_f32 v[34:35], v[34:35], v[36:37]
	v_mul_f32_e32 v36, 0xbfb8aa3b, v30
	v_cvt_pk_f16_f32 v41, v34, v35
	v_add_u32_e32 v34, 0x90, v140
	v_mad_i64_i32 v[34:35], s[10:11], v34, s3, v[114:115]
	v_lshl_add_u64 v[34:35], v[34:35], 0, v[116:117]
	global_store_dwordx4 v[34:35], v[38:41], off
	v_mul_f32_e32 v34, 0xbfb8aa3b, v28
	v_mul_f32_e32 v35, 0xbfb8aa3b, v29
	v_exp_f32_e32 v34, v34
	v_exp_f32_e32 v35, v35
	v_mul_f32_e32 v37, 0xbfb8aa3b, v31
	v_exp_f32_e32 v36, v36
	v_exp_f32_e32 v37, v37
	v_mul_f32_e32 v38, 0xbfb8aa3b, v24
	v_mul_f32_e32 v39, 0xbfb8aa3b, v25
	v_exp_f32_e32 v38, v38
	v_exp_f32_e32 v39, v39
	v_mul_f32_e32 v40, 0xbfb8aa3b, v26
	v_mul_f32_e32 v41, 0xbfb8aa3b, v27
	v_add_f32_e32 v34, 1.0, v34
	v_add_f32_e32 v35, 1.0, v35
	v_exp_f32_e32 v40, v40
	v_exp_f32_e32 v41, v41
	v_rcp_f32_e32 v34, v34
	v_rcp_f32_e32 v35, v35
	v_add_f32_e32 v36, 1.0, v36
	v_add_f32_e32 v37, 1.0, v37
	v_rcp_f32_e32 v36, v36
	v_rcp_f32_e32 v37, v37
	v_add_f32_e32 v38, 1.0, v38
	v_add_f32_e32 v39, 1.0, v39
	v_rcp_f32_e32 v38, v38
	v_rcp_f32_e32 v39, v39
	v_add_f32_e32 v40, 1.0, v40
	v_add_f32_e32 v41, 1.0, v41
	v_pk_mul_f32 v[28:29], v[28:29], v[34:35]
	v_rcp_f32_e32 v40, v40
	v_rcp_f32_e32 v41, v41
	v_pk_mul_f32 v[20:21], v[28:29], v[20:21]
	v_pk_mul_f32 v[28:29], v[30:31], v[36:37]
	v_cvt_pk_f16_f32 v20, v20, v21
	v_pk_mul_f32 v[22:23], v[28:29], v[22:23]
	s_nop 0
	v_cvt_pk_f16_f32 v21, v22, v23
	v_pk_mul_f32 v[22:23], v[24:25], v[38:39]
	s_nop 0
	v_pk_mul_f32 v[16:17], v[22:23], v[16:17]
	s_nop 0
	v_cvt_pk_f16_f32 v22, v16, v17
	v_pk_mul_f32 v[16:17], v[26:27], v[40:41]
	s_nop 0
	v_pk_mul_f32 v[16:17], v[16:17], v[18:19]
	v_mul_f32_e32 v18, 0xbfb8aa3b, v14
	v_cvt_pk_f16_f32 v23, v16, v17
	v_add_u32_e32 v16, 0xa0, v140
	v_mad_i64_i32 v[16:17], s[10:11], v16, s3, v[114:115]
	v_lshl_add_u64 v[16:17], v[16:17], 0, v[116:117]
	global_store_dwordx4 v[16:17], v[20:23], off
	v_mul_f32_e32 v16, 0xbfb8aa3b, v12
	v_mul_f32_e32 v17, 0xbfb8aa3b, v13
	v_exp_f32_e32 v16, v16
	v_exp_f32_e32 v17, v17
	v_mul_f32_e32 v19, 0xbfb8aa3b, v15
	v_exp_f32_e32 v18, v18
	v_exp_f32_e32 v19, v19
	v_mul_f32_e32 v20, 0xbfb8aa3b, v8
	v_mul_f32_e32 v21, 0xbfb8aa3b, v9
	v_exp_f32_e32 v20, v20
	v_exp_f32_e32 v21, v21
	v_mul_f32_e32 v22, 0xbfb8aa3b, v10
	v_mul_f32_e32 v23, 0xbfb8aa3b, v11
	v_add_f32_e32 v16, 1.0, v16
	v_add_f32_e32 v17, 1.0, v17
	v_exp_f32_e32 v22, v22
	v_exp_f32_e32 v23, v23
	v_rcp_f32_e32 v16, v16
	v_rcp_f32_e32 v17, v17
	v_add_f32_e32 v18, 1.0, v18
	v_add_f32_e32 v19, 1.0, v19
	v_rcp_f32_e32 v18, v18
	v_rcp_f32_e32 v19, v19
	v_add_f32_e32 v20, 1.0, v20
	v_add_f32_e32 v21, 1.0, v21
	v_rcp_f32_e32 v20, v20
	v_rcp_f32_e32 v21, v21
	v_add_f32_e32 v22, 1.0, v22
	v_add_f32_e32 v23, 1.0, v23
	v_pk_mul_f32 v[12:13], v[12:13], v[16:17]
	v_rcp_f32_e32 v22, v22
	v_rcp_f32_e32 v23, v23
	v_pk_mul_f32 v[4:5], v[12:13], v[4:5]
	v_pk_mul_f32 v[12:13], v[14:15], v[18:19]
	v_cvt_pk_f16_f32 v4, v4, v5
	v_pk_mul_f32 v[6:7], v[12:13], v[6:7]
	s_nop 0
	v_cvt_pk_f16_f32 v5, v6, v7
	v_pk_mul_f32 v[6:7], v[8:9], v[20:21]
	s_nop 0
	v_pk_mul_f32 v[0:1], v[6:7], v[0:1]
	s_nop 0
	v_cvt_pk_f16_f32 v6, v0, v1
	v_pk_mul_f32 v[0:1], v[10:11], v[22:23]
	s_nop 0
	v_pk_mul_f32 v[0:1], v[0:1], v[2:3]
	s_nop 0
	v_cvt_pk_f16_f32 v7, v0, v1
	v_add_u32_e32 v0, 0xb0, v140
	v_mad_i64_i32 v[0:1], s[10:11], v0, s3, v[114:115]
	v_lshl_add_u64 v[0:1], v[0:1], 0, v[116:117]
	global_store_dwordx4 v[0:1], v[4:7], off
	s_cmp_lg_u32 s34, 1
	s_cbranch_scc1 .Lups_skip
	s_and_b32 s0, s91, 63
	s_cmp_gt_u32 s0, 5
	s_cbranch_scc1 .Lups_skip
	s_cmp_gt_u32 s91, 196
	s_cbranch_scc1 .Lups_skip
	s_waitcnt vmcnt(0)
	s_barrier
	v_readlane_b32 s0, v251, 36
	s_cmp_lg_u32 s0, 0
	s_cbranch_scc1 .Lups_skip
	buffer_wbl2 sc1
	s_waitcnt vmcnt(0)
	v_readlane_b32 s2, v255, 45
	v_readlane_b32 s3, v254, 25
	s_lshl_b32 s2, s2, 1
	s_cmp_eq_u32 s3, 0
	s_cselect_b32 s3, 1, 0
	s_add_i32 s2, s2, s3
	s_lshl_b32 s2, s2, 2
	s_add_i32 s2, s2, 14016
	v_readlane_b32 s0, v251, 32
	v_readlane_b32 s1, v251, 33
	s_add_u32 s0, s0, s2
	s_addc_u32 s1, s1, 0
	s_mov_b64 s[2:3], exec
	s_mov_b64 exec, 1
	global_atomic_add v33, v248, s[0:1]
	s_mov_b64 exec, s[2:3]

.LBB0_1364:
	s_add_i32 s43, s42, -2
	s_add_u32 s44, s12, 0x100
	s_addc_u32 s45, s13, 0
	s_mov_b32 s14, 0
	s_add_i32 s46, s14, 2
	s_add_u32 s12, s10, 0x100
	s_addc_u32 s13, s11, 0
	s_add_i32 s47, 0, 0x10000
	v_add_u32_e32 v134, s47, v230
	ds_read_b128 v[106:109], v134
	ds_read_b128 v[114:117], v134 offset:2048
	ds_read_b128 v[110:113], v134 offset:1024
	ds_read_b128 v[134:137], v134 offset:3072
	s_cmp_eq_u32 s43, s14
	s_cselect_b32 s14, s8, s44
	s_cselect_b32 s17, s7, s13
	s_cselect_b32 s16, s6, s12
	s_cselect_b32 s15, s9, s45
	v_lshl_add_u64 v[178:179], s[10:11], 0, v[184:185]
	s_add_i32 m0, s24, 0xc000
	ds_read_b128 v[138:141], v232
	ds_read_b128 v[154:157], v232 offset:2048
	ds_read_b128 v[162:165], v232 offset:4096
	ds_read_b128 v[170:173], v232 offset:6144
	ds_read_b128 v[150:153], v232 offset:1024
	ds_read_b128 v[158:161], v232 offset:3072
	ds_read_b128 v[166:169], v232 offset:5120
	ds_read_b128 v[174:177], v232 offset:7168
	global_load_lds_dwordx4 v[178:179], off
	v_lshl_add_u64 v[178:179], s[10:11], 0, v[186:187]
	s_add_i32 m0, s24, 0xe000
	s_nop 0
	global_load_lds_dwordx4 v[178:179], off
	s_waitcnt lgkmcnt(8)
	s_barrier
	s_waitcnt lgkmcnt(7)
	s_setprio 1
	v_mfma_f32_16x16x32_f16 v[146:149], v[106:109], v[138:141], 0
	v_mfma_f32_16x16x32_f16 v[142:145], v[114:117], v[138:141], 0
	s_waitcnt lgkmcnt(6)
	v_mfma_f32_16x16x32_f16 v[130:133], v[106:109], v[154:157], 0
	v_mfma_f32_16x16x32_f16 v[122:125], v[114:117], v[154:157], 0
	s_waitcnt lgkmcnt(5)
	v_mfma_f32_16x16x32_f16 v[94:97], v[106:109], v[162:165], 0
	v_mfma_f32_16x16x32_f16 v[90:93], v[114:117], v[162:165], 0
	s_waitcnt lgkmcnt(4)
	v_mfma_f32_16x16x32_f16 v[78:81], v[106:109], v[170:173], 0
	v_mfma_f32_16x16x32_f16 v[74:77], v[114:117], v[170:173], 0
	s_waitcnt lgkmcnt(3)
	v_mfma_f32_16x16x32_f16 v[146:149], v[110:113], v[150:153], v[146:149]
	v_mfma_f32_16x16x32_f16 v[142:145], v[134:137], v[150:153], v[142:145]
	s_waitcnt lgkmcnt(2)
	v_mfma_f32_16x16x32_f16 v[130:133], v[110:113], v[158:161], v[130:133]
	v_mfma_f32_16x16x32_f16 v[122:125], v[134:137], v[158:161], v[122:125]
	s_waitcnt lgkmcnt(1)
	v_mfma_f32_16x16x32_f16 v[94:97], v[110:113], v[166:169], v[94:97]
	v_mfma_f32_16x16x32_f16 v[90:93], v[134:137], v[166:169], v[90:93]
	s_waitcnt lgkmcnt(0)
	v_mfma_f32_16x16x32_f16 v[78:81], v[110:113], v[174:177], v[78:81]
	v_mfma_f32_16x16x32_f16 v[74:77], v[134:137], v[174:177], v[74:77]
	s_setprio 0
	s_barrier
	s_add_i32 s48, 0, 0x14000
	s_add_i32 s10, s47, s23
	v_add_u32_e32 v196, s48, v230
	v_lshl_add_u64 v[200:201], s[14:15], 0, v[32:33]
	s_mov_b32 m0, s10
	ds_read_b128 v[178:181], v196
	ds_read_b128 v[192:195], v196 offset:2048
	ds_read_b128 v[188:191], v196 offset:1024
	ds_read_b128 v[196:199], v196 offset:3072
	global_load_lds_dwordx4 v[200:201], off
	v_lshl_add_u64 v[202:203], s[14:15], 0, v[182:183]
	s_add_i32 m0, s10, 0x2000
	s_nop 0
	global_load_lds_dwordx4 v[202:203], off
	s_barrier
	s_waitcnt lgkmcnt(2)
	s_setprio 1
	v_mfma_f32_16x16x32_f16 v[126:129], v[178:181], v[138:141], 0
	v_mfma_f32_16x16x32_f16 v[118:121], v[192:195], v[138:141], 0
	v_mfma_f32_16x16x32_f16 v[102:105], v[178:181], v[154:157], 0
	v_mfma_f32_16x16x32_f16 v[98:101], v[192:195], v[154:157], 0
	v_mfma_f32_16x16x32_f16 v[86:89], v[178:181], v[162:165], 0
	v_mfma_f32_16x16x32_f16 v[82:85], v[192:195], v[162:165], 0
	v_mfma_f32_16x16x32_f16 v[70:73], v[178:181], v[170:173], 0
	v_mfma_f32_16x16x32_f16 v[66:69], v[192:195], v[170:173], 0
	s_waitcnt lgkmcnt(0)
	v_mfma_f32_16x16x32_f16 v[126:129], v[188:191], v[150:153], v[126:129]
	v_mfma_f32_16x16x32_f16 v[118:121], v[196:199], v[150:153], v[118:121]
	v_mfma_f32_16x16x32_f16 v[102:105], v[188:191], v[158:161], v[102:105]
	v_mfma_f32_16x16x32_f16 v[98:101], v[196:199], v[158:161], v[98:101]
	v_mfma_f32_16x16x32_f16 v[86:89], v[188:191], v[166:169], v[86:89]
	v_mfma_f32_16x16x32_f16 v[82:85], v[196:199], v[166:169], v[82:85]
	v_mfma_f32_16x16x32_f16 v[70:73], v[188:191], v[174:177], v[70:73]
	v_mfma_f32_16x16x32_f16 v[66:69], v[196:199], v[174:177], v[66:69]
	s_setprio 0
	s_mov_b32 m0, s24
	v_lshl_add_u64 v[204:205], s[16:17], 0, v[32:33]
	s_barrier
	ds_read_b128 v[138:141], v232 offset:16384
	ds_read_b128 v[154:157], v232 offset:18432
	ds_read_b128 v[162:165], v232 offset:20480
	ds_read_b128 v[170:173], v232 offset:22528
	ds_read_b128 v[150:153], v232 offset:17408
	ds_read_b128 v[158:161], v232 offset:19456
	ds_read_b128 v[166:169], v232 offset:21504
	ds_read_b128 v[174:177], v232 offset:23552
	global_load_lds_dwordx4 v[204:205], off
	v_lshl_add_u64 v[206:207], s[16:17], 0, v[182:183]
	s_mov_b32 m0, s25
	s_nop 0
	global_load_lds_dwordx4 v[206:207], off
	s_barrier
	s_waitcnt lgkmcnt(7)
	s_setprio 1
	v_mfma_f32_16x16x32_f16 v[62:65], v[106:109], v[138:141], 0
	v_mfma_f32_16x16x32_f16 v[58:61], v[114:117], v[138:141], 0
	s_waitcnt lgkmcnt(6)
	v_mfma_f32_16x16x32_f16 v[46:49], v[106:109], v[154:157], 0
	v_mfma_f32_16x16x32_f16 v[42:45], v[114:117], v[154:157], 0
	s_waitcnt lgkmcnt(5)
	v_mfma_f32_16x16x32_f16 v[28:31], v[106:109], v[162:165], 0
	v_mfma_f32_16x16x32_f16 v[24:27], v[114:117], v[162:165], 0
	s_waitcnt lgkmcnt(4)
	v_mfma_f32_16x16x32_f16 v[12:15], v[106:109], v[170:173], 0
	v_mfma_f32_16x16x32_f16 v[8:11], v[114:117], v[170:173], 0
	s_waitcnt lgkmcnt(3)
	v_mfma_f32_16x16x32_f16 v[62:65], v[110:113], v[150:153], v[62:65]
	v_mfma_f32_16x16x32_f16 v[58:61], v[134:137], v[150:153], v[58:61]
	s_waitcnt lgkmcnt(2)
	v_mfma_f32_16x16x32_f16 v[46:49], v[110:113], v[158:161], v[46:49]
	v_mfma_f32_16x16x32_f16 v[42:45], v[134:137], v[158:161], v[42:45]
	s_waitcnt lgkmcnt(1)
	v_mfma_f32_16x16x32_f16 v[28:31], v[110:113], v[166:169], v[28:31]
	v_mfma_f32_16x16x32_f16 v[24:27], v[134:137], v[166:169], v[24:27]
	s_waitcnt lgkmcnt(0)
	v_mfma_f32_16x16x32_f16 v[12:15], v[110:113], v[174:177], v[12:15]
	v_mfma_f32_16x16x32_f16 v[8:11], v[134:137], v[174:177], v[8:11]
	s_setprio 0
	s_barrier
	s_add_u32 s10, s14, 0xb0000
	s_addc_u32 s11, s15, 0
	s_add_i32 s47, s48, s23
	v_lshl_add_u64 v[106:107], s[10:11], 0, v[32:33]
	s_mov_b32 m0, s47
	s_nop 0
	global_load_lds_dwordx4 v[106:107], off
	v_lshl_add_u64 v[106:107], s[10:11], 0, v[182:183]
	s_add_i32 m0, s47, 0x2000
	s_nop 0
	global_load_lds_dwordx4 v[106:107], off
	s_waitcnt vmcnt(6)
	s_barrier
	s_setprio 1
	v_mfma_f32_16x16x32_f16 v[54:57], v[178:181], v[138:141], 0
	v_mfma_f32_16x16x32_f16 v[50:53], v[192:195], v[138:141], 0
	v_mfma_f32_16x16x32_f16 v[38:41], v[178:181], v[154:157], 0
	v_mfma_f32_16x16x32_f16 v[34:37], v[192:195], v[154:157], 0
	v_mfma_f32_16x16x32_f16 v[20:23], v[178:181], v[162:165], 0
	v_mfma_f32_16x16x32_f16 v[16:19], v[192:195], v[162:165], 0
	v_mfma_f32_16x16x32_f16 v[4:7], v[178:181], v[170:173], 0
	v_mfma_f32_16x16x32_f16 v[0:3], v[192:195], v[170:173], 0
	v_mfma_f32_16x16x32_f16 v[54:57], v[188:191], v[150:153], v[54:57]
	v_mfma_f32_16x16x32_f16 v[50:53], v[196:199], v[150:153], v[50:53]
	v_mfma_f32_16x16x32_f16 v[38:41], v[188:191], v[158:161], v[38:41]
	v_mfma_f32_16x16x32_f16 v[34:37], v[196:199], v[158:161], v[34:37]
	v_mfma_f32_16x16x32_f16 v[20:23], v[188:191], v[166:169], v[20:23]
	v_mfma_f32_16x16x32_f16 v[16:19], v[196:199], v[166:169], v[16:19]
	v_mfma_f32_16x16x32_f16 v[4:7], v[188:191], v[174:177], v[4:7]
	v_mfma_f32_16x16x32_f16 v[0:3], v[196:199], v[174:177], v[0:3]
	s_setprio 0
	s_add_i32 s47, 0, 0x18000
	v_add_u32_e32 v134, s47, v230
	s_barrier
	ds_read_b128 v[106:109], v134
	ds_read_b128 v[114:117], v134 offset:2048
	ds_read_b128 v[110:113], v134 offset:1024
	ds_read_b128 v[134:137], v134 offset:3072
	s_add_u32 s10, s16, 0xb0000
	s_addc_u32 s11, s17, 0
	s_mov_b32 m0, s26
	v_lshl_add_u64 v[178:179], s[10:11], 0, v[32:33]
	ds_read_b128 v[138:141], v232 offset:32768
	ds_read_b128 v[154:157], v232 offset:34816
	ds_read_b128 v[162:165], v232 offset:36864
	ds_read_b128 v[170:173], v232 offset:38912
	ds_read_b128 v[150:153], v232 offset:33792
	ds_read_b128 v[158:161], v232 offset:35840
	ds_read_b128 v[166:169], v232 offset:37888
	ds_read_b128 v[174:177], v232 offset:39936
	global_load_lds_dwordx4 v[178:179], off
	v_lshl_add_u64 v[178:179], s[10:11], 0, v[182:183]
	s_mov_b32 m0, s27
	s_nop 0
	global_load_lds_dwordx4 v[178:179], off
	s_waitcnt lgkmcnt(8)
	s_barrier
	s_waitcnt lgkmcnt(7)
	s_setprio 1
	v_mfma_f32_16x16x32_f16 v[146:149], v[106:109], v[138:141], v[146:149]
	v_mfma_f32_16x16x32_f16 v[142:145], v[114:117], v[138:141], v[142:145]
	s_waitcnt lgkmcnt(6)
	v_mfma_f32_16x16x32_f16 v[130:133], v[106:109], v[154:157], v[130:133]
	v_mfma_f32_16x16x32_f16 v[122:125], v[114:117], v[154:157], v[122:125]
	s_waitcnt lgkmcnt(5)
	v_mfma_f32_16x16x32_f16 v[94:97], v[106:109], v[162:165], v[94:97]
	v_mfma_f32_16x16x32_f16 v[90:93], v[114:117], v[162:165], v[90:93]
	s_waitcnt lgkmcnt(4)
	v_mfma_f32_16x16x32_f16 v[78:81], v[106:109], v[170:173], v[78:81]
	v_mfma_f32_16x16x32_f16 v[74:77], v[114:117], v[170:173], v[74:77]
	s_waitcnt lgkmcnt(3)
	v_mfma_f32_16x16x32_f16 v[146:149], v[110:113], v[150:153], v[146:149]
	v_mfma_f32_16x16x32_f16 v[142:145], v[134:137], v[150:153], v[142:145]
	s_waitcnt lgkmcnt(2)
	v_mfma_f32_16x16x32_f16 v[130:133], v[110:113], v[158:161], v[130:133]
	v_mfma_f32_16x16x32_f16 v[122:125], v[134:137], v[158:161], v[122:125]
	s_waitcnt lgkmcnt(1)
	v_mfma_f32_16x16x32_f16 v[94:97], v[110:113], v[166:169], v[94:97]
	v_mfma_f32_16x16x32_f16 v[90:93], v[134:137], v[166:169], v[90:93]
	s_waitcnt lgkmcnt(0)
	v_mfma_f32_16x16x32_f16 v[78:81], v[110:113], v[174:177], v[78:81]
	v_mfma_f32_16x16x32_f16 v[74:77], v[134:137], v[174:177], v[74:77]
	s_setprio 0
	s_barrier
	s_add_i32 s16, 0, 0x1c000
	s_add_i32 s10, s47, s23
	v_add_u32_e32 v196, s16, v230
	v_lshl_add_u64 v[200:201], v[200:201], 0, s[84:85]
	s_mov_b32 m0, s10
	ds_read_b128 v[178:181], v196
	ds_read_b128 v[192:195], v196 offset:2048
	ds_read_b128 v[188:191], v196 offset:1024
	ds_read_b128 v[196:199], v196 offset:3072
	global_load_lds_dwordx4 v[200:201], off
	v_lshl_add_u64 v[200:201], v[202:203], 0, s[84:85]
	s_add_i32 m0, s10, 0x2000
	s_nop 0
	global_load_lds_dwordx4 v[200:201], off
	s_barrier
	s_waitcnt lgkmcnt(2)
	s_setprio 1
	v_mfma_f32_16x16x32_f16 v[126:129], v[178:181], v[138:141], v[126:129]
	v_mfma_f32_16x16x32_f16 v[118:121], v[192:195], v[138:141], v[118:121]
	v_mfma_f32_16x16x32_f16 v[102:105], v[178:181], v[154:157], v[102:105]
	v_mfma_f32_16x16x32_f16 v[98:101], v[192:195], v[154:157], v[98:101]
	v_mfma_f32_16x16x32_f16 v[86:89], v[178:181], v[162:165], v[86:89]
	v_mfma_f32_16x16x32_f16 v[82:85], v[192:195], v[162:165], v[82:85]
	v_mfma_f32_16x16x32_f16 v[70:73], v[178:181], v[170:173], v[70:73]
	v_mfma_f32_16x16x32_f16 v[66:69], v[192:195], v[170:173], v[66:69]
	s_waitcnt lgkmcnt(0)
	v_mfma_f32_16x16x32_f16 v[126:129], v[188:191], v[150:153], v[126:129]
	v_mfma_f32_16x16x32_f16 v[118:121], v[196:199], v[150:153], v[118:121]
	v_mfma_f32_16x16x32_f16 v[102:105], v[188:191], v[158:161], v[102:105]
	v_mfma_f32_16x16x32_f16 v[98:101], v[196:199], v[158:161], v[98:101]
	v_mfma_f32_16x16x32_f16 v[86:89], v[188:191], v[166:169], v[86:89]
	v_mfma_f32_16x16x32_f16 v[82:85], v[196:199], v[166:169], v[82:85]
	v_mfma_f32_16x16x32_f16 v[70:73], v[188:191], v[174:177], v[70:73]
	v_mfma_f32_16x16x32_f16 v[66:69], v[196:199], v[174:177], v[66:69]
	s_setprio 0
	s_mov_b32 m0, s29
	v_lshl_add_u64 v[200:201], v[204:205], 0, s[84:85]
	s_barrier
	ds_read_b128 v[138:141], v232 offset:49152
	ds_read_b128 v[154:157], v232 offset:51200
	ds_read_b128 v[162:165], v232 offset:53248
	ds_read_b128 v[170:173], v232 offset:55296
	ds_read_b128 v[150:153], v232 offset:50176
	ds_read_b128 v[158:161], v232 offset:52224
	ds_read_b128 v[166:169], v232 offset:54272
	ds_read_b128 v[174:177], v232 offset:56320
	global_load_lds_dwordx4 v[200:201], off
	v_lshl_add_u64 v[200:201], v[206:207], 0, s[84:85]
	s_mov_b32 m0, s30
	s_nop 0
	global_load_lds_dwordx4 v[200:201], off
	s_barrier
	s_waitcnt lgkmcnt(7)
	s_setprio 1
	v_mfma_f32_16x16x32_f16 v[62:65], v[106:109], v[138:141], v[62:65]
	v_mfma_f32_16x16x32_f16 v[58:61], v[114:117], v[138:141], v[58:61]
	s_waitcnt lgkmcnt(6)
	v_mfma_f32_16x16x32_f16 v[46:49], v[106:109], v[154:157], v[46:49]
	v_mfma_f32_16x16x32_f16 v[42:45], v[114:117], v[154:157], v[42:45]
	s_waitcnt lgkmcnt(5)
	v_mfma_f32_16x16x32_f16 v[28:31], v[106:109], v[162:165], v[28:31]
	v_mfma_f32_16x16x32_f16 v[24:27], v[114:117], v[162:165], v[24:27]
	s_waitcnt lgkmcnt(4)
	v_mfma_f32_16x16x32_f16 v[12:15], v[106:109], v[170:173], v[12:15]
	v_mfma_f32_16x16x32_f16 v[8:11], v[114:117], v[170:173], v[8:11]
	s_waitcnt lgkmcnt(3)
	v_mfma_f32_16x16x32_f16 v[62:65], v[110:113], v[150:153], v[62:65]
	v_mfma_f32_16x16x32_f16 v[58:61], v[134:137], v[150:153], v[58:61]
	s_waitcnt lgkmcnt(2)
	v_mfma_f32_16x16x32_f16 v[46:49], v[110:113], v[158:161], v[46:49]
	v_mfma_f32_16x16x32_f16 v[42:45], v[134:137], v[158:161], v[42:45]
	s_waitcnt lgkmcnt(1)
	v_mfma_f32_16x16x32_f16 v[28:31], v[110:113], v[166:169], v[28:31]
	v_mfma_f32_16x16x32_f16 v[24:27], v[134:137], v[166:169], v[24:27]
	s_waitcnt lgkmcnt(0)
	v_mfma_f32_16x16x32_f16 v[12:15], v[110:113], v[174:177], v[12:15]
	v_mfma_f32_16x16x32_f16 v[8:11], v[134:137], v[174:177], v[8:11]
	s_setprio 0
	s_barrier
	s_add_u32 s10, s14, 0xb0080
	s_addc_u32 s11, s15, 0
	s_add_i32 s14, s16, s23
	v_lshl_add_u64 v[106:107], s[10:11], 0, v[32:33]
	s_mov_b32 m0, s14
	s_nop 0
	global_load_lds_dwordx4 v[106:107], off
	v_lshl_add_u64 v[106:107], s[10:11], 0, v[182:183]
	s_add_i32 m0, s14, 0x2000
	s_nop 0
	global_load_lds_dwordx4 v[106:107], off
	s_waitcnt vmcnt(6)
	s_barrier
	s_setprio 1
	v_mfma_f32_16x16x32_f16 v[54:57], v[178:181], v[138:141], v[54:57]
	v_mfma_f32_16x16x32_f16 v[50:53], v[192:195], v[138:141], v[50:53]
	v_mfma_f32_16x16x32_f16 v[38:41], v[178:181], v[154:157], v[38:41]
	v_mfma_f32_16x16x32_f16 v[34:37], v[192:195], v[154:157], v[34:37]
	v_mfma_f32_16x16x32_f16 v[20:23], v[178:181], v[162:165], v[20:23]
	v_mfma_f32_16x16x32_f16 v[16:19], v[192:195], v[162:165], v[16:19]
	v_mfma_f32_16x16x32_f16 v[4:7], v[178:181], v[170:173], v[4:7]
	v_mfma_f32_16x16x32_f16 v[0:3], v[192:195], v[170:173], v[0:3]
	v_mfma_f32_16x16x32_f16 v[54:57], v[188:191], v[150:153], v[54:57]
	v_mfma_f32_16x16x32_f16 v[50:53], v[196:199], v[150:153], v[50:53]
	v_mfma_f32_16x16x32_f16 v[38:41], v[188:191], v[158:161], v[38:41]
	v_mfma_f32_16x16x32_f16 v[34:37], v[196:199], v[158:161], v[34:37]
	v_mfma_f32_16x16x32_f16 v[20:23], v[188:191], v[166:169], v[20:23]
	v_mfma_f32_16x16x32_f16 v[16:19], v[196:199], v[166:169], v[16:19]
	v_mfma_f32_16x16x32_f16 v[4:7], v[188:191], v[174:177], v[4:7]
	v_mfma_f32_16x16x32_f16 v[0:3], v[196:199], v[174:177], v[0:3]
	s_setprio 0
	s_add_u32 s44, s44, 0x100
	s_addc_u32 s45, s45, 0
	s_cmp_ge_u32 s46, s42
	s_mov_b64 s[10:11], s[12:13]
	s_mov_b32 s14, s46
	s_barrier
	s_cbranch_scc0 .LBB0_1365
	s_branch .Lpeelx5

.Lpeelx5:
	s_cmp_eq_u32 s40, 0
	s_cselect_b32 s6, 0x9000, 0
	v_lshl_or_b32 v106, s41, 8, v231
	s_add_u32 s6, s31, s6
	s_addc_u32 s7, s34, 0
	v_ashrrev_i32_e32 v107, 31, v106
	v_lshl_add_u64 v[116:117], v[106:107], 2, s[6:7]
	global_load_dwordx4 v[108:111], v[116:117], off offset:16
	global_load_dwordx4 v[112:115], v[116:117], off
	s_cmp_eq_u32 s39, 0
	s_waitcnt vmcnt(0)
	v_pk_mul_f32 v[194:195], v[110:111], 0.5 op_sel_hi:[1,0]
	v_pk_mul_f32 v[198:199], v[114:115], 0.5 op_sel_hi:[1,0]
	v_pk_mul_f32 v[202:203], v[112:113], 0.5 op_sel_hi:[1,0]
	v_pk_mul_f32 v[200:201], v[108:109], 0.5 op_sel_hi:[1,0]
	global_load_dwordx4 v[108:111], v[116:117], off offset:528
	global_load_dwordx4 v[112:115], v[116:117], off offset:512
	s_waitcnt vmcnt(0)
	v_pk_mul_f32 v[188:189], v[110:111], 0.5 op_sel_hi:[1,0]
	v_pk_mul_f32 v[196:197], v[112:113], 0.5 op_sel_hi:[1,0]
	v_lshl_add_u32 v112, s40, 8, v229
	v_pk_mul_f32 v[190:191], v[114:115], 0.5 op_sel_hi:[1,0]
	v_pk_mul_f32 v[192:193], v[108:109], 0.5 op_sel_hi:[1,0]
	v_or_b32_e32 v114, 16, v112
	v_or_b32_e32 v110, 32, v112
	v_or_b32_e32 v108, 48, v112
	v_ashrrev_i32_e32 v113, 31, v112
	v_ashrrev_i32_e32 v115, 31, v114
	v_ashrrev_i32_e32 v111, 31, v110
	v_ashrrev_i32_e32 v109, 31, v108
	s_cbranch_scc1 .LBB0_1368
	s_add_i32 s96, s39, -1
	s_lshl_b64 s[6:7], s[96:97], 20
	v_readlane_b32 s8, v252, 11
	v_readlane_b32 s9, v252, 12
	s_add_u32 s6, s8, s6
	s_addc_u32 s7, s9, s7
	v_lshlrev_b64 v[138:139], 2, v[106:107]
	v_lshrrev_b32_e32 v150, 5, v220
	v_mul_u32_u24_e32 v150, 48, v150
	s_nop 0
	v_sub_co_u32_e32 v138, vcc, v138, v150
	s_nop 1
	v_subbrev_co_u32_e32 v139, vcc, 0, v139, vcc
	v_lshl_add_u64 v[138:139], s[6:7], 0, v[138:139]
	s_mov_b64 s[6:7], 0x80000
	v_lshlrev_b64 v[204:205], 12, v[112:113]
	v_lshl_add_u64 v[204:205], v[204:205], 0, v[138:139]
	v_lshl_add_u64 v[212:213], v[204:205], 0, s[6:7]
	v_lshlrev_b64 v[206:207], 12, v[114:115]
	v_lshl_add_u64 v[206:207], v[206:207], 0, v[138:139]
	v_lshl_add_u64 v[214:215], v[206:207], 0, s[6:7]
	v_lshlrev_b64 v[208:209], 12, v[110:111]
	v_lshl_add_u64 v[208:209], v[208:209], 0, v[138:139]
	v_lshl_add_u64 v[216:217], v[208:209], 0, s[6:7]
	v_lshlrev_b64 v[210:211], 12, v[108:109]
	v_lshl_add_u64 v[210:211], v[210:211], 0, v[138:139]
	v_lshl_add_u64 v[218:219], v[210:211], 0, s[6:7]
	s_waitcnt vmcnt(0)
	v_pk_mul_f32 v[152:153], v[146:147], v[202:203]
	v_pk_mul_f32 v[154:155], v[148:149], v[198:199]
	v_pk_mul_f32 v[156:157], v[142:143], v[200:201]
	v_pk_mul_f32 v[158:159], v[144:145], v[194:195]
	s_nop 1
	v_permlane32_swap_b32_e32 v152, v156
	v_permlane32_swap_b32_e32 v153, v157
	v_permlane32_swap_b32_e32 v154, v158
	v_permlane32_swap_b32_e32 v155, v159
	s_nop 0
	global_store_dwordx4 v[204:205], v[152:155], off
	global_store_dwordx4 v[204:205], v[156:159], off offset:64
	v_pk_mul_f32 v[160:161], v[126:127], v[196:197]
	v_pk_mul_f32 v[162:163], v[128:129], v[190:191]
	v_pk_mul_f32 v[164:165], v[118:119], v[192:193]
	v_pk_mul_f32 v[166:167], v[120:121], v[188:189]
	s_nop 1
	v_permlane32_swap_b32_e32 v160, v164
	v_permlane32_swap_b32_e32 v161, v165
	v_permlane32_swap_b32_e32 v162, v166
	v_permlane32_swap_b32_e32 v163, v167
	s_nop 0
	global_store_dwordx4 v[204:205], v[160:163], off offset:512
	global_store_dwordx4 v[204:205], v[164:167], off offset:576
	v_pk_mul_f32 v[168:169], v[130:131], v[202:203]
	v_pk_mul_f32 v[170:171], v[132:133], v[198:199]
	v_pk_mul_f32 v[172:173], v[122:123], v[200:201]
	v_pk_mul_f32 v[174:175], v[124:125], v[194:195]
	s_nop 1
	v_permlane32_swap_b32_e32 v168, v172
	v_permlane32_swap_b32_e32 v169, v173
	v_permlane32_swap_b32_e32 v170, v174
	v_permlane32_swap_b32_e32 v171, v175
	s_nop 0
	global_store_dwordx4 v[206:207], v[168:171], off
	global_store_dwordx4 v[206:207], v[172:175], off offset:64
	v_pk_mul_f32 v[176:177], v[102:103], v[196:197]
	v_pk_mul_f32 v[178:179], v[104:105], v[190:191]
	v_pk_mul_f32 v[180:181], v[98:99], v[192:193]
	v_pk_mul_f32 v[182:183], v[100:101], v[188:189]
	s_nop 1
	v_permlane32_swap_b32_e32 v176, v180
	v_permlane32_swap_b32_e32 v177, v181
	v_permlane32_swap_b32_e32 v178, v182
	v_permlane32_swap_b32_e32 v179, v183
	s_nop 0
	global_store_dwordx4 v[206:207], v[176:179], off offset:512
	global_store_dwordx4 v[206:207], v[180:183], off offset:576
	v_pk_mul_f32 v[152:153], v[94:95], v[202:203]
	v_pk_mul_f32 v[154:155], v[96:97], v[198:199]
	v_pk_mul_f32 v[156:157], v[90:91], v[200:201]
	v_pk_mul_f32 v[158:159], v[92:93], v[194:195]
	s_nop 1
	v_permlane32_swap_b32_e32 v152, v156
	v_permlane32_swap_b32_e32 v153, v157
	v_permlane32_swap_b32_e32 v154, v158
	v_permlane32_swap_b32_e32 v155, v159
	s_nop 0
	global_store_dwordx4 v[208:209], v[152:155], off
	global_store_dwordx4 v[208:209], v[156:159], off offset:64
	v_pk_mul_f32 v[160:161], v[86:87], v[196:197]
	v_pk_mul_f32 v[162:163], v[88:89], v[190:191]
	v_pk_mul_f32 v[164:165], v[82:83], v[192:193]
	v_pk_mul_f32 v[166:167], v[84:85], v[188:189]
	s_nop 1
	v_permlane32_swap_b32_e32 v160, v164
	v_permlane32_swap_b32_e32 v161, v165
	v_permlane32_swap_b32_e32 v162, v166
	v_permlane32_swap_b32_e32 v163, v167
	s_nop 0
	global_store_dwordx4 v[208:209], v[160:163], off offset:512
	global_store_dwordx4 v[208:209], v[164:167], off offset:576
	v_pk_mul_f32 v[168:169], v[78:79], v[202:203]
	v_pk_mul_f32 v[170:171], v[80:81], v[198:199]
	v_pk_mul_f32 v[172:173], v[74:75], v[200:201]
	v_pk_mul_f32 v[174:175], v[76:77], v[194:195]
	s_nop 1
	v_permlane32_swap_b32_e32 v168, v172
	v_permlane32_swap_b32_e32 v169, v173
	v_permlane32_swap_b32_e32 v170, v174
	v_permlane32_swap_b32_e32 v171, v175
	s_nop 0
	global_store_dwordx4 v[210:211], v[168:171], off
	global_store_dwordx4 v[210:211], v[172:175], off offset:64
	v_pk_mul_f32 v[176:177], v[70:71], v[196:197]
	v_pk_mul_f32 v[178:179], v[72:73], v[190:191]
	v_pk_mul_f32 v[180:181], v[66:67], v[192:193]
	v_pk_mul_f32 v[182:183], v[68:69], v[188:189]
	s_nop 1
	v_permlane32_swap_b32_e32 v176, v180
	v_permlane32_swap_b32_e32 v177, v181
	v_permlane32_swap_b32_e32 v178, v182
	v_permlane32_swap_b32_e32 v179, v183
	s_nop 0
	global_store_dwordx4 v[210:211], v[176:179], off offset:512
	global_store_dwordx4 v[210:211], v[180:183], off offset:576
	v_pk_mul_f32 v[152:153], v[62:63], v[202:203]
	v_pk_mul_f32 v[154:155], v[64:65], v[198:199]
	v_pk_mul_f32 v[156:157], v[58:59], v[200:201]
	v_pk_mul_f32 v[158:159], v[60:61], v[194:195]
	s_nop 1
	v_permlane32_swap_b32_e32 v152, v156
	v_permlane32_swap_b32_e32 v153, v157
	v_permlane32_swap_b32_e32 v154, v158
	v_permlane32_swap_b32_e32 v155, v159
	s_nop 0
	global_store_dwordx4 v[212:213], v[152:155], off
	global_store_dwordx4 v[212:213], v[156:159], off offset:64
	v_pk_mul_f32 v[160:161], v[54:55], v[196:197]
	v_pk_mul_f32 v[162:163], v[56:57], v[190:191]
	v_pk_mul_f32 v[164:165], v[50:51], v[192:193]
	v_pk_mul_f32 v[166:167], v[52:53], v[188:189]
	s_nop 1
	v_permlane32_swap_b32_e32 v160, v164
	v_permlane32_swap_b32_e32 v161, v165
	v_permlane32_swap_b32_e32 v162, v166
	v_permlane32_swap_b32_e32 v163, v167
	s_nop 0
	global_store_dwordx4 v[212:213], v[160:163], off offset:512
	global_store_dwordx4 v[212:213], v[164:167], off offset:576
	v_pk_mul_f32 v[168:169], v[46:47], v[202:203]
	v_pk_mul_f32 v[170:171], v[48:49], v[198:199]
	v_pk_mul_f32 v[172:173], v[42:43], v[200:201]
	v_pk_mul_f32 v[174:175], v[44:45], v[194:195]
	s_nop 1
	v_permlane32_swap_b32_e32 v168, v172
	v_permlane32_swap_b32_e32 v169, v173
	v_permlane32_swap_b32_e32 v170, v174
	v_permlane32_swap_b32_e32 v171, v175
	s_nop 0
	global_store_dwordx4 v[214:215], v[168:171], off
	global_store_dwordx4 v[214:215], v[172:175], off offset:64
	v_pk_mul_f32 v[176:177], v[38:39], v[196:197]
	v_pk_mul_f32 v[178:179], v[40:41], v[190:191]
	v_pk_mul_f32 v[180:181], v[34:35], v[192:193]
	v_pk_mul_f32 v[182:183], v[36:37], v[188:189]
	s_nop 1
	v_permlane32_swap_b32_e32 v176, v180
	v_permlane32_swap_b32_e32 v177, v181
	v_permlane32_swap_b32_e32 v178, v182
	v_permlane32_swap_b32_e32 v179, v183
	s_nop 0
	global_store_dwordx4 v[214:215], v[176:179], off offset:512
	global_store_dwordx4 v[214:215], v[180:183], off offset:576
	v_pk_mul_f32 v[152:153], v[28:29], v[202:203]
	v_pk_mul_f32 v[154:155], v[30:31], v[198:199]
	v_pk_mul_f32 v[156:157], v[24:25], v[200:201]
	v_pk_mul_f32 v[158:159], v[26:27], v[194:195]
	s_nop 1
	v_permlane32_swap_b32_e32 v152, v156
	v_permlane32_swap_b32_e32 v153, v157
	v_permlane32_swap_b32_e32 v154, v158
	v_permlane32_swap_b32_e32 v155, v159
	s_nop 0
	global_store_dwordx4 v[216:217], v[152:155], off
	global_store_dwordx4 v[216:217], v[156:159], off offset:64
	v_pk_mul_f32 v[160:161], v[20:21], v[196:197]
	v_pk_mul_f32 v[162:163], v[22:23], v[190:191]
	v_pk_mul_f32 v[164:165], v[16:17], v[192:193]
	v_pk_mul_f32 v[166:167], v[18:19], v[188:189]
	s_nop 1
	v_permlane32_swap_b32_e32 v160, v164
	v_permlane32_swap_b32_e32 v161, v165
	v_permlane32_swap_b32_e32 v162, v166
	v_permlane32_swap_b32_e32 v163, v167
	s_nop 0
	global_store_dwordx4 v[216:217], v[160:163], off offset:512
	global_store_dwordx4 v[216:217], v[164:167], off offset:576
	v_pk_mul_f32 v[168:169], v[12:13], v[202:203]
	v_pk_mul_f32 v[170:171], v[14:15], v[198:199]
	v_pk_mul_f32 v[172:173], v[8:9], v[200:201]
	v_pk_mul_f32 v[174:175], v[10:11], v[194:195]
	s_nop 1
	v_permlane32_swap_b32_e32 v168, v172
	v_permlane32_swap_b32_e32 v169, v173
	v_permlane32_swap_b32_e32 v170, v174
	v_permlane32_swap_b32_e32 v171, v175
	s_nop 0
	global_store_dwordx4 v[218:219], v[168:171], off
	global_store_dwordx4 v[218:219], v[172:175], off offset:64
	v_pk_mul_f32 v[176:177], v[4:5], v[196:197]
	v_pk_mul_f32 v[178:179], v[6:7], v[190:191]
	v_pk_mul_f32 v[180:181], v[0:1], v[192:193]
	v_pk_mul_f32 v[182:183], v[2:3], v[188:189]
	s_nop 1
	v_permlane32_swap_b32_e32 v176, v180
	v_permlane32_swap_b32_e32 v177, v181
	v_permlane32_swap_b32_e32 v178, v182
	v_permlane32_swap_b32_e32 v179, v183
	s_nop 0
	global_store_dwordx4 v[218:219], v[176:179], off offset:512
	global_store_dwordx4 v[218:219], v[180:183], off offset:576
	s_cbranch_execnz .LBB0_1352
	s_branch .LBB0_1351
